# GEMM mainloops: per-segment s_setprio toggling removed, one static priority raise for the wave half that takes the extra entry barrier (strategy 4)
# baseline (speedup 1.0000x reference)
; #define PG8_STAGE(bufoff, gbase, voff) do { _Pragma("unroll") for (int _i = 0; _i < 2; ++_i) \
;         __builtin_amdgcn_global_load_lds((const unsigned*)((const char*)(gbase) + (voff)[_i]), (LAS unsigned*)(lds + (bufoff) + ldsw + _i * 8192), 16, 0, 0); } while (0)
; #define PG8_WAIT_V(n) asm volatile("s_waitcnt vmcnt(" #n ")" ::: "memory")
; #define PG8_BAR __builtin_amdgcn_s_barrier()
; template <class Epi>
; __device__ __forceinline__ void gemm_phase(LAS unsigned char* lds, const Gemm g, const StaticOrder& S, const Epi& E) {
;     const int tid = threadIdx.x, wid = __builtin_amdgcn_readfirstlane(tid >> 6), lane = tid & 63, wr = wid >> 2, wc = wid & 3, fr = lane & 15, fq = lane >> 4;
;     const int K = g.K, nt = K / BK;
;     unsigned voffA[2], voffB[2];
; #pragma unroll
;     for (int i = 0; i < 2; ++i) { int R, C; stage_rc(tid * 16 + i * 8192, R, C); const int Rb = Epi::PERM ? ((R & ~31) + perm32(R & 31)) : R;
;         voffA[i] = (unsigned)(R * K + C) * 2u; voffB[i] = (unsigned)(Rb * K + C) * 2u; }
;     const size_t kstep = (size_t)(BK * 2);
;     const size_t hstep = (size_t)HALF * K * 2;
;     const size_t tstep = 2 * hstep;
;     const unsigned ldsw = (unsigned)wid * 1024u;
;     const int aoff = lds_byte(wr * 64 + fr, fq * 8), boff = lds_byte(wc * 32 + fr, fq * 8);
;     ...
;     Unit cur, nxt; int ui = 0;
;     if (!S.next(0, cur)) return;
;     f32x4 acc[2][2][4][2];
; #pragma unroll
;     for (int a = 0; a < 2; ++a)
; #pragma unroll
;         for (int b = 0; b < 2; ++b)
; #pragma unroll
;             for (int m = 0; m < 4; ++m)
; #pragma unroll
;                 for (int n = 0; n < 2; ++n) acc[a][b][m][n] = (f32x4){0.f, 0.f, 0.f, 0.f};
;     bf16x8 At[4][2], B0[2][2], B1[2][2];
;     const char* cA = (const char*)g.A + (size_t)cur.pm * tstep; const char* cB = (const char*)g.Bt + (size_t)cur.pn * tstep;
;     PG8_STAGE(PG8_SB(0, 0), cB, voffB); PG8_STAGE(PG8_SB(0, 1), cB + hstep, voffB); PG8_STAGE(PG8_SA(0, 0), cA, voffA); PG8_STAGE(PG8_SA(0, 1), cA + hstep, voffA);
;     if (wr == 1) PG8_BAR;
;     PG8_WAIT_V(2); PG8_BAR;
;     PG8_STAGE(PG8_SB(1, 0), cB + kstep, voffB); PG8_STAGE(PG8_SA(1, 0), cA + kstep, voffA); PG8_STAGE(PG8_SB(1, 1), cB + hstep + kstep, voffB);
;     PG8_WAIT_V(6); PG8_BAR;
.LBB0_64:
	s_cmp_lt_i32 s6, 2
	s_cselect_b64 s[2:3], -1, 0
	s_cmp_gt_i32 s7, 1
	s_cselect_b64 s[4:5], -1, 0
	s_and_b64 s[2:3], s[2:3], s[4:5]
	s_andn2_b64 vcc, exec, s[2:3]
	s_mov_b64 s[2:3], 0
	v_writelane_b32 v238, s2, 23
	s_nop 1
	v_writelane_b32 v238, s3, 24
	s_cbranch_vccnz .LBB0_142
	v_and_b32_e32 v1, 0x3ff, v0
	s_cmpk_gt_i32 s92, 0xaff
	v_readfirstlane_b32 s5, v1
	s_cbranch_scc1 .LBB0_81
	v_lshrrev_b32_e32 v2, 5, v1
	v_lshrrev_b32_e32 v4, 1, v1
	v_and_b32_e32 v2, 4, v2
	v_bfe_u32 v3, v1, 2, 2
	v_and_b32_e32 v13, 24, v4
	v_or3_b32 v2, v2, v3, v13
	v_lshlrev_b32_e32 v3, 4, v1
	v_add_u32_e32 v10, 0x2000, v3
	v_lshrrev_b32_e32 v4, 7, v10
	s_movk_i32 s2, 0xe0
	v_and_b32_e32 v6, 32, v1
	s_add_u32 s33, s86, 0x3000000
	v_and_or_b32 v5, v4, s2, v2
	v_bitop3_b32 v11, v3, v6, 48 bitop3:0x6c
	v_and_b32_e32 v12, 64, v1
	v_bfe_u32 v14, v1, 2, 4
	s_movk_i32 s2, 0xf0
	s_addc_u32 s40, s87, 0
	v_or_b32_e32 v3, v11, v12
	v_and_or_b32 v4, v4, s2, v14
	s_add_u32 s41, s86, 0x100000
	v_lshl_or_b32 v132, v4, 11, v3
	v_lshrrev_b32_e32 v4, 3, v1
	s_movk_i32 s2, 0x60
	s_addc_u32 s42, s87, 0
	v_and_or_b32 v2, v4, s2, v2
	s_movk_i32 s2, 0x70
	s_ashr_i32 s44, s92, 31
	v_lshl_or_b32 v134, v2, 11, v3
	v_and_or_b32 v2, v4, s2, v14
	s_lshr_b32 s2, s44, 29
	s_add_i32 s2, s92, s2
	s_lshr_b32 s8, s5, 6
	s_ashr_i32 s3, s2, 3
	s_and_b32 s2, s2, -8
	s_lshr_b32 s10, s5, 8
	s_lshl_b32 s43, s8, 10
	s_sub_i32 s2, s92, s2
	s_cmp_lt_i32 s2, 0
	s_movk_i32 s45, 0x161
	s_cselect_b32 s4, s45, 0x160
	s_mul_i32 s2, s2, s4
	s_add_i32 s2, s2, s3
	s_mul_hi_i32 s3, s2, 0x2e8ba2e9
	s_lshr_b32 s4, s3, 31
	s_ashr_i32 s3, s3, 5
	s_add_i32 s3, s3, s4
	s_lshl_b32 s6, s3, 3
	s_mulk_i32 s3, 0xb0
	s_sub_i32 s2, s2, s3
	s_sext_i32_i16 s3, s2
	s_bfe_u32 s3, s3, 0x3001c
	s_add_i32 s3, s2, s3
	s_sext_i32_i16 s4, s3
	s_and_b32 s3, s3, 0xfff8
	s_sub_i32 s2, s2, s3
	s_sext_i32_i16 s2, s2
	s_lshr_b32 s4, s4, 3
	s_add_i32 s30, s6, s2
	s_ashr_i32 s31, s30, 31
	s_bfe_i64 s[6:7], s[4:5], 0x100000
	s_lshl_b64 s[2:3], s[30:31], 19
	s_lshl_b64 s[6:7], s[6:7], 19
	s_add_u32 s36, s41, s6
	s_addc_u32 s37, s42, s7
	s_add_i32 s31, s43, 0
	s_add_i32 m0, s31, 0x10000
	v_lshl_or_b32 v130, v5, 11, v3
	global_load_lds_dwordx4 v134, s[36:37]
	s_add_i32 m0, s31, 0x12000
	s_add_u32 s6, s36, 0x40000
	global_load_lds_dwordx4 v130, s[36:37]
	s_addc_u32 s7, s37, 0
	s_add_i32 m0, s31, 0x14000
	v_lshl_or_b32 v136, v2, 11, v3
	global_load_lds_dwordx4 v134, s[6:7]
	s_add_i32 m0, s31, 0x16000
	s_add_u32 s34, s33, s2
	s_addc_u32 s35, s40, s3
	s_add_i32 s46, s31, 0x2000
	global_load_lds_dwordx4 v130, s[6:7]
	s_mov_b32 m0, s31
	s_add_u32 s2, s34, 0x40000
	global_load_lds_dwordx4 v136, s[34:35]
	s_mov_b32 m0, s46
	s_addc_u32 s3, s35, 0
	s_add_i32 s47, s31, 0x4000
	global_load_lds_dwordx4 v132, s[34:35]
	s_mov_b32 m0, s47
	s_add_i32 s48, s31, 0x6000
	global_load_lds_dwordx4 v136, s[2:3]
	s_mov_b32 m0, s48
	v_mov_b32_e32 v135, 0
	global_load_lds_dwordx4 v132, s[2:3]
	v_mov_b32_e32 v131, v135
	v_mov_b32_e32 v137, v135
	v_mov_b32_e32 v133, v135
	s_cmp_eq_u32 s10, 1
	s_mov_b32 s49, 0
	v_lshl_add_u64 v[8:9], s[36:37], 0, v[134:135]
	v_lshl_add_u64 v[6:7], s[36:37], 0, v[130:131]
	v_lshl_add_u64 v[2:3], s[34:35], 0, v[136:137]
	s_cselect_b64 s[2:3], -1, 0
	s_cmp_lg_u32 s10, 1
	v_lshl_add_u64 v[4:5], s[34:35], 0, v[132:133]
	s_cbranch_scc1 .LBB0_68
	s_barrier
	s_setprio 1

; #define PG8_STAGE(bufoff, gbase, voff) do { _Pragma("unroll") for (int _i = 0; _i < 2; ++_i) \
;         __builtin_amdgcn_global_load_lds((const unsigned*)((const char*)(gbase) + (voff)[_i]), (LAS unsigned*)(lds + (bufoff) + ldsw + _i * 8192), 16, 0, 0); } while (0)
; #define PG8_LDA(dst, b, h) do { _Pragma("unroll") for (int m = 0; m < 4; ++m) _Pragma("unroll") for (int k = 0; k < 2; ++k) dst[m][k] = *(const LAS bf16x8*)(lds + PG8_SA(b, h) + aoff + m * 2048 + k * 1024); } while (0)
; #define PG8_LDB(dst, b, h) do { _Pragma("unroll") for (int n = 0; n < 2; ++n) _Pragma("unroll") for (int k = 0; k < 2; ++k) dst[n][k] = *(const LAS bf16x8*)(lds + PG8_SB(b, h) + boff + n * 2048 + k * 1024); } while (0)
; #define PG8_MMA(ai, bj, At, Bt) do { __builtin_amdgcn_s_setprio(1); _Pragma("unroll") for (int m = 0; m < 4; ++m) _Pragma("unroll") for (int n = 0; n < 2; ++n) _Pragma("unroll") for (int k = 0; k < 2; ++k) \
;         acc[ai][bj][m][n] = __builtin_amdgcn_mfma_f32_16x16x32_bf16(Bt[n][k], At[m][k], acc[ai][bj][m][n], 0, 0, 0); __builtin_amdgcn_s_setprio(0); } while (0)
; #define PG8_WAIT_V(n) asm volatile("s_waitcnt vmcnt(" #n ")" ::: "memory")
; #define PG8_WAIT_L(n) asm volatile("s_waitcnt lgkmcnt(" #n ")" ::: "memory")
; #define PG8_BAR __builtin_amdgcn_s_barrier()
; #define PG8_SCHED __builtin_amdgcn_sched_barrier(0)
; template <class Epi>
; __device__ __forceinline__ void gemm_phase(LAS unsigned char* lds, const Gemm g, const StaticOrder& S, const Epi& E) {
;     ...
;         for (int t = 0; t < nt; t += 2) {
;             const bool last = (t == nt - 2);
;             const char* a1 = cA + (size_t)(t + 1) * kstep;
;             const char* a2 = last ? nA : cA + (size_t)(t + 2) * kstep; const char* b2 = last ? nB : cB + (size_t)(t + 2) * kstep;
;             const char* a3 = a2 + kstep; const char* b3 = b2 + kstep;
;             PG8_LDB(B0, 0, 0); PG8_LDB(B1, 0, 1); PG8_SCHED; PG8_LDA(At, 0, 0); PG8_STAGE(PG8_SA(1, 1), a1 + hstep, voffA);
;             PG8_WAIT_V(8); PG8_WAIT_L(0); PG8_BAR; PG8_MMA(0, 0, At, B0); PG8_MMA(0, 1, At, B1); PG8_BAR; PG8_SCHED;
;             PG8_LDA(At, 0, 1); PG8_STAGE(PG8_SB(0, 0), b2, voffB); PG8_STAGE(PG8_SB(0, 1), b2 + hstep, voffB); PG8_STAGE(PG8_SA(0, 0), a2, voffA);
.LBB0_74:
	ds_read_b128 v[146:149], v153
	ds_read_b128 v[156:159], v153 offset:1024
	ds_read_b128 v[160:163], v153 offset:2048
	ds_read_b128 v[164:167], v153 offset:3072
	ds_read_b128 v[168:171], v154
	ds_read_b128 v[172:175], v154 offset:1024
	ds_read_b128 v[176:179], v154 offset:2048
	ds_read_b128 v[180:183], v154 offset:3072
	s_add_u32 s36, s34, 0xfffc0080
	s_addc_u32 s37, s35, -1
	s_cmp_eq_u32 s61, 12
	s_cselect_b32 s39, s21, s37
	s_cselect_b32 s38, s57, s36
	s_cselect_b32 s37, s19, s60
	s_cselect_b32 s36, s58, s59
	v_lshl_add_u64 v[216:217], s[34:35], 0, v[138:139]
	s_add_i32 m0, s31, 0xc000
	ds_read_b128 v[184:187], v155
	ds_read_b128 v[188:191], v155 offset:1024
	ds_read_b128 v[192:195], v155 offset:2048
	ds_read_b128 v[196:199], v155 offset:3072
	ds_read_b128 v[200:203], v155 offset:4096
	ds_read_b128 v[204:207], v155 offset:5120
	ds_read_b128 v[208:211], v155 offset:6144
	ds_read_b128 v[212:215], v155 offset:7168
	global_load_lds_dwordx4 v[216:217], off
	v_lshl_add_u64 v[216:217], s[34:35], 0, v[140:141]
	s_add_i32 m0, s31, 0xe000
	s_nop 0
	global_load_lds_dwordx4 v[216:217], off
	s_waitcnt vmcnt(8)
	s_waitcnt lgkmcnt(0)
	s_barrier
	s_waitcnt lgkmcnt(0)
	v_mfma_f32_16x16x32_bf16 v[126:129], v[146:149], v[184:187], v[126:129]
	v_mfma_f32_16x16x32_bf16 v[118:121], v[160:163], v[184:187], v[118:121]
	v_mfma_f32_16x16x32_bf16 v[110:113], v[146:149], v[192:195], v[110:113]
	v_mfma_f32_16x16x32_bf16 v[102:105], v[160:163], v[192:195], v[102:105]
	v_mfma_f32_16x16x32_bf16 v[94:97], v[146:149], v[200:203], v[94:97]
	v_mfma_f32_16x16x32_bf16 v[86:89], v[160:163], v[200:203], v[86:89]
	v_mfma_f32_16x16x32_bf16 v[78:81], v[146:149], v[208:211], v[78:81]
	v_mfma_f32_16x16x32_bf16 v[70:73], v[160:163], v[208:211], v[70:73]
	v_mfma_f32_16x16x32_bf16 v[126:129], v[156:159], v[188:191], v[126:129]
	v_mfma_f32_16x16x32_bf16 v[118:121], v[164:167], v[188:191], v[118:121]
	v_mfma_f32_16x16x32_bf16 v[110:113], v[156:159], v[196:199], v[110:113]
	v_mfma_f32_16x16x32_bf16 v[102:105], v[164:167], v[196:199], v[102:105]
	v_mfma_f32_16x16x32_bf16 v[94:97], v[156:159], v[204:207], v[94:97]
	v_mfma_f32_16x16x32_bf16 v[86:89], v[164:167], v[204:207], v[86:89]
	v_mfma_f32_16x16x32_bf16 v[78:81], v[156:159], v[212:215], v[78:81]
	v_mfma_f32_16x16x32_bf16 v[70:73], v[164:167], v[212:215], v[70:73]
	v_mfma_f32_16x16x32_bf16 v[122:125], v[168:171], v[184:187], v[122:125]
	v_mfma_f32_16x16x32_bf16 v[114:117], v[176:179], v[184:187], v[114:117]
	v_mfma_f32_16x16x32_bf16 v[106:109], v[168:171], v[192:195], v[106:109]
	v_mfma_f32_16x16x32_bf16 v[98:101], v[176:179], v[192:195], v[98:101]
	v_mfma_f32_16x16x32_bf16 v[90:93], v[168:171], v[200:203], v[90:93]
	v_mfma_f32_16x16x32_bf16 v[82:85], v[176:179], v[200:203], v[82:85]
	v_mfma_f32_16x16x32_bf16 v[74:77], v[168:171], v[208:211], v[74:77]
	v_mfma_f32_16x16x32_bf16 v[66:69], v[176:179], v[208:211], v[66:69]
	v_mfma_f32_16x16x32_bf16 v[122:125], v[172:175], v[188:191], v[122:125]
	v_mfma_f32_16x16x32_bf16 v[114:117], v[180:183], v[188:191], v[114:117]
	v_mfma_f32_16x16x32_bf16 v[106:109], v[172:175], v[196:199], v[106:109]
	v_mfma_f32_16x16x32_bf16 v[98:101], v[180:183], v[196:199], v[98:101]
	v_mfma_f32_16x16x32_bf16 v[90:93], v[172:175], v[204:207], v[90:93]
	v_mfma_f32_16x16x32_bf16 v[82:85], v[180:183], v[204:207], v[82:85]
	v_mfma_f32_16x16x32_bf16 v[74:77], v[172:175], v[212:215], v[74:77]
	v_mfma_f32_16x16x32_bf16 v[66:69], v[180:183], v[212:215], v[66:69]
	s_barrier
	s_add_i32 s62, s53, s43
	v_lshl_add_u64 v[216:217], s[36:37], 0, v[134:135]
	s_mov_b32 m0, s62
	ds_read_b128 v[184:187], v155 offset:16384
	ds_read_b128 v[188:191], v155 offset:17408
	ds_read_b128 v[192:195], v155 offset:18432
	ds_read_b128 v[196:199], v155 offset:19456
	ds_read_b128 v[200:203], v155 offset:20480
	ds_read_b128 v[204:207], v155 offset:21504
	ds_read_b128 v[208:211], v155 offset:22528
	ds_read_b128 v[212:215], v155 offset:23552
	global_load_lds_dwordx4 v[216:217], off
	s_add_i32 m0, s62, 0x2000
	s_add_u32 s62, s36, 0x40000
	v_lshl_add_u64 v[218:219], s[36:37], 0, v[130:131]
	s_addc_u32 s63, s37, 0
	s_add_i32 s64, s54, s43
	global_load_lds_dwordx4 v[218:219], off
	v_lshl_add_u64 v[220:221], s[62:63], 0, v[134:135]
	s_mov_b32 m0, s64
	v_lshl_add_u64 v[222:223], s[38:39], 0, v[132:133]
	global_load_lds_dwordx4 v[220:221], off
	v_lshl_add_u64 v[220:221], s[62:63], 0, v[130:131]
	s_add_i32 m0, s64, 0x2000
	s_nop 0
	global_load_lds_dwordx4 v[220:221], off
	v_lshl_add_u64 v[220:221], s[38:39], 0, v[136:137]
	s_mov_b32 m0, s31
	s_nop 0
	global_load_lds_dwordx4 v[220:221], off
	s_mov_b32 m0, s46
	s_nop 0
	global_load_lds_dwordx4 v[222:223], off
	s_waitcnt vmcnt(8)
	s_waitcnt lgkmcnt(0)
	s_barrier
; #define PG8_STAGE(bufoff, gbase, voff) do { _Pragma("unroll") for (int _i = 0; _i < 2; ++_i) \
;         __builtin_amdgcn_global_load_lds((const unsigned*)((const char*)(gbase) + (voff)[_i]), (LAS unsigned*)(lds + (bufoff) + ldsw + _i * 8192), 16, 0, 0); } while (0)
; #define PG8_LDA(dst, b, h) do { _Pragma("unroll") for (int m = 0; m < 4; ++m) _Pragma("unroll") for (int k = 0; k < 2; ++k) dst[m][k] = *(const LAS bf16x8*)(lds + PG8_SA(b, h) + aoff + m * 2048 + k * 1024); } while (0)
; #define PG8_LDB(dst, b, h) do { _Pragma("unroll") for (int n = 0; n < 2; ++n) _Pragma("unroll") for (int k = 0; k < 2; ++k) dst[n][k] = *(const LAS bf16x8*)(lds + PG8_SB(b, h) + boff + n * 2048 + k * 1024); } while (0)
; #define PG8_MMA(ai, bj, At, Bt) do { __builtin_amdgcn_s_setprio(1); _Pragma("unroll") for (int m = 0; m < 4; ++m) _Pragma("unroll") for (int n = 0; n < 2; ++n) _Pragma("unroll") for (int k = 0; k < 2; ++k) \
;         acc[ai][bj][m][n] = __builtin_amdgcn_mfma_f32_16x16x32_bf16(Bt[n][k], At[m][k], acc[ai][bj][m][n], 0, 0, 0); __builtin_amdgcn_s_setprio(0); } while (0)
; #define PG8_WAIT_V(n) asm volatile("s_waitcnt vmcnt(" #n ")" ::: "memory")
; #define PG8_WAIT_L(n) asm volatile("s_waitcnt lgkmcnt(" #n ")" ::: "memory")
; #define PG8_BAR __builtin_amdgcn_s_barrier()
; #define PG8_SCHED __builtin_amdgcn_sched_barrier(0)
; template <class Epi>
; __device__ __forceinline__ void gemm_phase(LAS unsigned char* lds, const Gemm g, const StaticOrder& S, const Epi& E) {
;     ...
;             PG8_WAIT_V(8); PG8_WAIT_L(0); PG8_BAR; PG8_MMA(1, 0, At, B0); PG8_MMA(1, 1, At, B1); PG8_BAR; PG8_SCHED;
;             PG8_LDB(B0, 1, 0); PG8_LDB(B1, 1, 1); PG8_SCHED; PG8_LDA(At, 1, 0); PG8_STAGE(PG8_SA(0, 1), a2 + hstep, voffA);
;             PG8_WAIT_V(8); PG8_WAIT_L(0); PG8_BAR; PG8_MMA(0, 0, At, B0); PG8_MMA(0, 1, At, B1); PG8_BAR; PG8_SCHED;
;             PG8_LDA(At, 1, 1); PG8_STAGE(PG8_SB(1, 0), b3, voffB); PG8_STAGE(PG8_SB(1, 1), b3 + hstep, voffB); PG8_STAGE(PG8_SA(1, 0), a3, voffA);
	s_waitcnt lgkmcnt(0)
	v_mfma_f32_16x16x32_bf16 v[62:65], v[146:149], v[184:187], v[62:65]
	v_mfma_f32_16x16x32_bf16 v[54:57], v[160:163], v[184:187], v[54:57]
	v_mfma_f32_16x16x32_bf16 v[46:49], v[146:149], v[192:195], v[46:49]
	v_mfma_f32_16x16x32_bf16 v[38:41], v[160:163], v[192:195], v[38:41]
	v_mfma_f32_16x16x32_bf16 v[30:33], v[146:149], v[200:203], v[30:33]
	v_mfma_f32_16x16x32_bf16 v[22:25], v[160:163], v[200:203], v[22:25]
	v_mfma_f32_16x16x32_bf16 v[14:17], v[146:149], v[208:211], v[14:17]
	v_mfma_f32_16x16x32_bf16 v[6:9], v[160:163], v[208:211], v[6:9]
	v_mfma_f32_16x16x32_bf16 v[62:65], v[156:159], v[188:191], v[62:65]
	v_mfma_f32_16x16x32_bf16 v[54:57], v[164:167], v[188:191], v[54:57]
	v_mfma_f32_16x16x32_bf16 v[46:49], v[156:159], v[196:199], v[46:49]
	v_mfma_f32_16x16x32_bf16 v[38:41], v[164:167], v[196:199], v[38:41]
	v_mfma_f32_16x16x32_bf16 v[30:33], v[156:159], v[204:207], v[30:33]
	v_mfma_f32_16x16x32_bf16 v[22:25], v[164:167], v[204:207], v[22:25]
	v_mfma_f32_16x16x32_bf16 v[14:17], v[156:159], v[212:215], v[14:17]
	v_mfma_f32_16x16x32_bf16 v[6:9], v[164:167], v[212:215], v[6:9]
	v_mfma_f32_16x16x32_bf16 v[58:61], v[168:171], v[184:187], v[58:61]
	v_mfma_f32_16x16x32_bf16 v[50:53], v[176:179], v[184:187], v[50:53]
	v_mfma_f32_16x16x32_bf16 v[42:45], v[168:171], v[192:195], v[42:45]
	v_mfma_f32_16x16x32_bf16 v[34:37], v[176:179], v[192:195], v[34:37]
	v_mfma_f32_16x16x32_bf16 v[26:29], v[168:171], v[200:203], v[26:29]
	v_mfma_f32_16x16x32_bf16 v[18:21], v[176:179], v[200:203], v[18:21]
	v_mfma_f32_16x16x32_bf16 v[10:13], v[168:171], v[208:211], v[10:13]
	v_mfma_f32_16x16x32_bf16 v[2:5], v[176:179], v[208:211], v[2:5]
	v_mfma_f32_16x16x32_bf16 v[58:61], v[172:175], v[188:191], v[58:61]
	v_mfma_f32_16x16x32_bf16 v[50:53], v[180:183], v[188:191], v[50:53]
	v_mfma_f32_16x16x32_bf16 v[42:45], v[172:175], v[196:199], v[42:45]
	v_mfma_f32_16x16x32_bf16 v[34:37], v[180:183], v[196:199], v[34:37]
	v_mfma_f32_16x16x32_bf16 v[26:29], v[172:175], v[204:207], v[26:29]
	v_mfma_f32_16x16x32_bf16 v[18:21], v[180:183], v[204:207], v[18:21]
	v_mfma_f32_16x16x32_bf16 v[10:13], v[172:175], v[212:215], v[10:13]
	v_mfma_f32_16x16x32_bf16 v[2:5], v[180:183], v[212:215], v[2:5]
	s_barrier
	s_add_i32 s62, 0, 0x18000
	s_add_i32 s63, 0, 0x1c000
	v_add_u32_e32 v164, s62, v151
	v_add_u32_e32 v180, s63, v151
	ds_read_b128 v[146:149], v164
	ds_read_b128 v[156:159], v164 offset:1024
	ds_read_b128 v[160:163], v164 offset:2048
	ds_read_b128 v[164:167], v164 offset:3072
	ds_read_b128 v[168:171], v180
	ds_read_b128 v[172:175], v180 offset:1024
	ds_read_b128 v[176:179], v180 offset:2048
	ds_read_b128 v[180:183], v180 offset:3072
	s_add_u32 s38, s38, 0x40000
	s_addc_u32 s39, s39, 0
	s_mov_b32 m0, s47
	v_lshl_add_u64 v[224:225], s[38:39], 0, v[136:137]
	ds_read_b128 v[184:187], v155 offset:32768
	ds_read_b128 v[188:191], v155 offset:33792
	ds_read_b128 v[192:195], v155 offset:34816
	ds_read_b128 v[196:199], v155 offset:35840
	ds_read_b128 v[200:203], v155 offset:36864
	ds_read_b128 v[204:207], v155 offset:37888
	ds_read_b128 v[208:211], v155 offset:38912
	ds_read_b128 v[212:215], v155 offset:39936
	global_load_lds_dwordx4 v[224:225], off
	v_lshl_add_u64 v[224:225], s[38:39], 0, v[132:133]
	s_mov_b32 m0, s48
	s_nop 0
	global_load_lds_dwordx4 v[224:225], off
	s_waitcnt vmcnt(8)
	s_waitcnt lgkmcnt(0)
	s_barrier
	s_waitcnt lgkmcnt(0)
	v_mfma_f32_16x16x32_bf16 v[126:129], v[146:149], v[184:187], v[126:129]
	v_mfma_f32_16x16x32_bf16 v[118:121], v[160:163], v[184:187], v[118:121]
	v_mfma_f32_16x16x32_bf16 v[110:113], v[146:149], v[192:195], v[110:113]
	v_mfma_f32_16x16x32_bf16 v[102:105], v[160:163], v[192:195], v[102:105]
	v_mfma_f32_16x16x32_bf16 v[94:97], v[146:149], v[200:203], v[94:97]
	v_mfma_f32_16x16x32_bf16 v[86:89], v[160:163], v[200:203], v[86:89]
	v_mfma_f32_16x16x32_bf16 v[78:81], v[146:149], v[208:211], v[78:81]
	v_mfma_f32_16x16x32_bf16 v[70:73], v[160:163], v[208:211], v[70:73]
	v_mfma_f32_16x16x32_bf16 v[126:129], v[156:159], v[188:191], v[126:129]
	v_mfma_f32_16x16x32_bf16 v[118:121], v[164:167], v[188:191], v[118:121]
	v_mfma_f32_16x16x32_bf16 v[110:113], v[156:159], v[196:199], v[110:113]
	v_mfma_f32_16x16x32_bf16 v[102:105], v[164:167], v[196:199], v[102:105]
	v_mfma_f32_16x16x32_bf16 v[94:97], v[156:159], v[204:207], v[94:97]
	v_mfma_f32_16x16x32_bf16 v[86:89], v[164:167], v[204:207], v[86:89]
	v_mfma_f32_16x16x32_bf16 v[78:81], v[156:159], v[212:215], v[78:81]
	v_mfma_f32_16x16x32_bf16 v[70:73], v[164:167], v[212:215], v[70:73]
	v_mfma_f32_16x16x32_bf16 v[122:125], v[168:171], v[184:187], v[122:125]
	v_mfma_f32_16x16x32_bf16 v[114:117], v[176:179], v[184:187], v[114:117]
	v_mfma_f32_16x16x32_bf16 v[106:109], v[168:171], v[192:195], v[106:109]
	v_mfma_f32_16x16x32_bf16 v[98:101], v[176:179], v[192:195], v[98:101]
	v_mfma_f32_16x16x32_bf16 v[90:93], v[168:171], v[200:203], v[90:93]
	v_mfma_f32_16x16x32_bf16 v[82:85], v[176:179], v[200:203], v[82:85]
	v_mfma_f32_16x16x32_bf16 v[74:77], v[168:171], v[208:211], v[74:77]
	v_mfma_f32_16x16x32_bf16 v[66:69], v[176:179], v[208:211], v[66:69]
	v_mfma_f32_16x16x32_bf16 v[122:125], v[172:175], v[188:191], v[122:125]
	v_mfma_f32_16x16x32_bf16 v[114:117], v[180:183], v[188:191], v[114:117]
	v_mfma_f32_16x16x32_bf16 v[106:109], v[172:175], v[196:199], v[106:109]
	v_mfma_f32_16x16x32_bf16 v[98:101], v[180:183], v[196:199], v[98:101]
	v_mfma_f32_16x16x32_bf16 v[90:93], v[172:175], v[204:207], v[90:93]
	v_mfma_f32_16x16x32_bf16 v[82:85], v[180:183], v[204:207], v[82:85]
	v_mfma_f32_16x16x32_bf16 v[74:77], v[172:175], v[212:215], v[74:77]
	v_mfma_f32_16x16x32_bf16 v[66:69], v[180:183], v[212:215], v[66:69]
	s_barrier
; #define PG8_STAGE(bufoff, gbase, voff) do { _Pragma("unroll") for (int _i = 0; _i < 2; ++_i) \
;         __builtin_amdgcn_global_load_lds((const unsigned*)((const char*)(gbase) + (voff)[_i]), (LAS unsigned*)(lds + (bufoff) + ldsw + _i * 8192), 16, 0, 0); } while (0)
; #define PG8_LDA(dst, b, h) do { _Pragma("unroll") for (int m = 0; m < 4; ++m) _Pragma("unroll") for (int k = 0; k < 2; ++k) dst[m][k] = *(const LAS bf16x8*)(lds + PG8_SA(b, h) + aoff + m * 2048 + k * 1024); } while (0)
; #define PG8_MMA(ai, bj, At, Bt) do { __builtin_amdgcn_s_setprio(1); _Pragma("unroll") for (int m = 0; m < 4; ++m) _Pragma("unroll") for (int n = 0; n < 2; ++n) _Pragma("unroll") for (int k = 0; k < 2; ++k) \
;         acc[ai][bj][m][n] = __builtin_amdgcn_mfma_f32_16x16x32_bf16(Bt[n][k], At[m][k], acc[ai][bj][m][n], 0, 0, 0); __builtin_amdgcn_s_setprio(0); } while (0)
; #define PG8_WAIT_V(n) asm volatile("s_waitcnt vmcnt(" #n ")" ::: "memory")
; #define PG8_WAIT_L(n) asm volatile("s_waitcnt lgkmcnt(" #n ")" ::: "memory")
; #define PG8_BAR __builtin_amdgcn_s_barrier()
; #define PG8_SCHED __builtin_amdgcn_sched_barrier(0)
; template <class Epi>
; __device__ __forceinline__ void gemm_phase(LAS unsigned char* lds, const Gemm g, const StaticOrder& S, const Epi& E) {
;     ...
;             PG8_LDA(At, 1, 1); PG8_STAGE(PG8_SB(1, 0), b3, voffB); PG8_STAGE(PG8_SB(1, 1), b3 + hstep, voffB); PG8_STAGE(PG8_SA(1, 0), a3, voffA);
;             PG8_WAIT_V(8); PG8_WAIT_L(0); PG8_BAR; PG8_MMA(1, 0, At, B0); PG8_MMA(1, 1, At, B1); PG8_BAR; PG8_SCHED;
;         }
;         if (wr == 0) PG8_BAR;
	s_add_i32 s38, s62, s43
	v_lshl_add_u64 v[216:217], v[216:217], 0, s[8:9]
	s_mov_b32 m0, s38
	ds_read_b128 v[184:187], v155 offset:49152
	ds_read_b128 v[188:191], v155 offset:50176
	ds_read_b128 v[192:195], v155 offset:51200
	ds_read_b128 v[196:199], v155 offset:52224
	ds_read_b128 v[200:203], v155 offset:53248
	ds_read_b128 v[204:207], v155 offset:54272
	ds_read_b128 v[208:211], v155 offset:55296
	ds_read_b128 v[212:215], v155 offset:56320
	global_load_lds_dwordx4 v[216:217], off
	s_add_i32 m0, s38, 0x2000
	s_add_u32 s36, s36, 0x40080
	v_lshl_add_u64 v[216:217], v[218:219], 0, s[8:9]
	s_addc_u32 s37, s37, 0
	s_add_i32 s38, s63, s43
	global_load_lds_dwordx4 v[216:217], off
	v_lshl_add_u64 v[216:217], s[36:37], 0, v[134:135]
	s_mov_b32 m0, s38
	s_nop 0
	global_load_lds_dwordx4 v[216:217], off
	v_lshl_add_u64 v[216:217], s[36:37], 0, v[130:131]
	s_add_i32 m0, s38, 0x2000
	s_nop 0
	global_load_lds_dwordx4 v[216:217], off
	v_lshl_add_u64 v[216:217], v[220:221], 0, s[8:9]
	s_mov_b32 m0, s50
	s_nop 0
	global_load_lds_dwordx4 v[216:217], off
	v_lshl_add_u64 v[216:217], v[222:223], 0, s[8:9]
	s_mov_b32 m0, s51
	s_nop 0
	global_load_lds_dwordx4 v[216:217], off
	s_waitcnt vmcnt(8)
	s_waitcnt lgkmcnt(0)
	s_barrier
	s_waitcnt lgkmcnt(0)
	v_mfma_f32_16x16x32_bf16 v[62:65], v[146:149], v[184:187], v[62:65]
	v_mfma_f32_16x16x32_bf16 v[54:57], v[160:163], v[184:187], v[54:57]
	v_mfma_f32_16x16x32_bf16 v[46:49], v[146:149], v[192:195], v[46:49]
	v_mfma_f32_16x16x32_bf16 v[38:41], v[160:163], v[192:195], v[38:41]
	v_mfma_f32_16x16x32_bf16 v[30:33], v[146:149], v[200:203], v[30:33]
	v_mfma_f32_16x16x32_bf16 v[22:25], v[160:163], v[200:203], v[22:25]
	v_mfma_f32_16x16x32_bf16 v[14:17], v[146:149], v[208:211], v[14:17]
	v_mfma_f32_16x16x32_bf16 v[6:9], v[160:163], v[208:211], v[6:9]
	v_mfma_f32_16x16x32_bf16 v[62:65], v[156:159], v[188:191], v[62:65]
	v_mfma_f32_16x16x32_bf16 v[54:57], v[164:167], v[188:191], v[54:57]
	v_mfma_f32_16x16x32_bf16 v[46:49], v[156:159], v[196:199], v[46:49]
	v_mfma_f32_16x16x32_bf16 v[38:41], v[164:167], v[196:199], v[38:41]
	v_mfma_f32_16x16x32_bf16 v[30:33], v[156:159], v[204:207], v[30:33]
	v_mfma_f32_16x16x32_bf16 v[22:25], v[164:167], v[204:207], v[22:25]
	v_mfma_f32_16x16x32_bf16 v[14:17], v[156:159], v[212:215], v[14:17]
	v_mfma_f32_16x16x32_bf16 v[6:9], v[164:167], v[212:215], v[6:9]
	v_mfma_f32_16x16x32_bf16 v[58:61], v[168:171], v[184:187], v[58:61]
	v_mfma_f32_16x16x32_bf16 v[50:53], v[176:179], v[184:187], v[50:53]
	v_mfma_f32_16x16x32_bf16 v[42:45], v[168:171], v[192:195], v[42:45]
	v_mfma_f32_16x16x32_bf16 v[34:37], v[176:179], v[192:195], v[34:37]
	v_mfma_f32_16x16x32_bf16 v[26:29], v[168:171], v[200:203], v[26:29]
	v_mfma_f32_16x16x32_bf16 v[18:21], v[176:179], v[200:203], v[18:21]
	v_mfma_f32_16x16x32_bf16 v[10:13], v[168:171], v[208:211], v[10:13]
	v_mfma_f32_16x16x32_bf16 v[2:5], v[176:179], v[208:211], v[2:5]
	v_mfma_f32_16x16x32_bf16 v[58:61], v[172:175], v[188:191], v[58:61]
	v_mfma_f32_16x16x32_bf16 v[50:53], v[180:183], v[188:191], v[50:53]
	v_mfma_f32_16x16x32_bf16 v[42:45], v[172:175], v[196:199], v[42:45]
	v_mfma_f32_16x16x32_bf16 v[34:37], v[180:183], v[196:199], v[34:37]
	v_mfma_f32_16x16x32_bf16 v[26:29], v[172:175], v[204:207], v[26:29]
	v_mfma_f32_16x16x32_bf16 v[18:21], v[180:183], v[204:207], v[18:21]
	v_mfma_f32_16x16x32_bf16 v[10:13], v[172:175], v[212:215], v[10:13]
	v_mfma_f32_16x16x32_bf16 v[2:5], v[180:183], v[212:215], v[2:5]
	s_barrier
	s_add_i32 s61, s61, 2
	s_add_u32 s34, s34, 0x100
	s_addc_u32 s35, s35, 0
	s_add_u32 s59, s59, 0x100
	s_addc_u32 s60, s60, 0
	s_cmp_gt_u32 s61, 13
	s_cbranch_scc0 .LBB0_74
	s_and_b64 vcc, exec, s[10:11]
	s_cbranch_vccz .LBB0_77
	s_barrier

; #define SEAM(k) do { if ((k) + 1 < hi) { if ((k) == 0) { __syncthreads(); cg::this_grid().sync(); } \
;         else { if (!xposted) { if (threadIdx.x == 0) { xst[0] = 0u; xst[1] = 0u; } __syncthreads(); xbar = xcd_barrier_post((unsigned*)(ws + 65536), xst); xposted = true; } xcd_barrier(xbar); } } } while (0)
; __global__ void __launch_bounds__(512) fwd_kernel(Args a) {
;     ...
;     if (IN(1)) { pg8::Gemm g{(const bf16_t*)(ws + WS_XB), (const bf16_t*)(ws + WS_WUP1), M, NUP, D}; pg8::StaticOrder S; S.init(M, NUP, G, bx);
;                  pg8::EpiSwiGLU E{(bf16_t*)(ws + WS_BIG), FF}; pg8::gemm_phase(lds, g, S, E); SEAM(1); }
.LBB0_81:
	s_setprio 0
	s_load_dwordx2 s[2:3], s[0:1], 0xd0
	s_waitcnt lgkmcnt(0)
	s_cmp_lt_i32 s3, 3
	s_cbranch_scc1 .LBB0_98
	v_cmp_eq_u32_e32 vcc, 0, v1
	s_and_saveexec_b64 s[2:3], vcc
	s_cbranch_execz .LBB0_84
	s_add_i32 s4, 0, 0x23ff0
	v_mov_b32_e32 v1, 0
	v_mov_b32_e32 v2, s4
	s_add_i32 s4, 0, 0x23ff4
	ds_write_b32 v2, v1
	v_mov_b32_e32 v2, s4
	ds_write_b32 v2, v1

; #define PG8_STAGE(bufoff, gbase, voff) do { _Pragma("unroll") for (int _i = 0; _i < 2; ++_i) \
;         __builtin_amdgcn_global_load_lds((const unsigned*)((const char*)(gbase) + (voff)[_i]), (LAS unsigned*)(lds + (bufoff) + ldsw + _i * 8192), 16, 0, 0); } while (0)
; #define PG8_WAIT_V(n) asm volatile("s_waitcnt vmcnt(" #n ")" ::: "memory")
; #define PG8_BAR __builtin_amdgcn_s_barrier()
; template <class Epi>
; __device__ __forceinline__ void gemm_phase(LAS unsigned char* lds, const Gemm g, const StaticOrder& S, const Epi& E) {
;     const int tid = threadIdx.x, wid = __builtin_amdgcn_readfirstlane(tid >> 6), lane = tid & 63, wr = wid >> 2, wc = wid & 3, fr = lane & 15, fq = lane >> 4;
;     const int K = g.K, nt = K / BK;
;     unsigned voffA[2], voffB[2];
; #pragma unroll
;     for (int i = 0; i < 2; ++i) { int R, C; stage_rc(tid * 16 + i * 8192, R, C); const int Rb = Epi::PERM ? ((R & ~31) + perm32(R & 31)) : R;
;         voffA[i] = (unsigned)(R * K + C) * 2u; voffB[i] = (unsigned)(Rb * K + C) * 2u; }
;     const size_t kstep = (size_t)(BK * 2);
;     const size_t hstep = (size_t)HALF * K * 2;
;     const size_t tstep = 2 * hstep;
;     const unsigned ldsw = (unsigned)wid * 1024u;
;     const int aoff = lds_byte(wr * 64 + fr, fq * 8), boff = lds_byte(wc * 32 + fr, fq * 8);
;     ...
;     Unit cur, nxt; int ui = 0;
;     if (!S.next(0, cur)) return;
;     f32x4 acc[2][2][4][2];
; #pragma unroll
;     for (int a = 0; a < 2; ++a)
; #pragma unroll
;         for (int b = 0; b < 2; ++b)
; #pragma unroll
;             for (int m = 0; m < 4; ++m)
; #pragma unroll
;                 for (int n = 0; n < 2; ++n) acc[a][b][m][n] = (f32x4){0.f, 0.f, 0.f, 0.f};
;     bf16x8 At[4][2], B0[2][2], B1[2][2];
;     const char* cA = (const char*)g.A + (size_t)cur.pm * tstep; const char* cB = (const char*)g.Bt + (size_t)cur.pn * tstep;
;     PG8_STAGE(PG8_SB(0, 0), cB, voffB); PG8_STAGE(PG8_SB(0, 1), cB + hstep, voffB); PG8_STAGE(PG8_SA(0, 0), cA, voffA); PG8_STAGE(PG8_SA(0, 1), cA + hstep, voffA);
;     if (wr == 1) PG8_BAR;
;     PG8_WAIT_V(2); PG8_BAR;
;     PG8_STAGE(PG8_SB(1, 0), cB + kstep, voffB); PG8_STAGE(PG8_SA(1, 0), cA + kstep, voffA); PG8_STAGE(PG8_SB(1, 1), cB + hstep + kstep, voffB);
;     PG8_WAIT_V(6); PG8_BAR;
.LBB0_148:
	s_ashr_i32 s1, s3, 3
	s_add_u32 s33, s86, 0x7000000
	s_addc_u32 s54, s87, 0
	s_add_u32 s55, s86, 0xc00000
	s_addc_u32 s56, s87, 0
	s_add_i32 s1, s2, s1
	v_lshlrev_b32_e32 v2, 4, v1
	v_and_b32_e32 v3, 32, v1
	s_ashr_i32 s2, s1, 31
	v_bfe_u32 v4, v1, 2, 4
	v_bitop3_b32 v10, v2, v3, 48 bitop3:0x6c
	v_lshrrev_b32_e32 v5, 3, v1
	s_movk_i32 s3, 0x70
	v_add_u32_e32 v2, 0x2000, v2
	s_lshr_b32 s2, s2, 27
	v_and_or_b32 v5, v5, s3, v4
	v_lshrrev_b32_e32 v2, 7, v2
	s_movk_i32 s3, 0xf0
	s_add_i32 s2, s1, s2
	v_and_or_b32 v2, v2, s3, v4
	s_ashr_i32 s3, s2, 5
	s_andn2_b32 s2, s2, 31
	s_sub_i32 s2, s1, s2
	s_bfe_i32 s1, s2, 0x80000
	s_bfe_u32 s1, s1, 0x3000c
	s_add_i32 s6, s2, s1
	s_bfe_i32 s1, s6, 0x80000
	s_and_b32 s6, s6, 0xf8
	s_sub_i32 s2, s2, s6
	s_lshl_b32 s3, s3, 3
	s_sext_i32_i16 s7, s1
	s_sext_i32_i8 s2, s2
	s_lshr_b32 s5, s4, 6
	s_add_i32 s70, s3, s2
	s_ashr_i32 s2, s7, 3
	s_lshr_b32 s0, s4, 8
	s_lshl_b32 s57, s5, 10
	s_lshr_b32 s1, s7, 3
	s_mul_hi_i32 s3, s2, 0x160000
	s_mul_i32 s2, s2, 0x160000
	v_and_b32_e32 v11, 64, v1
	s_add_u32 s34, s55, s2
	v_or_b32_e32 v3, v10, v11
	v_mul_u32_u24_e32 v12, 0x1600, v5
	s_addc_u32 s35, s56, s3
	s_add_i32 s58, s57, 0
	v_or_b32_e32 v130, v12, v3
	s_add_i32 m0, s58, 0x10000
	v_mul_u32_u24_e32 v13, 0x1600, v2
	global_load_lds_dwordx4 v130, s[34:35]
	s_add_i32 m0, s58, 0x12000
	v_or_b32_e32 v132, v13, v3
	s_add_u32 s2, s34, 0xb0000
	global_load_lds_dwordx4 v132, s[34:35]
	s_addc_u32 s3, s35, 0
	s_add_i32 m0, s58, 0x14000
	s_mul_i32 s8, s70, 0x160000
	global_load_lds_dwordx4 v130, s[2:3]
	s_add_i32 m0, s58, 0x16000
	s_mul_hi_i32 s6, s70, 0x160000
	s_add_u32 s30, s33, s8
	s_addc_u32 s31, s54, s6
	s_add_i32 s59, s58, 0x2000
	global_load_lds_dwordx4 v132, s[2:3]
	s_mov_b32 m0, s58
	s_add_u32 s2, s30, 0xb0000
	global_load_lds_dwordx4 v130, s[30:31]
	s_mov_b32 m0, s59
	s_addc_u32 s3, s31, 0
	s_add_i32 s60, s58, 0x4000
	global_load_lds_dwordx4 v132, s[30:31]
	s_mov_b32 m0, s60
	s_add_i32 s61, s58, 0x6000
	global_load_lds_dwordx4 v130, s[2:3]
	s_mov_b32 m0, s61
	v_mov_b32_e32 v131, 0
	global_load_lds_dwordx4 v132, s[2:3]
	v_mov_b32_e32 v133, v131
	s_cmp_eq_u32 s0, 1
	s_mov_b32 s62, 0
	v_lshl_add_u64 v[8:9], s[34:35], 0, v[130:131]
	v_lshl_add_u64 v[6:7], s[34:35], 0, v[132:133]
	v_lshl_add_u64 v[2:3], s[30:31], 0, v[130:131]
	s_cselect_b64 s[2:3], -1, 0
	s_cmp_lg_u32 s0, 1
	v_lshl_add_u64 v[4:5], s[30:31], 0, v[132:133]
	s_cbranch_scc1 .LBB0_150
	s_barrier
	s_setprio 1

; #define PG8_STAGE(bufoff, gbase, voff) do { _Pragma("unroll") for (int _i = 0; _i < 2; ++_i) \
;         __builtin_amdgcn_global_load_lds((const unsigned*)((const char*)(gbase) + (voff)[_i]), (LAS unsigned*)(lds + (bufoff) + ldsw + _i * 8192), 16, 0, 0); } while (0)
; #define PG8_LDA(dst, b, h) do { _Pragma("unroll") for (int m = 0; m < 4; ++m) _Pragma("unroll") for (int k = 0; k < 2; ++k) dst[m][k] = *(const LAS bf16x8*)(lds + PG8_SA(b, h) + aoff + m * 2048 + k * 1024); } while (0)
; #define PG8_LDB(dst, b, h) do { _Pragma("unroll") for (int n = 0; n < 2; ++n) _Pragma("unroll") for (int k = 0; k < 2; ++k) dst[n][k] = *(const LAS bf16x8*)(lds + PG8_SB(b, h) + boff + n * 2048 + k * 1024); } while (0)
; #define PG8_MMA(ai, bj, At, Bt) do { __builtin_amdgcn_s_setprio(1); _Pragma("unroll") for (int m = 0; m < 4; ++m) _Pragma("unroll") for (int n = 0; n < 2; ++n) _Pragma("unroll") for (int k = 0; k < 2; ++k) \
;         acc[ai][bj][m][n] = __builtin_amdgcn_mfma_f32_16x16x32_bf16(Bt[n][k], At[m][k], acc[ai][bj][m][n], 0, 0, 0); __builtin_amdgcn_s_setprio(0); } while (0)
; #define PG8_WAIT_V(n) asm volatile("s_waitcnt vmcnt(" #n ")" ::: "memory")
; #define PG8_WAIT_L(n) asm volatile("s_waitcnt lgkmcnt(" #n ")" ::: "memory")
; #define PG8_BAR __builtin_amdgcn_s_barrier()
; #define PG8_SCHED __builtin_amdgcn_sched_barrier(0)
; template <class Epi>
; __device__ __forceinline__ void gemm_phase(LAS unsigned char* lds, const Gemm g, const StaticOrder& S, const Epi& E) {
;     ...
;         for (int t = 0; t < nt; t += 2) {
;             const bool last = (t == nt - 2);
;             const char* a1 = cA + (size_t)(t + 1) * kstep;
;             const char* a2 = last ? nA : cA + (size_t)(t + 2) * kstep; const char* b2 = last ? nB : cB + (size_t)(t + 2) * kstep;
;             const char* a3 = a2 + kstep; const char* b3 = b2 + kstep;
;             PG8_LDB(B0, 0, 0); PG8_LDB(B1, 0, 1); PG8_SCHED; PG8_LDA(At, 0, 0); PG8_STAGE(PG8_SA(1, 1), a1 + hstep, voffA);
;             PG8_WAIT_V(8); PG8_WAIT_L(0); PG8_BAR; PG8_MMA(0, 0, At, B0); PG8_MMA(0, 1, At, B1); PG8_BAR; PG8_SCHED;
;             PG8_LDA(At, 0, 1); PG8_STAGE(PG8_SB(0, 0), b2, voffB); PG8_STAGE(PG8_SB(0, 1), b2 + hstep, voffB); PG8_STAGE(PG8_SA(0, 0), a2, voffA);
.LBB0_164:
	ds_read_b128 v[150:153], v147
	ds_read_b128 v[154:157], v147 offset:1024
	ds_read_b128 v[158:161], v147 offset:2048
	ds_read_b128 v[162:165], v147 offset:3072
	ds_read_b128 v[166:169], v148
	ds_read_b128 v[170:173], v148 offset:1024
	ds_read_b128 v[174:177], v148 offset:2048
	ds_read_b128 v[178:181], v148 offset:3072
	s_add_u32 s34, s30, 0xfff50080
	s_addc_u32 s35, s31, -1
	s_cmp_eq_u32 s74, 40
	s_cselect_b32 s53, s5, s35
	s_cselect_b32 s52, s4, s34
	s_cselect_b32 s35, s29, s73
	s_cselect_b32 s34, s28, s72
	v_lshl_add_u64 v[142:143], s[30:31], 0, v[134:135]
	s_add_i32 m0, s58, 0xc000
	ds_read_b128 v[182:185], v149
	ds_read_b128 v[186:189], v149 offset:1024
	ds_read_b128 v[190:193], v149 offset:2048
	ds_read_b128 v[194:197], v149 offset:3072
	ds_read_b128 v[198:201], v149 offset:4096
	ds_read_b128 v[202:205], v149 offset:5120
	ds_read_b128 v[206:209], v149 offset:6144
	ds_read_b128 v[210:213], v149 offset:7168
	global_load_lds_dwordx4 v[142:143], off
	v_lshl_add_u64 v[142:143], s[30:31], 0, v[136:137]
	s_add_i32 m0, s58, 0xe000
	s_nop 0
	global_load_lds_dwordx4 v[142:143], off
	s_waitcnt vmcnt(8)
	s_waitcnt lgkmcnt(0)
	s_barrier
	s_waitcnt lgkmcnt(0)
	v_mfma_f32_16x16x32_bf16 v[126:129], v[150:153], v[182:185], v[126:129]
	v_mfma_f32_16x16x32_bf16 v[122:125], v[158:161], v[182:185], v[122:125]
	v_mfma_f32_16x16x32_bf16 v[114:117], v[150:153], v[190:193], v[114:117]
	v_mfma_f32_16x16x32_bf16 v[106:109], v[158:161], v[190:193], v[106:109]
	v_mfma_f32_16x16x32_bf16 v[98:101], v[150:153], v[198:201], v[98:101]
	v_mfma_f32_16x16x32_bf16 v[90:93], v[158:161], v[198:201], v[90:93]
	v_mfma_f32_16x16x32_bf16 v[82:85], v[150:153], v[206:209], v[82:85]
	v_mfma_f32_16x16x32_bf16 v[74:77], v[158:161], v[206:209], v[74:77]
	v_mfma_f32_16x16x32_bf16 v[126:129], v[154:157], v[186:189], v[126:129]
	v_mfma_f32_16x16x32_bf16 v[122:125], v[162:165], v[186:189], v[122:125]
	v_mfma_f32_16x16x32_bf16 v[114:117], v[154:157], v[194:197], v[114:117]
	v_mfma_f32_16x16x32_bf16 v[106:109], v[162:165], v[194:197], v[106:109]
	v_mfma_f32_16x16x32_bf16 v[98:101], v[154:157], v[202:205], v[98:101]
	v_mfma_f32_16x16x32_bf16 v[90:93], v[162:165], v[202:205], v[90:93]
	v_mfma_f32_16x16x32_bf16 v[82:85], v[154:157], v[210:213], v[82:85]
	v_mfma_f32_16x16x32_bf16 v[74:77], v[162:165], v[210:213], v[74:77]
	v_mfma_f32_16x16x32_bf16 v[118:121], v[166:169], v[182:185], v[118:121]
	v_mfma_f32_16x16x32_bf16 v[110:113], v[174:177], v[182:185], v[110:113]
	v_mfma_f32_16x16x32_bf16 v[102:105], v[166:169], v[190:193], v[102:105]
	v_mfma_f32_16x16x32_bf16 v[94:97], v[174:177], v[190:193], v[94:97]
	v_mfma_f32_16x16x32_bf16 v[86:89], v[166:169], v[198:201], v[86:89]
	v_mfma_f32_16x16x32_bf16 v[78:81], v[174:177], v[198:201], v[78:81]
	v_mfma_f32_16x16x32_bf16 v[70:73], v[166:169], v[206:209], v[70:73]
	v_mfma_f32_16x16x32_bf16 v[66:69], v[174:177], v[206:209], v[66:69]
	v_mfma_f32_16x16x32_bf16 v[118:121], v[170:173], v[186:189], v[118:121]
	v_mfma_f32_16x16x32_bf16 v[110:113], v[178:181], v[186:189], v[110:113]
	v_mfma_f32_16x16x32_bf16 v[102:105], v[170:173], v[194:197], v[102:105]
	v_mfma_f32_16x16x32_bf16 v[94:97], v[178:181], v[194:197], v[94:97]
	v_mfma_f32_16x16x32_bf16 v[86:89], v[170:173], v[202:205], v[86:89]
	v_mfma_f32_16x16x32_bf16 v[78:81], v[178:181], v[202:205], v[78:81]
	v_mfma_f32_16x16x32_bf16 v[70:73], v[170:173], v[210:213], v[70:73]
	v_mfma_f32_16x16x32_bf16 v[66:69], v[178:181], v[210:213], v[66:69]
	s_barrier
	s_add_i32 s75, s66, s57
	v_lshl_add_u64 v[142:143], s[34:35], 0, v[130:131]
	s_mov_b32 m0, s75
	ds_read_b128 v[182:185], v149 offset:16384
	ds_read_b128 v[186:189], v149 offset:17408
	ds_read_b128 v[190:193], v149 offset:18432
	ds_read_b128 v[194:197], v149 offset:19456
	ds_read_b128 v[198:201], v149 offset:20480
	ds_read_b128 v[202:205], v149 offset:21504
	ds_read_b128 v[206:209], v149 offset:22528
	ds_read_b128 v[210:213], v149 offset:23552
	global_load_lds_dwordx4 v[142:143], off
	s_add_i32 m0, s75, 0x2000
	s_add_u32 s76, s34, 0xb0000
	v_lshl_add_u64 v[214:215], s[34:35], 0, v[132:133]
	s_addc_u32 s77, s35, 0
	s_add_i32 s75, s67, s57
	global_load_lds_dwordx4 v[214:215], off
	v_lshl_add_u64 v[216:217], s[76:77], 0, v[130:131]
	s_mov_b32 m0, s75
	v_lshl_add_u64 v[218:219], s[52:53], 0, v[132:133]
	global_load_lds_dwordx4 v[216:217], off
	v_lshl_add_u64 v[216:217], s[76:77], 0, v[132:133]
	s_add_i32 m0, s75, 0x2000
	s_nop 0
	global_load_lds_dwordx4 v[216:217], off
	v_lshl_add_u64 v[216:217], s[52:53], 0, v[130:131]
	s_mov_b32 m0, s58
	s_nop 0
	global_load_lds_dwordx4 v[216:217], off
	s_mov_b32 m0, s59
	s_nop 0
	global_load_lds_dwordx4 v[218:219], off
	s_waitcnt vmcnt(8)
	s_waitcnt lgkmcnt(0)
	s_barrier
; #define PG8_STAGE(bufoff, gbase, voff) do { _Pragma("unroll") for (int _i = 0; _i < 2; ++_i) \
;         __builtin_amdgcn_global_load_lds((const unsigned*)((const char*)(gbase) + (voff)[_i]), (LAS unsigned*)(lds + (bufoff) + ldsw + _i * 8192), 16, 0, 0); } while (0)
; #define PG8_LDA(dst, b, h) do { _Pragma("unroll") for (int m = 0; m < 4; ++m) _Pragma("unroll") for (int k = 0; k < 2; ++k) dst[m][k] = *(const LAS bf16x8*)(lds + PG8_SA(b, h) + aoff + m * 2048 + k * 1024); } while (0)
; #define PG8_LDB(dst, b, h) do { _Pragma("unroll") for (int n = 0; n < 2; ++n) _Pragma("unroll") for (int k = 0; k < 2; ++k) dst[n][k] = *(const LAS bf16x8*)(lds + PG8_SB(b, h) + boff + n * 2048 + k * 1024); } while (0)
; #define PG8_MMA(ai, bj, At, Bt) do { __builtin_amdgcn_s_setprio(1); _Pragma("unroll") for (int m = 0; m < 4; ++m) _Pragma("unroll") for (int n = 0; n < 2; ++n) _Pragma("unroll") for (int k = 0; k < 2; ++k) \
;         acc[ai][bj][m][n] = __builtin_amdgcn_mfma_f32_16x16x32_bf16(Bt[n][k], At[m][k], acc[ai][bj][m][n], 0, 0, 0); __builtin_amdgcn_s_setprio(0); } while (0)
; #define PG8_WAIT_V(n) asm volatile("s_waitcnt vmcnt(" #n ")" ::: "memory")
; #define PG8_WAIT_L(n) asm volatile("s_waitcnt lgkmcnt(" #n ")" ::: "memory")
; #define PG8_BAR __builtin_amdgcn_s_barrier()
; #define PG8_SCHED __builtin_amdgcn_sched_barrier(0)
; template <class Epi>
; __device__ __forceinline__ void gemm_phase(LAS unsigned char* lds, const Gemm g, const StaticOrder& S, const Epi& E) {
;     ...
;             PG8_WAIT_V(8); PG8_WAIT_L(0); PG8_BAR; PG8_MMA(1, 0, At, B0); PG8_MMA(1, 1, At, B1); PG8_BAR; PG8_SCHED;
;             PG8_LDB(B0, 1, 0); PG8_LDB(B1, 1, 1); PG8_SCHED; PG8_LDA(At, 1, 0); PG8_STAGE(PG8_SA(0, 1), a2 + hstep, voffA);
;             PG8_WAIT_V(8); PG8_WAIT_L(0); PG8_BAR; PG8_MMA(0, 0, At, B0); PG8_MMA(0, 1, At, B1); PG8_BAR; PG8_SCHED;
;             PG8_LDA(At, 1, 1); PG8_STAGE(PG8_SB(1, 0), b3, voffB); PG8_STAGE(PG8_SB(1, 1), b3 + hstep, voffB); PG8_STAGE(PG8_SA(1, 0), a3, voffA);
	s_waitcnt lgkmcnt(0)
	v_mfma_f32_16x16x32_bf16 v[62:65], v[150:153], v[182:185], v[62:65]
	v_mfma_f32_16x16x32_bf16 v[58:61], v[158:161], v[182:185], v[58:61]
	v_mfma_f32_16x16x32_bf16 v[50:53], v[150:153], v[190:193], v[50:53]
	v_mfma_f32_16x16x32_bf16 v[42:45], v[158:161], v[190:193], v[42:45]
	v_mfma_f32_16x16x32_bf16 v[34:37], v[150:153], v[198:201], v[34:37]
	v_mfma_f32_16x16x32_bf16 v[26:29], v[158:161], v[198:201], v[26:29]
	v_mfma_f32_16x16x32_bf16 v[18:21], v[150:153], v[206:209], v[18:21]
	v_mfma_f32_16x16x32_bf16 v[10:13], v[158:161], v[206:209], v[10:13]
	v_mfma_f32_16x16x32_bf16 v[62:65], v[154:157], v[186:189], v[62:65]
	v_mfma_f32_16x16x32_bf16 v[58:61], v[162:165], v[186:189], v[58:61]
	v_mfma_f32_16x16x32_bf16 v[50:53], v[154:157], v[194:197], v[50:53]
	v_mfma_f32_16x16x32_bf16 v[42:45], v[162:165], v[194:197], v[42:45]
	v_mfma_f32_16x16x32_bf16 v[34:37], v[154:157], v[202:205], v[34:37]
	v_mfma_f32_16x16x32_bf16 v[26:29], v[162:165], v[202:205], v[26:29]
	v_mfma_f32_16x16x32_bf16 v[18:21], v[154:157], v[210:213], v[18:21]
	v_mfma_f32_16x16x32_bf16 v[10:13], v[162:165], v[210:213], v[10:13]
	v_mfma_f32_16x16x32_bf16 v[54:57], v[166:169], v[182:185], v[54:57]
	v_mfma_f32_16x16x32_bf16 v[46:49], v[174:177], v[182:185], v[46:49]
	v_mfma_f32_16x16x32_bf16 v[38:41], v[166:169], v[190:193], v[38:41]
	v_mfma_f32_16x16x32_bf16 v[30:33], v[174:177], v[190:193], v[30:33]
	v_mfma_f32_16x16x32_bf16 v[22:25], v[166:169], v[198:201], v[22:25]
	v_mfma_f32_16x16x32_bf16 v[14:17], v[174:177], v[198:201], v[14:17]
	v_mfma_f32_16x16x32_bf16 v[6:9], v[166:169], v[206:209], v[6:9]
	v_mfma_f32_16x16x32_bf16 v[2:5], v[174:177], v[206:209], v[2:5]
	v_mfma_f32_16x16x32_bf16 v[54:57], v[170:173], v[186:189], v[54:57]
	v_mfma_f32_16x16x32_bf16 v[46:49], v[178:181], v[186:189], v[46:49]
	v_mfma_f32_16x16x32_bf16 v[38:41], v[170:173], v[194:197], v[38:41]
	v_mfma_f32_16x16x32_bf16 v[30:33], v[178:181], v[194:197], v[30:33]
	v_mfma_f32_16x16x32_bf16 v[22:25], v[170:173], v[202:205], v[22:25]
	v_mfma_f32_16x16x32_bf16 v[14:17], v[178:181], v[202:205], v[14:17]
	v_mfma_f32_16x16x32_bf16 v[6:9], v[170:173], v[210:213], v[6:9]
	v_mfma_f32_16x16x32_bf16 v[2:5], v[178:181], v[210:213], v[2:5]
	s_barrier
	s_add_i32 s75, 0, 0x18000
	s_add_i32 s76, 0, 0x1c000
	v_add_u32_e32 v162, s75, v145
	v_add_u32_e32 v178, s76, v145
	ds_read_b128 v[150:153], v162
	ds_read_b128 v[154:157], v162 offset:1024
	ds_read_b128 v[158:161], v162 offset:2048
	ds_read_b128 v[162:165], v162 offset:3072
	ds_read_b128 v[166:169], v178
	ds_read_b128 v[170:173], v178 offset:1024
	ds_read_b128 v[174:177], v178 offset:2048
	ds_read_b128 v[178:181], v178 offset:3072
	s_add_u32 s52, s52, 0xb0000
	s_addc_u32 s53, s53, 0
	s_mov_b32 m0, s60
	v_lshl_add_u64 v[220:221], s[52:53], 0, v[130:131]
	ds_read_b128 v[182:185], v149 offset:32768
	ds_read_b128 v[186:189], v149 offset:33792
	ds_read_b128 v[190:193], v149 offset:34816
	ds_read_b128 v[194:197], v149 offset:35840
	ds_read_b128 v[198:201], v149 offset:36864
	ds_read_b128 v[202:205], v149 offset:37888
	ds_read_b128 v[206:209], v149 offset:38912
	ds_read_b128 v[210:213], v149 offset:39936
	global_load_lds_dwordx4 v[220:221], off
	v_lshl_add_u64 v[220:221], s[52:53], 0, v[132:133]
	s_mov_b32 m0, s61
	s_nop 0
	global_load_lds_dwordx4 v[220:221], off
	s_waitcnt vmcnt(8)
	s_waitcnt lgkmcnt(0)
	s_barrier
	s_waitcnt lgkmcnt(0)
	v_mfma_f32_16x16x32_bf16 v[126:129], v[150:153], v[182:185], v[126:129]
	v_mfma_f32_16x16x32_bf16 v[122:125], v[158:161], v[182:185], v[122:125]
	v_mfma_f32_16x16x32_bf16 v[114:117], v[150:153], v[190:193], v[114:117]
	v_mfma_f32_16x16x32_bf16 v[106:109], v[158:161], v[190:193], v[106:109]
	v_mfma_f32_16x16x32_bf16 v[98:101], v[150:153], v[198:201], v[98:101]
	v_mfma_f32_16x16x32_bf16 v[90:93], v[158:161], v[198:201], v[90:93]
	v_mfma_f32_16x16x32_bf16 v[82:85], v[150:153], v[206:209], v[82:85]
	v_mfma_f32_16x16x32_bf16 v[74:77], v[158:161], v[206:209], v[74:77]
	v_mfma_f32_16x16x32_bf16 v[126:129], v[154:157], v[186:189], v[126:129]
	v_mfma_f32_16x16x32_bf16 v[122:125], v[162:165], v[186:189], v[122:125]
	v_mfma_f32_16x16x32_bf16 v[114:117], v[154:157], v[194:197], v[114:117]
	v_mfma_f32_16x16x32_bf16 v[106:109], v[162:165], v[194:197], v[106:109]
	v_mfma_f32_16x16x32_bf16 v[98:101], v[154:157], v[202:205], v[98:101]
	v_mfma_f32_16x16x32_bf16 v[90:93], v[162:165], v[202:205], v[90:93]
	v_mfma_f32_16x16x32_bf16 v[82:85], v[154:157], v[210:213], v[82:85]
	v_mfma_f32_16x16x32_bf16 v[74:77], v[162:165], v[210:213], v[74:77]
	v_mfma_f32_16x16x32_bf16 v[118:121], v[166:169], v[182:185], v[118:121]
	v_mfma_f32_16x16x32_bf16 v[110:113], v[174:177], v[182:185], v[110:113]
	v_mfma_f32_16x16x32_bf16 v[102:105], v[166:169], v[190:193], v[102:105]
	v_mfma_f32_16x16x32_bf16 v[94:97], v[174:177], v[190:193], v[94:97]
	v_mfma_f32_16x16x32_bf16 v[86:89], v[166:169], v[198:201], v[86:89]
	v_mfma_f32_16x16x32_bf16 v[78:81], v[174:177], v[198:201], v[78:81]
	v_mfma_f32_16x16x32_bf16 v[70:73], v[166:169], v[206:209], v[70:73]
	v_mfma_f32_16x16x32_bf16 v[66:69], v[174:177], v[206:209], v[66:69]
	v_mfma_f32_16x16x32_bf16 v[118:121], v[170:173], v[186:189], v[118:121]
	v_mfma_f32_16x16x32_bf16 v[110:113], v[178:181], v[186:189], v[110:113]
	v_mfma_f32_16x16x32_bf16 v[102:105], v[170:173], v[194:197], v[102:105]
	v_mfma_f32_16x16x32_bf16 v[94:97], v[178:181], v[194:197], v[94:97]
	v_mfma_f32_16x16x32_bf16 v[86:89], v[170:173], v[202:205], v[86:89]
	v_mfma_f32_16x16x32_bf16 v[78:81], v[178:181], v[202:205], v[78:81]
	v_mfma_f32_16x16x32_bf16 v[70:73], v[170:173], v[210:213], v[70:73]
	v_mfma_f32_16x16x32_bf16 v[66:69], v[178:181], v[210:213], v[66:69]
	s_barrier
; #define PG8_STAGE(bufoff, gbase, voff) do { _Pragma("unroll") for (int _i = 0; _i < 2; ++_i) \
;         __builtin_amdgcn_global_load_lds((const unsigned*)((const char*)(gbase) + (voff)[_i]), (LAS unsigned*)(lds + (bufoff) + ldsw + _i * 8192), 16, 0, 0); } while (0)
; #define PG8_LDA(dst, b, h) do { _Pragma("unroll") for (int m = 0; m < 4; ++m) _Pragma("unroll") for (int k = 0; k < 2; ++k) dst[m][k] = *(const LAS bf16x8*)(lds + PG8_SA(b, h) + aoff + m * 2048 + k * 1024); } while (0)
; #define PG8_MMA(ai, bj, At, Bt) do { __builtin_amdgcn_s_setprio(1); _Pragma("unroll") for (int m = 0; m < 4; ++m) _Pragma("unroll") for (int n = 0; n < 2; ++n) _Pragma("unroll") for (int k = 0; k < 2; ++k) \
;         acc[ai][bj][m][n] = __builtin_amdgcn_mfma_f32_16x16x32_bf16(Bt[n][k], At[m][k], acc[ai][bj][m][n], 0, 0, 0); __builtin_amdgcn_s_setprio(0); } while (0)
; #define PG8_WAIT_V(n) asm volatile("s_waitcnt vmcnt(" #n ")" ::: "memory")
; #define PG8_WAIT_L(n) asm volatile("s_waitcnt lgkmcnt(" #n ")" ::: "memory")
; #define PG8_BAR __builtin_amdgcn_s_barrier()
; #define PG8_SCHED __builtin_amdgcn_sched_barrier(0)
; template <class Epi>
; __device__ __forceinline__ void gemm_phase(LAS unsigned char* lds, const Gemm g, const StaticOrder& S, const Epi& E) {
;     ...
;             PG8_LDA(At, 1, 1); PG8_STAGE(PG8_SB(1, 0), b3, voffB); PG8_STAGE(PG8_SB(1, 1), b3 + hstep, voffB); PG8_STAGE(PG8_SA(1, 0), a3, voffA);
;             PG8_WAIT_V(8); PG8_WAIT_L(0); PG8_BAR; PG8_MMA(1, 0, At, B0); PG8_MMA(1, 1, At, B1); PG8_BAR; PG8_SCHED;
;         }
;         if (wr == 0) PG8_BAR;
	s_add_i32 s52, s75, s57
	v_lshl_add_u64 v[142:143], v[142:143], 0, s[6:7]
	s_mov_b32 m0, s52
	ds_read_b128 v[182:185], v149 offset:49152
	ds_read_b128 v[186:189], v149 offset:50176
	ds_read_b128 v[190:193], v149 offset:51200
	ds_read_b128 v[194:197], v149 offset:52224
	ds_read_b128 v[198:201], v149 offset:53248
	ds_read_b128 v[202:205], v149 offset:54272
	ds_read_b128 v[206:209], v149 offset:55296
	ds_read_b128 v[210:213], v149 offset:56320
	global_load_lds_dwordx4 v[142:143], off
	s_add_i32 m0, s52, 0x2000
	s_add_u32 s34, s34, 0xb0080
	v_lshl_add_u64 v[142:143], v[214:215], 0, s[6:7]
	s_addc_u32 s35, s35, 0
	s_add_i32 s52, s76, s57
	global_load_lds_dwordx4 v[142:143], off
	v_lshl_add_u64 v[142:143], s[34:35], 0, v[130:131]
	s_mov_b32 m0, s52
	s_nop 0
	global_load_lds_dwordx4 v[142:143], off
	v_lshl_add_u64 v[142:143], s[34:35], 0, v[132:133]
	s_add_i32 m0, s52, 0x2000
	s_nop 0
	global_load_lds_dwordx4 v[142:143], off
	v_lshl_add_u64 v[142:143], v[216:217], 0, s[6:7]
	s_mov_b32 m0, s63
	s_nop 0
	global_load_lds_dwordx4 v[142:143], off
	v_lshl_add_u64 v[142:143], v[218:219], 0, s[6:7]
	s_mov_b32 m0, s64
	s_nop 0
	global_load_lds_dwordx4 v[142:143], off
	s_waitcnt vmcnt(8)
	s_waitcnt lgkmcnt(0)
	s_barrier
	s_waitcnt lgkmcnt(0)
	v_mfma_f32_16x16x32_bf16 v[62:65], v[150:153], v[182:185], v[62:65]
	v_mfma_f32_16x16x32_bf16 v[58:61], v[158:161], v[182:185], v[58:61]
	v_mfma_f32_16x16x32_bf16 v[50:53], v[150:153], v[190:193], v[50:53]
	v_mfma_f32_16x16x32_bf16 v[42:45], v[158:161], v[190:193], v[42:45]
	v_mfma_f32_16x16x32_bf16 v[34:37], v[150:153], v[198:201], v[34:37]
	v_mfma_f32_16x16x32_bf16 v[26:29], v[158:161], v[198:201], v[26:29]
	v_mfma_f32_16x16x32_bf16 v[18:21], v[150:153], v[206:209], v[18:21]
	v_mfma_f32_16x16x32_bf16 v[10:13], v[158:161], v[206:209], v[10:13]
	v_mfma_f32_16x16x32_bf16 v[62:65], v[154:157], v[186:189], v[62:65]
	v_mfma_f32_16x16x32_bf16 v[58:61], v[162:165], v[186:189], v[58:61]
	v_mfma_f32_16x16x32_bf16 v[50:53], v[154:157], v[194:197], v[50:53]
	v_mfma_f32_16x16x32_bf16 v[42:45], v[162:165], v[194:197], v[42:45]
	v_mfma_f32_16x16x32_bf16 v[34:37], v[154:157], v[202:205], v[34:37]
	v_mfma_f32_16x16x32_bf16 v[26:29], v[162:165], v[202:205], v[26:29]
	v_mfma_f32_16x16x32_bf16 v[18:21], v[154:157], v[210:213], v[18:21]
	v_mfma_f32_16x16x32_bf16 v[10:13], v[162:165], v[210:213], v[10:13]
	v_mfma_f32_16x16x32_bf16 v[54:57], v[166:169], v[182:185], v[54:57]
	v_mfma_f32_16x16x32_bf16 v[46:49], v[174:177], v[182:185], v[46:49]
	v_mfma_f32_16x16x32_bf16 v[38:41], v[166:169], v[190:193], v[38:41]
	v_mfma_f32_16x16x32_bf16 v[30:33], v[174:177], v[190:193], v[30:33]
	v_mfma_f32_16x16x32_bf16 v[22:25], v[166:169], v[198:201], v[22:25]
	v_mfma_f32_16x16x32_bf16 v[14:17], v[174:177], v[198:201], v[14:17]
	v_mfma_f32_16x16x32_bf16 v[6:9], v[166:169], v[206:209], v[6:9]
	v_mfma_f32_16x16x32_bf16 v[2:5], v[174:177], v[206:209], v[2:5]
	v_mfma_f32_16x16x32_bf16 v[54:57], v[170:173], v[186:189], v[54:57]
	v_mfma_f32_16x16x32_bf16 v[46:49], v[178:181], v[186:189], v[46:49]
	v_mfma_f32_16x16x32_bf16 v[38:41], v[170:173], v[194:197], v[38:41]
	v_mfma_f32_16x16x32_bf16 v[30:33], v[178:181], v[194:197], v[30:33]
	v_mfma_f32_16x16x32_bf16 v[22:25], v[170:173], v[202:205], v[22:25]
	v_mfma_f32_16x16x32_bf16 v[14:17], v[178:181], v[202:205], v[14:17]
	v_mfma_f32_16x16x32_bf16 v[6:9], v[170:173], v[210:213], v[6:9]
	v_mfma_f32_16x16x32_bf16 v[2:5], v[178:181], v[210:213], v[2:5]
	s_barrier
	s_add_i32 s74, s74, 2
	s_add_u32 s30, s30, 0x100
	s_addc_u32 s31, s31, 0
	s_add_u32 s72, s72, 0x100
	s_addc_u32 s73, s73, 0
	s_cmp_gt_u32 s74, 41
	s_cbranch_scc0 .LBB0_164
	s_and_b64 vcc, exec, s[8:9]
	s_cbranch_vccz .LBB0_167
	s_barrier

; #define SEAM(k) do { if ((k) + 1 < hi) { if ((k) == 0) { __syncthreads(); cg::this_grid().sync(); } \
;         else { if (!xposted) { if (threadIdx.x == 0) { xst[0] = 0u; xst[1] = 0u; } __syncthreads(); xbar = xcd_barrier_post((unsigned*)(ws + 65536), xst); xposted = true; } xcd_barrier(xbar); } } } while (0)
; __global__ void __launch_bounds__(512) fwd_kernel(Args a) {
;     ...
;     if (IN(2)) { pg8::Gemm g{(const bf16_t*)(ws + WS_BIG), (const bf16_t*)(ws + WS_WD1), M, D, FF}; pg8::StaticOrder S; S.init(M, D, G, bx);
;                  pg8::EpiResid E{a.in[0], hbuf, ALPHA, 0.5f}; pg8::gemm_phase(lds, g, S, E); SEAM(2); }
.LBB0_171:
	s_setprio 0
	v_readlane_b32 s0, v238, 21
	v_readlane_b32 s1, v238, 22
	s_cmp_lt_i32 s1, 4
	s_cbranch_scc1 .LBB0_228
	v_readlane_b32 s0, v238, 23
	v_readlane_b32 s1, v238, 24
	s_xor_b64 s[0:1], s[0:1], -1
	s_andn2_b64 vcc, exec, s[0:1]
	v_cmp_eq_u32_e64 s[0:1], 0, v1
	s_cbranch_vccnz .LBB0_179
	s_and_saveexec_b64 s[2:3], s[0:1]
	s_cbranch_execz .LBB0_175
	s_add_i32 s4, 0, 0x23ff0
	v_mov_b32_e32 v2, 0
	v_mov_b32_e32 v3, s4
	s_add_i32 s4, 0, 0x23ff4
	ds_write_b32 v3, v2
	v_mov_b32_e32 v3, s4
	ds_write_b32 v3, v2

; #define PG8_STAGE(bufoff, gbase, voff) do { _Pragma("unroll") for (int _i = 0; _i < 2; ++_i) \
;         __builtin_amdgcn_global_load_lds((const unsigned*)((const char*)(gbase) + (voff)[_i]), (LAS unsigned*)(lds + (bufoff) + ldsw + _i * 8192), 16, 0, 0); } while (0)
; #define PG8_WAIT_V(n) asm volatile("s_waitcnt vmcnt(" #n ")" ::: "memory")
; #define PG8_BAR __builtin_amdgcn_s_barrier()
; template <class Epi>
; __device__ __forceinline__ void gemm_phase(LAS unsigned char* lds, const Gemm g, const StaticOrder& S, const Epi& E) {
;     const int tid = threadIdx.x, wid = __builtin_amdgcn_readfirstlane(tid >> 6), lane = tid & 63, wr = wid >> 2, wc = wid & 3, fr = lane & 15, fq = lane >> 4;
;     const int K = g.K, nt = K / BK;
;     unsigned voffA[2], voffB[2];
; #pragma unroll
;     for (int i = 0; i < 2; ++i) { int R, C; stage_rc(tid * 16 + i * 8192, R, C); const int Rb = Epi::PERM ? ((R & ~31) + perm32(R & 31)) : R;
;         voffA[i] = (unsigned)(R * K + C) * 2u; voffB[i] = (unsigned)(Rb * K + C) * 2u; }
;     const size_t kstep = (size_t)(BK * 2);
;     const size_t hstep = (size_t)HALF * K * 2;
;     const size_t tstep = 2 * hstep;
;     const unsigned ldsw = (unsigned)wid * 1024u;
;     const int aoff = lds_byte(wr * 64 + fr, fq * 8), boff = lds_byte(wc * 32 + fr, fq * 8);
;     ...
;     Unit cur, nxt; int ui = 0;
;     if (!S.next(0, cur)) return;
;     f32x4 acc[2][2][4][2];
; #pragma unroll
;     for (int a = 0; a < 2; ++a)
; #pragma unroll
;         for (int b = 0; b < 2; ++b)
; #pragma unroll
;             for (int m = 0; m < 4; ++m)
; #pragma unroll
;                 for (int n = 0; n < 2; ++n) acc[a][b][m][n] = (f32x4){0.f, 0.f, 0.f, 0.f};
;     bf16x8 At[4][2], B0[2][2], B1[2][2];
;     const char* cA = (const char*)g.A + (size_t)cur.pm * tstep; const char* cB = (const char*)g.Bt + (size_t)cur.pn * tstep;
;     PG8_STAGE(PG8_SB(0, 0), cB, voffB); PG8_STAGE(PG8_SB(0, 1), cB + hstep, voffB); PG8_STAGE(PG8_SA(0, 0), cA, voffA); PG8_STAGE(PG8_SA(0, 1), cA + hstep, voffA);
;     if (wr == 1) PG8_BAR;
;     PG8_WAIT_V(2); PG8_BAR;
;     PG8_STAGE(PG8_SB(1, 0), cB + kstep, voffB); PG8_STAGE(PG8_SA(1, 0), cA + kstep, voffA); PG8_STAGE(PG8_SB(1, 1), cB + hstep + kstep, voffB);
;     PG8_WAIT_V(6); PG8_BAR;
.LBB0_304:
	s_nop 0
	v_readlane_b32 s2, v238, 21
	v_readlane_b32 s3, v238, 22
	s_cmp_lt_i32 s2, 5
	s_cselect_b64 s[0:1], -1, 0
	s_cmp_gt_i32 s3, 4
	s_cselect_b64 s[2:3], -1, 0
	s_and_b64 s[0:1], s[0:1], s[2:3]
	s_andn2_b64 vcc, exec, s[0:1]
	s_cbranch_vccnz .LBB0_378
	v_and_b32_e32 v1, 0x3ff, v0
	s_cmpk_gt_i32 s92, 0x6ff
	v_readfirstlane_b32 s1, v1
	s_cbranch_scc1 .LBB0_321
	v_lshrrev_b32_e32 v2, 5, v1
	v_lshrrev_b32_e32 v4, 1, v1
	v_and_b32_e32 v2, 4, v2
	v_bfe_u32 v3, v1, 2, 2
	v_and_b32_e32 v13, 24, v4
	v_or3_b32 v2, v2, v3, v13
	v_lshlrev_b32_e32 v3, 4, v1
	v_add_u32_e32 v10, 0x2000, v3
	v_lshrrev_b32_e32 v4, 7, v10
	s_movk_i32 s0, 0xe0
	v_and_b32_e32 v6, 32, v1
	s_add_u32 s30, s86, 0x3000000
	v_and_or_b32 v5, v4, s0, v2
	v_bitop3_b32 v11, v3, v6, 48 bitop3:0x6c
	v_and_b32_e32 v12, 64, v1
	v_bfe_u32 v14, v1, 2, 4
	s_movk_i32 s0, 0xf0
	s_addc_u32 s31, s87, 0
	v_or_b32_e32 v3, v11, v12
	v_and_or_b32 v4, v4, s0, v14
	s_add_u32 s33, s86, 0x1200000
	v_lshl_or_b32 v132, v4, 11, v3
	v_lshrrev_b32_e32 v4, 3, v1
	s_movk_i32 s0, 0x60
	s_addc_u32 s34, s87, 0
	v_and_or_b32 v2, v4, s0, v2
	s_movk_i32 s0, 0x70
	s_waitcnt lgkmcnt(0)
	s_ashr_i32 s36, s92, 31
	v_lshl_or_b32 v134, v2, 11, v3
	v_and_or_b32 v2, v4, s0, v14
	s_lshr_b32 s0, s36, 29
	s_add_i32 s0, s92, s0
	s_lshr_b32 s6, s1, 6
	s_ashr_i32 s2, s0, 3
	s_and_b32 s0, s0, -8
	s_lshr_b32 s8, s1, 8
	s_lshl_b32 s35, s6, 10
	s_sub_i32 s0, s92, s0
	s_cmp_lt_i32 s0, 0
	s_movk_i32 s37, 0xe1
	s_cselect_b32 s3, s37, 0xe0
	s_mul_i32 s0, s0, s3
	s_add_i32 s0, s0, s2
	s_mul_hi_i32 s2, s0, 0x92492493
	s_add_i32 s2, s2, s0
	s_lshr_b32 s3, s2, 31
	s_ashr_i32 s2, s2, 6
	s_add_i32 s2, s2, s3
	s_lshl_b32 s3, s2, 3
	s_mulk_i32 s2, 0x70
	s_sub_i32 s2, s0, s2
	s_bfe_i32 s0, s2, 0x80000
	s_bfe_u32 s0, s0, 0x3000c
	s_add_i32 s4, s2, s0
	s_bfe_i32 s0, s4, 0x80000
	s_and_b32 s4, s4, 0xf8
	s_sub_i32 s2, s2, s4
	s_sext_i32_i16 s0, s0
	s_sext_i32_i8 s2, s2
	s_lshr_b32 s0, s0, 3
	s_add_i32 s10, s3, s2
	s_ashr_i32 s11, s10, 31
	s_bfe_i64 s[4:5], s[0:1], 0x100000
	s_lshl_b64 s[2:3], s[10:11], 19
	s_lshl_b64 s[4:5], s[4:5], 19
	s_add_u32 s22, s33, s4
	s_addc_u32 s23, s34, s5
	s_add_i32 s11, s35, 0
	s_add_i32 m0, s11, 0x10000
	v_lshl_or_b32 v130, v5, 11, v3
	global_load_lds_dwordx4 v134, s[22:23]
	s_add_i32 m0, s11, 0x12000
	s_add_u32 s4, s22, 0x40000
	global_load_lds_dwordx4 v130, s[22:23]
	s_addc_u32 s5, s23, 0
	s_add_i32 m0, s11, 0x14000
	v_lshl_or_b32 v136, v2, 11, v3
	global_load_lds_dwordx4 v134, s[4:5]
	s_add_i32 m0, s11, 0x16000
	s_add_u32 s20, s30, s2
	s_addc_u32 s21, s31, s3
	s_add_i32 s38, s11, 0x2000
	global_load_lds_dwordx4 v130, s[4:5]
	s_mov_b32 m0, s11
	s_add_u32 s2, s20, 0x40000
	global_load_lds_dwordx4 v136, s[20:21]
	s_mov_b32 m0, s38
	s_addc_u32 s3, s21, 0
	s_add_i32 s39, s11, 0x4000
	global_load_lds_dwordx4 v132, s[20:21]
	s_mov_b32 m0, s39
	s_add_i32 s52, s11, 0x6000
	global_load_lds_dwordx4 v136, s[2:3]
	s_mov_b32 m0, s52
	v_mov_b32_e32 v135, 0
	global_load_lds_dwordx4 v132, s[2:3]
	v_mov_b32_e32 v131, v135
	v_mov_b32_e32 v137, v135
	v_mov_b32_e32 v133, v135
	s_cmp_eq_u32 s8, 1
	s_mov_b32 s53, 0
	v_lshl_add_u64 v[8:9], s[22:23], 0, v[134:135]
	v_lshl_add_u64 v[6:7], s[22:23], 0, v[130:131]
	v_lshl_add_u64 v[2:3], s[20:21], 0, v[136:137]
	s_cselect_b64 s[2:3], -1, 0
	s_cmp_lg_u32 s8, 1
	v_lshl_add_u64 v[4:5], s[20:21], 0, v[132:133]
	s_cbranch_scc1 .LBB0_308
	s_barrier
	s_setprio 1

; #define PG8_STAGE(bufoff, gbase, voff) do { _Pragma("unroll") for (int _i = 0; _i < 2; ++_i) \
;         __builtin_amdgcn_global_load_lds((const unsigned*)((const char*)(gbase) + (voff)[_i]), (LAS unsigned*)(lds + (bufoff) + ldsw + _i * 8192), 16, 0, 0); } while (0)
; #define PG8_LDA(dst, b, h) do { _Pragma("unroll") for (int m = 0; m < 4; ++m) _Pragma("unroll") for (int k = 0; k < 2; ++k) dst[m][k] = *(const LAS bf16x8*)(lds + PG8_SA(b, h) + aoff + m * 2048 + k * 1024); } while (0)
; #define PG8_LDB(dst, b, h) do { _Pragma("unroll") for (int n = 0; n < 2; ++n) _Pragma("unroll") for (int k = 0; k < 2; ++k) dst[n][k] = *(const LAS bf16x8*)(lds + PG8_SB(b, h) + boff + n * 2048 + k * 1024); } while (0)
; #define PG8_MMA(ai, bj, At, Bt) do { __builtin_amdgcn_s_setprio(1); _Pragma("unroll") for (int m = 0; m < 4; ++m) _Pragma("unroll") for (int n = 0; n < 2; ++n) _Pragma("unroll") for (int k = 0; k < 2; ++k) \
;         acc[ai][bj][m][n] = __builtin_amdgcn_mfma_f32_16x16x32_bf16(Bt[n][k], At[m][k], acc[ai][bj][m][n], 0, 0, 0); __builtin_amdgcn_s_setprio(0); } while (0)
; #define PG8_WAIT_V(n) asm volatile("s_waitcnt vmcnt(" #n ")" ::: "memory")
; #define PG8_WAIT_L(n) asm volatile("s_waitcnt lgkmcnt(" #n ")" ::: "memory")
; #define PG8_BAR __builtin_amdgcn_s_barrier()
; #define PG8_SCHED __builtin_amdgcn_sched_barrier(0)
; template <class Epi>
; __device__ __forceinline__ void gemm_phase(LAS unsigned char* lds, const Gemm g, const StaticOrder& S, const Epi& E) {
;     ...
;         for (int t = 0; t < nt; t += 2) {
;             const bool last = (t == nt - 2);
;             const char* a1 = cA + (size_t)(t + 1) * kstep;
;             const char* a2 = last ? nA : cA + (size_t)(t + 2) * kstep; const char* b2 = last ? nB : cB + (size_t)(t + 2) * kstep;
;             const char* a3 = a2 + kstep; const char* b3 = b2 + kstep;
;             PG8_LDB(B0, 0, 0); PG8_LDB(B1, 0, 1); PG8_SCHED; PG8_LDA(At, 0, 0); PG8_STAGE(PG8_SA(1, 1), a1 + hstep, voffA);
;             PG8_WAIT_V(8); PG8_WAIT_L(0); PG8_BAR; PG8_MMA(0, 0, At, B0); PG8_MMA(0, 1, At, B1); PG8_BAR; PG8_SCHED;
;             PG8_LDA(At, 0, 1); PG8_STAGE(PG8_SB(0, 0), b2, voffB); PG8_STAGE(PG8_SB(0, 1), b2 + hstep, voffB); PG8_STAGE(PG8_SA(0, 0), a2, voffA);
.LBB0_314:
	ds_read_b128 v[152:155], v149
	ds_read_b128 v[156:159], v149 offset:1024
	ds_read_b128 v[160:163], v149 offset:2048
	ds_read_b128 v[164:167], v149 offset:3072
	ds_read_b128 v[168:171], v150
	ds_read_b128 v[172:175], v150 offset:1024
	ds_read_b128 v[176:179], v150 offset:2048
	ds_read_b128 v[180:183], v150 offset:3072
	s_add_u32 s22, s20, 0xfffc0080
	s_addc_u32 s23, s21, -1
	s_cmp_eq_u32 s65, 12
	s_cselect_b32 s29, s15, s23
	s_cselect_b32 s28, s61, s22
	s_cselect_b32 s23, s13, s64
	s_cselect_b32 s22, s62, s63
	v_lshl_add_u64 v[216:217], s[20:21], 0, v[138:139]
	s_add_i32 m0, s11, 0xc000
	ds_read_b128 v[184:187], v151
	ds_read_b128 v[188:191], v151 offset:1024
	ds_read_b128 v[192:195], v151 offset:2048
	ds_read_b128 v[196:199], v151 offset:3072
	ds_read_b128 v[200:203], v151 offset:4096
	ds_read_b128 v[204:207], v151 offset:5120
	ds_read_b128 v[208:211], v151 offset:6144
	ds_read_b128 v[212:215], v151 offset:7168
	global_load_lds_dwordx4 v[216:217], off
	v_lshl_add_u64 v[216:217], s[20:21], 0, v[140:141]
	s_add_i32 m0, s11, 0xe000
	s_nop 0
	global_load_lds_dwordx4 v[216:217], off
	s_waitcnt vmcnt(8)
	s_waitcnt lgkmcnt(0)
	s_barrier
	s_waitcnt lgkmcnt(0)
	v_mfma_f32_16x16x32_bf16 v[126:129], v[152:155], v[184:187], v[126:129]
	v_mfma_f32_16x16x32_bf16 v[122:125], v[160:163], v[184:187], v[122:125]
	v_mfma_f32_16x16x32_bf16 v[118:121], v[152:155], v[192:195], v[118:121]
	v_mfma_f32_16x16x32_bf16 v[114:117], v[160:163], v[192:195], v[114:117]
	v_mfma_f32_16x16x32_bf16 v[102:105], v[152:155], v[200:203], v[102:105]
	v_mfma_f32_16x16x32_bf16 v[98:101], v[160:163], v[200:203], v[98:101]
	v_mfma_f32_16x16x32_bf16 v[86:89], v[152:155], v[208:211], v[86:89]
	v_mfma_f32_16x16x32_bf16 v[82:85], v[160:163], v[208:211], v[82:85]
	v_mfma_f32_16x16x32_bf16 v[126:129], v[156:159], v[188:191], v[126:129]
	v_mfma_f32_16x16x32_bf16 v[122:125], v[164:167], v[188:191], v[122:125]
	v_mfma_f32_16x16x32_bf16 v[118:121], v[156:159], v[196:199], v[118:121]
	v_mfma_f32_16x16x32_bf16 v[114:117], v[164:167], v[196:199], v[114:117]
	v_mfma_f32_16x16x32_bf16 v[102:105], v[156:159], v[204:207], v[102:105]
	v_mfma_f32_16x16x32_bf16 v[98:101], v[164:167], v[204:207], v[98:101]
	v_mfma_f32_16x16x32_bf16 v[86:89], v[156:159], v[212:215], v[86:89]
	v_mfma_f32_16x16x32_bf16 v[82:85], v[164:167], v[212:215], v[82:85]
	v_mfma_f32_16x16x32_bf16 v[110:113], v[168:171], v[184:187], v[110:113]
	v_mfma_f32_16x16x32_bf16 v[106:109], v[176:179], v[184:187], v[106:109]
	v_mfma_f32_16x16x32_bf16 v[94:97], v[168:171], v[192:195], v[94:97]
	v_mfma_f32_16x16x32_bf16 v[90:93], v[176:179], v[192:195], v[90:93]
	v_mfma_f32_16x16x32_bf16 v[78:81], v[168:171], v[200:203], v[78:81]
	v_mfma_f32_16x16x32_bf16 v[74:77], v[176:179], v[200:203], v[74:77]
	v_mfma_f32_16x16x32_bf16 v[70:73], v[168:171], v[208:211], v[70:73]
	v_mfma_f32_16x16x32_bf16 v[66:69], v[176:179], v[208:211], v[66:69]
	v_mfma_f32_16x16x32_bf16 v[110:113], v[172:175], v[188:191], v[110:113]
	v_mfma_f32_16x16x32_bf16 v[106:109], v[180:183], v[188:191], v[106:109]
	v_mfma_f32_16x16x32_bf16 v[94:97], v[172:175], v[196:199], v[94:97]
	v_mfma_f32_16x16x32_bf16 v[90:93], v[180:183], v[196:199], v[90:93]
	v_mfma_f32_16x16x32_bf16 v[78:81], v[172:175], v[204:207], v[78:81]
	v_mfma_f32_16x16x32_bf16 v[74:77], v[180:183], v[204:207], v[74:77]
	v_mfma_f32_16x16x32_bf16 v[70:73], v[172:175], v[212:215], v[70:73]
	v_mfma_f32_16x16x32_bf16 v[66:69], v[180:183], v[212:215], v[66:69]
	s_barrier
	s_add_i32 s66, s57, s35
	v_lshl_add_u64 v[216:217], s[22:23], 0, v[134:135]
	s_mov_b32 m0, s66
	ds_read_b128 v[184:187], v151 offset:16384
	ds_read_b128 v[188:191], v151 offset:17408
	ds_read_b128 v[192:195], v151 offset:18432
	ds_read_b128 v[196:199], v151 offset:19456
	ds_read_b128 v[200:203], v151 offset:20480
	ds_read_b128 v[204:207], v151 offset:21504
	ds_read_b128 v[208:211], v151 offset:22528
	ds_read_b128 v[212:215], v151 offset:23552
	global_load_lds_dwordx4 v[216:217], off
	s_add_i32 m0, s66, 0x2000
	s_add_u32 s66, s22, 0x40000
	v_lshl_add_u64 v[218:219], s[22:23], 0, v[130:131]
	s_addc_u32 s67, s23, 0
	s_add_i32 s68, s58, s35
	global_load_lds_dwordx4 v[218:219], off
	v_lshl_add_u64 v[220:221], s[66:67], 0, v[134:135]
	s_mov_b32 m0, s68
	v_lshl_add_u64 v[222:223], s[28:29], 0, v[132:133]
	global_load_lds_dwordx4 v[220:221], off
	v_lshl_add_u64 v[220:221], s[66:67], 0, v[130:131]
	s_add_i32 m0, s68, 0x2000
	s_nop 0
	global_load_lds_dwordx4 v[220:221], off
	v_lshl_add_u64 v[220:221], s[28:29], 0, v[136:137]
	s_mov_b32 m0, s11
	s_nop 0
	global_load_lds_dwordx4 v[220:221], off
	s_mov_b32 m0, s38
	s_nop 0
	global_load_lds_dwordx4 v[222:223], off
	s_waitcnt vmcnt(8)
	s_waitcnt lgkmcnt(0)
	s_barrier
; #define PG8_STAGE(bufoff, gbase, voff) do { _Pragma("unroll") for (int _i = 0; _i < 2; ++_i) \
;         __builtin_amdgcn_global_load_lds((const unsigned*)((const char*)(gbase) + (voff)[_i]), (LAS unsigned*)(lds + (bufoff) + ldsw + _i * 8192), 16, 0, 0); } while (0)
; #define PG8_LDA(dst, b, h) do { _Pragma("unroll") for (int m = 0; m < 4; ++m) _Pragma("unroll") for (int k = 0; k < 2; ++k) dst[m][k] = *(const LAS bf16x8*)(lds + PG8_SA(b, h) + aoff + m * 2048 + k * 1024); } while (0)
; #define PG8_LDB(dst, b, h) do { _Pragma("unroll") for (int n = 0; n < 2; ++n) _Pragma("unroll") for (int k = 0; k < 2; ++k) dst[n][k] = *(const LAS bf16x8*)(lds + PG8_SB(b, h) + boff + n * 2048 + k * 1024); } while (0)
; #define PG8_MMA(ai, bj, At, Bt) do { __builtin_amdgcn_s_setprio(1); _Pragma("unroll") for (int m = 0; m < 4; ++m) _Pragma("unroll") for (int n = 0; n < 2; ++n) _Pragma("unroll") for (int k = 0; k < 2; ++k) \
;         acc[ai][bj][m][n] = __builtin_amdgcn_mfma_f32_16x16x32_bf16(Bt[n][k], At[m][k], acc[ai][bj][m][n], 0, 0, 0); __builtin_amdgcn_s_setprio(0); } while (0)
; #define PG8_WAIT_V(n) asm volatile("s_waitcnt vmcnt(" #n ")" ::: "memory")
; #define PG8_WAIT_L(n) asm volatile("s_waitcnt lgkmcnt(" #n ")" ::: "memory")
; #define PG8_BAR __builtin_amdgcn_s_barrier()
; #define PG8_SCHED __builtin_amdgcn_sched_barrier(0)
; template <class Epi>
; __device__ __forceinline__ void gemm_phase(LAS unsigned char* lds, const Gemm g, const StaticOrder& S, const Epi& E) {
;     ...
;             PG8_WAIT_V(8); PG8_WAIT_L(0); PG8_BAR; PG8_MMA(1, 0, At, B0); PG8_MMA(1, 1, At, B1); PG8_BAR; PG8_SCHED;
;             PG8_LDB(B0, 1, 0); PG8_LDB(B1, 1, 1); PG8_SCHED; PG8_LDA(At, 1, 0); PG8_STAGE(PG8_SA(0, 1), a2 + hstep, voffA);
;             PG8_WAIT_V(8); PG8_WAIT_L(0); PG8_BAR; PG8_MMA(0, 0, At, B0); PG8_MMA(0, 1, At, B1); PG8_BAR; PG8_SCHED;
;             PG8_LDA(At, 1, 1); PG8_STAGE(PG8_SB(1, 0), b3, voffB); PG8_STAGE(PG8_SB(1, 1), b3 + hstep, voffB); PG8_STAGE(PG8_SA(1, 0), a3, voffA);
	s_waitcnt lgkmcnt(0)
	v_mfma_f32_16x16x32_bf16 v[62:65], v[152:155], v[184:187], v[62:65]
	v_mfma_f32_16x16x32_bf16 v[58:61], v[160:163], v[184:187], v[58:61]
	v_mfma_f32_16x16x32_bf16 v[54:57], v[152:155], v[192:195], v[54:57]
	v_mfma_f32_16x16x32_bf16 v[50:53], v[160:163], v[192:195], v[50:53]
	v_mfma_f32_16x16x32_bf16 v[38:41], v[152:155], v[200:203], v[38:41]
	v_mfma_f32_16x16x32_bf16 v[34:37], v[160:163], v[200:203], v[34:37]
	v_mfma_f32_16x16x32_bf16 v[22:25], v[152:155], v[208:211], v[22:25]
	v_mfma_f32_16x16x32_bf16 v[18:21], v[160:163], v[208:211], v[18:21]
	v_mfma_f32_16x16x32_bf16 v[62:65], v[156:159], v[188:191], v[62:65]
	v_mfma_f32_16x16x32_bf16 v[58:61], v[164:167], v[188:191], v[58:61]
	v_mfma_f32_16x16x32_bf16 v[54:57], v[156:159], v[196:199], v[54:57]
	v_mfma_f32_16x16x32_bf16 v[50:53], v[164:167], v[196:199], v[50:53]
	v_mfma_f32_16x16x32_bf16 v[38:41], v[156:159], v[204:207], v[38:41]
	v_mfma_f32_16x16x32_bf16 v[34:37], v[164:167], v[204:207], v[34:37]
	v_mfma_f32_16x16x32_bf16 v[22:25], v[156:159], v[212:215], v[22:25]
	v_mfma_f32_16x16x32_bf16 v[18:21], v[164:167], v[212:215], v[18:21]
	v_mfma_f32_16x16x32_bf16 v[46:49], v[168:171], v[184:187], v[46:49]
	v_mfma_f32_16x16x32_bf16 v[42:45], v[176:179], v[184:187], v[42:45]
	v_mfma_f32_16x16x32_bf16 v[30:33], v[168:171], v[192:195], v[30:33]
	v_mfma_f32_16x16x32_bf16 v[26:29], v[176:179], v[192:195], v[26:29]
	v_mfma_f32_16x16x32_bf16 v[14:17], v[168:171], v[200:203], v[14:17]
	v_mfma_f32_16x16x32_bf16 v[10:13], v[176:179], v[200:203], v[10:13]
	v_mfma_f32_16x16x32_bf16 v[6:9], v[168:171], v[208:211], v[6:9]
	v_mfma_f32_16x16x32_bf16 v[2:5], v[176:179], v[208:211], v[2:5]
	v_mfma_f32_16x16x32_bf16 v[46:49], v[172:175], v[188:191], v[46:49]
	v_mfma_f32_16x16x32_bf16 v[42:45], v[180:183], v[188:191], v[42:45]
	v_mfma_f32_16x16x32_bf16 v[30:33], v[172:175], v[196:199], v[30:33]
	v_mfma_f32_16x16x32_bf16 v[26:29], v[180:183], v[196:199], v[26:29]
	v_mfma_f32_16x16x32_bf16 v[14:17], v[172:175], v[204:207], v[14:17]
	v_mfma_f32_16x16x32_bf16 v[10:13], v[180:183], v[204:207], v[10:13]
	v_mfma_f32_16x16x32_bf16 v[6:9], v[172:175], v[212:215], v[6:9]
	v_mfma_f32_16x16x32_bf16 v[2:5], v[180:183], v[212:215], v[2:5]
	s_barrier
	s_add_i32 s66, 0, 0x18000
	s_add_i32 s67, 0, 0x1c000
	v_add_u32_e32 v164, s66, v147
	v_add_u32_e32 v180, s67, v147
	ds_read_b128 v[152:155], v164
	ds_read_b128 v[156:159], v164 offset:1024
	ds_read_b128 v[160:163], v164 offset:2048
	ds_read_b128 v[164:167], v164 offset:3072
	ds_read_b128 v[168:171], v180
	ds_read_b128 v[172:175], v180 offset:1024
	ds_read_b128 v[176:179], v180 offset:2048
	ds_read_b128 v[180:183], v180 offset:3072
	s_add_u32 s28, s28, 0x40000
	s_addc_u32 s29, s29, 0
	s_mov_b32 m0, s39
	v_lshl_add_u64 v[224:225], s[28:29], 0, v[136:137]
	ds_read_b128 v[184:187], v151 offset:32768
	ds_read_b128 v[188:191], v151 offset:33792
	ds_read_b128 v[192:195], v151 offset:34816
	ds_read_b128 v[196:199], v151 offset:35840
	ds_read_b128 v[200:203], v151 offset:36864
	ds_read_b128 v[204:207], v151 offset:37888
	ds_read_b128 v[208:211], v151 offset:38912
	ds_read_b128 v[212:215], v151 offset:39936
	global_load_lds_dwordx4 v[224:225], off
	v_lshl_add_u64 v[224:225], s[28:29], 0, v[132:133]
	s_mov_b32 m0, s52
	s_nop 0
	global_load_lds_dwordx4 v[224:225], off
	s_waitcnt vmcnt(8)
	s_waitcnt lgkmcnt(0)
	s_barrier
	s_waitcnt lgkmcnt(0)
	v_mfma_f32_16x16x32_bf16 v[126:129], v[152:155], v[184:187], v[126:129]
	v_mfma_f32_16x16x32_bf16 v[122:125], v[160:163], v[184:187], v[122:125]
	v_mfma_f32_16x16x32_bf16 v[118:121], v[152:155], v[192:195], v[118:121]
	v_mfma_f32_16x16x32_bf16 v[114:117], v[160:163], v[192:195], v[114:117]
	v_mfma_f32_16x16x32_bf16 v[102:105], v[152:155], v[200:203], v[102:105]
	v_mfma_f32_16x16x32_bf16 v[98:101], v[160:163], v[200:203], v[98:101]
	v_mfma_f32_16x16x32_bf16 v[86:89], v[152:155], v[208:211], v[86:89]
	v_mfma_f32_16x16x32_bf16 v[82:85], v[160:163], v[208:211], v[82:85]
	v_mfma_f32_16x16x32_bf16 v[126:129], v[156:159], v[188:191], v[126:129]
	v_mfma_f32_16x16x32_bf16 v[122:125], v[164:167], v[188:191], v[122:125]
	v_mfma_f32_16x16x32_bf16 v[118:121], v[156:159], v[196:199], v[118:121]
	v_mfma_f32_16x16x32_bf16 v[114:117], v[164:167], v[196:199], v[114:117]
	v_mfma_f32_16x16x32_bf16 v[102:105], v[156:159], v[204:207], v[102:105]
	v_mfma_f32_16x16x32_bf16 v[98:101], v[164:167], v[204:207], v[98:101]
	v_mfma_f32_16x16x32_bf16 v[86:89], v[156:159], v[212:215], v[86:89]
	v_mfma_f32_16x16x32_bf16 v[82:85], v[164:167], v[212:215], v[82:85]
	v_mfma_f32_16x16x32_bf16 v[110:113], v[168:171], v[184:187], v[110:113]
	v_mfma_f32_16x16x32_bf16 v[106:109], v[176:179], v[184:187], v[106:109]
	v_mfma_f32_16x16x32_bf16 v[94:97], v[168:171], v[192:195], v[94:97]
	v_mfma_f32_16x16x32_bf16 v[90:93], v[176:179], v[192:195], v[90:93]
	v_mfma_f32_16x16x32_bf16 v[78:81], v[168:171], v[200:203], v[78:81]
	v_mfma_f32_16x16x32_bf16 v[74:77], v[176:179], v[200:203], v[74:77]
	v_mfma_f32_16x16x32_bf16 v[70:73], v[168:171], v[208:211], v[70:73]
	v_mfma_f32_16x16x32_bf16 v[66:69], v[176:179], v[208:211], v[66:69]
	v_mfma_f32_16x16x32_bf16 v[110:113], v[172:175], v[188:191], v[110:113]
	v_mfma_f32_16x16x32_bf16 v[106:109], v[180:183], v[188:191], v[106:109]
	v_mfma_f32_16x16x32_bf16 v[94:97], v[172:175], v[196:199], v[94:97]
	v_mfma_f32_16x16x32_bf16 v[90:93], v[180:183], v[196:199], v[90:93]
	v_mfma_f32_16x16x32_bf16 v[78:81], v[172:175], v[204:207], v[78:81]
	v_mfma_f32_16x16x32_bf16 v[74:77], v[180:183], v[204:207], v[74:77]
	v_mfma_f32_16x16x32_bf16 v[70:73], v[172:175], v[212:215], v[70:73]
	v_mfma_f32_16x16x32_bf16 v[66:69], v[180:183], v[212:215], v[66:69]
	s_barrier
; #define PG8_STAGE(bufoff, gbase, voff) do { _Pragma("unroll") for (int _i = 0; _i < 2; ++_i) \
;         __builtin_amdgcn_global_load_lds((const unsigned*)((const char*)(gbase) + (voff)[_i]), (LAS unsigned*)(lds + (bufoff) + ldsw + _i * 8192), 16, 0, 0); } while (0)
; #define PG8_LDA(dst, b, h) do { _Pragma("unroll") for (int m = 0; m < 4; ++m) _Pragma("unroll") for (int k = 0; k < 2; ++k) dst[m][k] = *(const LAS bf16x8*)(lds + PG8_SA(b, h) + aoff + m * 2048 + k * 1024); } while (0)
; #define PG8_MMA(ai, bj, At, Bt) do { __builtin_amdgcn_s_setprio(1); _Pragma("unroll") for (int m = 0; m < 4; ++m) _Pragma("unroll") for (int n = 0; n < 2; ++n) _Pragma("unroll") for (int k = 0; k < 2; ++k) \
;         acc[ai][bj][m][n] = __builtin_amdgcn_mfma_f32_16x16x32_bf16(Bt[n][k], At[m][k], acc[ai][bj][m][n], 0, 0, 0); __builtin_amdgcn_s_setprio(0); } while (0)
; #define PG8_WAIT_V(n) asm volatile("s_waitcnt vmcnt(" #n ")" ::: "memory")
; #define PG8_WAIT_L(n) asm volatile("s_waitcnt lgkmcnt(" #n ")" ::: "memory")
; #define PG8_BAR __builtin_amdgcn_s_barrier()
; #define PG8_SCHED __builtin_amdgcn_sched_barrier(0)
; template <class Epi>
; __device__ __forceinline__ void gemm_phase(LAS unsigned char* lds, const Gemm g, const StaticOrder& S, const Epi& E) {
;     ...
;             PG8_LDA(At, 1, 1); PG8_STAGE(PG8_SB(1, 0), b3, voffB); PG8_STAGE(PG8_SB(1, 1), b3 + hstep, voffB); PG8_STAGE(PG8_SA(1, 0), a3, voffA);
;             PG8_WAIT_V(8); PG8_WAIT_L(0); PG8_BAR; PG8_MMA(1, 0, At, B0); PG8_MMA(1, 1, At, B1); PG8_BAR; PG8_SCHED;
;         }
;         if (wr == 0) PG8_BAR;
	s_add_i32 s28, s66, s35
	v_lshl_add_u64 v[216:217], v[216:217], 0, s[6:7]
	s_mov_b32 m0, s28
	ds_read_b128 v[184:187], v151 offset:49152
	ds_read_b128 v[188:191], v151 offset:50176
	ds_read_b128 v[192:195], v151 offset:51200
	ds_read_b128 v[196:199], v151 offset:52224
	ds_read_b128 v[200:203], v151 offset:53248
	ds_read_b128 v[204:207], v151 offset:54272
	ds_read_b128 v[208:211], v151 offset:55296
	ds_read_b128 v[212:215], v151 offset:56320
	global_load_lds_dwordx4 v[216:217], off
	s_add_i32 m0, s28, 0x2000
	s_add_u32 s22, s22, 0x40080
	v_lshl_add_u64 v[216:217], v[218:219], 0, s[6:7]
	s_addc_u32 s23, s23, 0
	s_add_i32 s28, s67, s35
	global_load_lds_dwordx4 v[216:217], off
	v_lshl_add_u64 v[216:217], s[22:23], 0, v[134:135]
	s_mov_b32 m0, s28
	s_nop 0
	global_load_lds_dwordx4 v[216:217], off
	v_lshl_add_u64 v[216:217], s[22:23], 0, v[130:131]
	s_add_i32 m0, s28, 0x2000
	s_nop 0
	global_load_lds_dwordx4 v[216:217], off
	v_lshl_add_u64 v[216:217], v[220:221], 0, s[6:7]
	s_mov_b32 m0, s54
	s_nop 0
	global_load_lds_dwordx4 v[216:217], off
	v_lshl_add_u64 v[216:217], v[222:223], 0, s[6:7]
	s_mov_b32 m0, s55
	s_nop 0
	global_load_lds_dwordx4 v[216:217], off
	s_waitcnt vmcnt(8)
	s_waitcnt lgkmcnt(0)
	s_barrier
	s_waitcnt lgkmcnt(0)
	v_mfma_f32_16x16x32_bf16 v[62:65], v[152:155], v[184:187], v[62:65]
	v_mfma_f32_16x16x32_bf16 v[58:61], v[160:163], v[184:187], v[58:61]
	v_mfma_f32_16x16x32_bf16 v[54:57], v[152:155], v[192:195], v[54:57]
	v_mfma_f32_16x16x32_bf16 v[50:53], v[160:163], v[192:195], v[50:53]
	v_mfma_f32_16x16x32_bf16 v[38:41], v[152:155], v[200:203], v[38:41]
	v_mfma_f32_16x16x32_bf16 v[34:37], v[160:163], v[200:203], v[34:37]
	v_mfma_f32_16x16x32_bf16 v[22:25], v[152:155], v[208:211], v[22:25]
	v_mfma_f32_16x16x32_bf16 v[18:21], v[160:163], v[208:211], v[18:21]
	v_mfma_f32_16x16x32_bf16 v[62:65], v[156:159], v[188:191], v[62:65]
	v_mfma_f32_16x16x32_bf16 v[58:61], v[164:167], v[188:191], v[58:61]
	v_mfma_f32_16x16x32_bf16 v[54:57], v[156:159], v[196:199], v[54:57]
	v_mfma_f32_16x16x32_bf16 v[50:53], v[164:167], v[196:199], v[50:53]
	v_mfma_f32_16x16x32_bf16 v[38:41], v[156:159], v[204:207], v[38:41]
	v_mfma_f32_16x16x32_bf16 v[34:37], v[164:167], v[204:207], v[34:37]
	v_mfma_f32_16x16x32_bf16 v[22:25], v[156:159], v[212:215], v[22:25]
	v_mfma_f32_16x16x32_bf16 v[18:21], v[164:167], v[212:215], v[18:21]
	v_mfma_f32_16x16x32_bf16 v[46:49], v[168:171], v[184:187], v[46:49]
	v_mfma_f32_16x16x32_bf16 v[42:45], v[176:179], v[184:187], v[42:45]
	v_mfma_f32_16x16x32_bf16 v[30:33], v[168:171], v[192:195], v[30:33]
	v_mfma_f32_16x16x32_bf16 v[26:29], v[176:179], v[192:195], v[26:29]
	v_mfma_f32_16x16x32_bf16 v[14:17], v[168:171], v[200:203], v[14:17]
	v_mfma_f32_16x16x32_bf16 v[10:13], v[176:179], v[200:203], v[10:13]
	v_mfma_f32_16x16x32_bf16 v[6:9], v[168:171], v[208:211], v[6:9]
	v_mfma_f32_16x16x32_bf16 v[2:5], v[176:179], v[208:211], v[2:5]
	v_mfma_f32_16x16x32_bf16 v[46:49], v[172:175], v[188:191], v[46:49]
	v_mfma_f32_16x16x32_bf16 v[42:45], v[180:183], v[188:191], v[42:45]
	v_mfma_f32_16x16x32_bf16 v[30:33], v[172:175], v[196:199], v[30:33]
	v_mfma_f32_16x16x32_bf16 v[26:29], v[180:183], v[196:199], v[26:29]
	v_mfma_f32_16x16x32_bf16 v[14:17], v[172:175], v[204:207], v[14:17]
	v_mfma_f32_16x16x32_bf16 v[10:13], v[180:183], v[204:207], v[10:13]
	v_mfma_f32_16x16x32_bf16 v[6:9], v[172:175], v[212:215], v[6:9]
	v_mfma_f32_16x16x32_bf16 v[2:5], v[180:183], v[212:215], v[2:5]
	s_barrier
	s_add_i32 s65, s65, 2
	s_add_u32 s20, s20, 0x100
	s_addc_u32 s21, s21, 0
	s_add_u32 s63, s63, 0x100
	s_addc_u32 s64, s64, 0
	s_cmp_gt_u32 s65, 13
	s_cbranch_scc0 .LBB0_314
	s_and_b64 vcc, exec, s[8:9]
	s_cbranch_vccz .LBB0_317
	s_barrier

; #define SEAM(k) do { if ((k) + 1 < hi) { if ((k) == 0) { __syncthreads(); cg::this_grid().sync(); } \
;         else { if (!xposted) { if (threadIdx.x == 0) { xst[0] = 0u; xst[1] = 0u; } __syncthreads(); xbar = xcd_barrier_post((unsigned*)(ws + 65536), xst); xposted = true; } xcd_barrier(xbar); } } } while (0)
; __global__ void __launch_bounds__(512) fwd_kernel(Args a) {
;     ...
;     if (IN(4)) { pg8::Gemm g{(const bf16_t*)(ws + WS_XB), (const bf16_t*)(ws + WS_WIN), M, NIN, D}; pg8::StaticOrder S; S.init(M, NIN, G, bx);
;                  pg8::EpiBf16 E{(bf16_t*)(ws + WS_BIG), NIN}; pg8::gemm_phase(lds, g, S, E); SEAM(4); }
.LBB0_321:
	s_setprio 0
	v_readlane_b32 s0, v238, 21
	v_readlane_b32 s1, v238, 22
	s_cmp_lt_i32 s1, 6
	s_cbranch_scc1 .LBB0_378
	v_readlane_b32 s0, v238, 23
	v_readlane_b32 s1, v238, 24
	s_xor_b64 s[0:1], s[0:1], -1
	s_andn2_b64 vcc, exec, s[0:1]
	v_cmp_eq_u32_e64 s[0:1], 0, v1
	s_cbranch_vccnz .LBB0_329
	s_and_saveexec_b64 s[2:3], s[0:1]
	s_cbranch_execz .LBB0_325
	s_add_i32 s4, 0, 0x23ff0
	v_mov_b32_e32 v2, 0
	v_mov_b32_e32 v3, s4
	s_add_i32 s4, 0, 0x23ff4
	ds_write_b32 v3, v2
	v_mov_b32_e32 v3, s4
	ds_write_b32 v3, v2

; #define PG8_STAGE(bufoff, gbase, voff) do { _Pragma("unroll") for (int _i = 0; _i < 2; ++_i) \
;         __builtin_amdgcn_global_load_lds((const unsigned*)((const char*)(gbase) + (voff)[_i]), (LAS unsigned*)(lds + (bufoff) + ldsw + _i * 8192), 16, 0, 0); } while (0)
; #define PG8_WAIT_V(n) asm volatile("s_waitcnt vmcnt(" #n ")" ::: "memory")
; #define PG8_BAR __builtin_amdgcn_s_barrier()
; template <class Epi>
; __device__ __forceinline__ void gemm_phase(LAS unsigned char* lds, const Gemm g, const StaticOrder& S, const Epi& E) {
;     const int tid = threadIdx.x, wid = __builtin_amdgcn_readfirstlane(tid >> 6), lane = tid & 63, wr = wid >> 2, wc = wid & 3, fr = lane & 15, fq = lane >> 4;
;     const int K = g.K, nt = K / BK;
;     unsigned voffA[2], voffB[2];
; #pragma unroll
;     for (int i = 0; i < 2; ++i) { int R, C; stage_rc(tid * 16 + i * 8192, R, C); const int Rb = Epi::PERM ? ((R & ~31) + perm32(R & 31)) : R;
;         voffA[i] = (unsigned)(R * K + C) * 2u; voffB[i] = (unsigned)(Rb * K + C) * 2u; }
;     const size_t kstep = (size_t)(BK * 2);
;     const size_t hstep = (size_t)HALF * K * 2;
;     const size_t tstep = 2 * hstep;
;     const unsigned ldsw = (unsigned)wid * 1024u;
;     const int aoff = lds_byte(wr * 64 + fr, fq * 8), boff = lds_byte(wc * 32 + fr, fq * 8);
;     ...
;     Unit cur, nxt; int ui = 0;
;     if (!S.next(0, cur)) return;
;     f32x4 acc[2][2][4][2];
; #pragma unroll
;     for (int a = 0; a < 2; ++a)
; #pragma unroll
;         for (int b = 0; b < 2; ++b)
; #pragma unroll
;             for (int m = 0; m < 4; ++m)
; #pragma unroll
;                 for (int n = 0; n < 2; ++n) acc[a][b][m][n] = (f32x4){0.f, 0.f, 0.f, 0.f};
;     bf16x8 At[4][2], B0[2][2], B1[2][2];
;     const char* cA = (const char*)g.A + (size_t)cur.pm * tstep; const char* cB = (const char*)g.Bt + (size_t)cur.pn * tstep;
;     PG8_STAGE(PG8_SB(0, 0), cB, voffB); PG8_STAGE(PG8_SB(0, 1), cB + hstep, voffB); PG8_STAGE(PG8_SA(0, 0), cA, voffA); PG8_STAGE(PG8_SA(0, 1), cA + hstep, voffA);
;     if (wr == 1) PG8_BAR;
;     PG8_WAIT_V(2); PG8_BAR;
;     PG8_STAGE(PG8_SB(1, 0), cB + kstep, voffB); PG8_STAGE(PG8_SA(1, 0), cA + kstep, voffA); PG8_STAGE(PG8_SB(1, 1), cB + hstep + kstep, voffB);
;     PG8_WAIT_V(6); PG8_BAR;
.LBB0_704:
	s_ashr_i32 s0, s3, 3
	s_add_u32 s33, s86, 0x3000000
	s_waitcnt lgkmcnt(0)
	s_addc_u32 s36, s87, 0
	s_add_u32 s37, s86, 0x1900000
	s_addc_u32 s38, s87, 0
	s_add_i32 s0, s2, s0
	v_lshlrev_b32_e32 v2, 4, v1
	s_ashr_i32 s2, s0, 31
	v_and_b32_e32 v3, 32, v1
	v_bfe_u32 v12, v1, 2, 4
	v_lshrrev_b32_e32 v4, 3, v1
	s_movk_i32 s3, 0x70
	v_add_u32_e32 v13, 0x2000, v2
	s_lshr_b32 s2, s2, 27
	v_bitop3_b32 v10, v2, v3, 48 bitop3:0x6c
	v_and_or_b32 v4, v4, s3, v12
	v_lshrrev_b32_e32 v2, 7, v13
	s_movk_i32 s3, 0xf0
	s_add_i32 s2, s0, s2
	v_and_or_b32 v2, v2, s3, v12
	s_ashr_i32 s3, s2, 5
	s_andn2_b32 s2, s2, 31
	s_sub_i32 s2, s0, s2
	s_bfe_i32 s0, s2, 0x80000
	s_bfe_u32 s0, s0, 0x3000c
	s_add_i32 s5, s2, s0
	s_bfe_i32 s0, s5, 0x80000
	s_and_b32 s5, s5, 0xf8
	s_sub_i32 s2, s2, s5
	s_lshl_b32 s3, s3, 3
	s_sext_i32_i16 s0, s0
	s_sext_i32_i8 s2, s2
	s_lshr_b32 s1, s6, 8
	s_lshr_b32 s0, s0, 3
	s_add_i32 s26, s3, s2
	s_lshr_b32 s4, s6, 6
	s_ashr_i32 s27, s26, 31
	s_bfe_i64 s[10:11], s[0:1], 0x100000
	s_lshl_b32 s39, s4, 10
	s_lshl_b64 s[2:3], s[26:27], 19
	s_lshl_b64 s[10:11], s[10:11], 19
	v_and_b32_e32 v11, 64, v1
	s_add_u32 s30, s37, s10
	v_or_b32_e32 v3, v10, v11
	s_addc_u32 s31, s38, s11
	s_add_i32 s40, s39, 0
	v_lshl_or_b32 v130, v4, 11, v3
	s_add_i32 m0, s40, 0x10000
	v_lshl_or_b32 v132, v2, 11, v3
	global_load_lds_dwordx4 v130, s[30:31]
	s_add_i32 m0, s40, 0x12000
	s_add_u32 s10, s30, 0x40000
	global_load_lds_dwordx4 v132, s[30:31]
	s_addc_u32 s11, s31, 0
	s_add_i32 m0, s40, 0x14000
	v_mov_b32_e32 v131, 0
	global_load_lds_dwordx4 v130, s[10:11]
	s_add_i32 m0, s40, 0x16000
	s_add_u32 s28, s33, s2
	s_addc_u32 s29, s36, s3
	s_add_i32 s41, s40, 0x2000
	global_load_lds_dwordx4 v132, s[10:11]
	s_mov_b32 m0, s40
	s_add_u32 s2, s28, 0x40000
	global_load_lds_dwordx4 v130, s[28:29]
	s_mov_b32 m0, s41
	s_addc_u32 s3, s29, 0
	s_add_i32 s42, s40, 0x4000
	global_load_lds_dwordx4 v132, s[28:29]
	s_mov_b32 m0, s42
	s_add_i32 s43, s40, 0x6000
	global_load_lds_dwordx4 v130, s[2:3]
	s_mov_b32 m0, s43
	v_mov_b32_e32 v133, v131
	global_load_lds_dwordx4 v132, s[2:3]
	s_cmp_eq_u32 s1, 1
	s_mov_b32 s44, 0
	v_lshl_add_u64 v[8:9], s[30:31], 0, v[130:131]
	v_lshl_add_u64 v[6:7], s[30:31], 0, v[132:133]
	v_lshl_add_u64 v[2:3], s[28:29], 0, v[130:131]
	s_cselect_b64 s[2:3], -1, 0
	s_cmp_lg_u32 s1, 1
	v_lshl_add_u64 v[4:5], s[28:29], 0, v[132:133]
	s_cbranch_scc1 .LBB0_706
	s_barrier
	s_setprio 1

; #define PG8_STAGE(bufoff, gbase, voff) do { _Pragma("unroll") for (int _i = 0; _i < 2; ++_i) \
;         __builtin_amdgcn_global_load_lds((const unsigned*)((const char*)(gbase) + (voff)[_i]), (LAS unsigned*)(lds + (bufoff) + ldsw + _i * 8192), 16, 0, 0); } while (0)
; #define PG8_LDA(dst, b, h) do { _Pragma("unroll") for (int m = 0; m < 4; ++m) _Pragma("unroll") for (int k = 0; k < 2; ++k) dst[m][k] = *(const LAS bf16x8*)(lds + PG8_SA(b, h) + aoff + m * 2048 + k * 1024); } while (0)
; #define PG8_LDB(dst, b, h) do { _Pragma("unroll") for (int n = 0; n < 2; ++n) _Pragma("unroll") for (int k = 0; k < 2; ++k) dst[n][k] = *(const LAS bf16x8*)(lds + PG8_SB(b, h) + boff + n * 2048 + k * 1024); } while (0)
; #define PG8_MMA(ai, bj, At, Bt) do { __builtin_amdgcn_s_setprio(1); _Pragma("unroll") for (int m = 0; m < 4; ++m) _Pragma("unroll") for (int n = 0; n < 2; ++n) _Pragma("unroll") for (int k = 0; k < 2; ++k) \
;         acc[ai][bj][m][n] = __builtin_amdgcn_mfma_f32_16x16x32_bf16(Bt[n][k], At[m][k], acc[ai][bj][m][n], 0, 0, 0); __builtin_amdgcn_s_setprio(0); } while (0)
; #define PG8_WAIT_V(n) asm volatile("s_waitcnt vmcnt(" #n ")" ::: "memory")
; #define PG8_WAIT_L(n) asm volatile("s_waitcnt lgkmcnt(" #n ")" ::: "memory")
; #define PG8_BAR __builtin_amdgcn_s_barrier()
; #define PG8_SCHED __builtin_amdgcn_sched_barrier(0)
; template <class Epi>
; __device__ __forceinline__ void gemm_phase(LAS unsigned char* lds, const Gemm g, const StaticOrder& S, const Epi& E) {
;     ...
;         for (int t = 0; t < nt; t += 2) {
;             const bool last = (t == nt - 2);
;             const char* a1 = cA + (size_t)(t + 1) * kstep;
;             const char* a2 = last ? nA : cA + (size_t)(t + 2) * kstep; const char* b2 = last ? nB : cB + (size_t)(t + 2) * kstep;
;             const char* a3 = a2 + kstep; const char* b3 = b2 + kstep;
;             PG8_LDB(B0, 0, 0); PG8_LDB(B1, 0, 1); PG8_SCHED; PG8_LDA(At, 0, 0); PG8_STAGE(PG8_SA(1, 1), a1 + hstep, voffA);
;             PG8_WAIT_V(8); PG8_WAIT_L(0); PG8_BAR; PG8_MMA(0, 0, At, B0); PG8_MMA(0, 1, At, B1); PG8_BAR; PG8_SCHED;
;             PG8_LDA(At, 0, 1); PG8_STAGE(PG8_SB(0, 0), b2, voffB); PG8_STAGE(PG8_SB(0, 1), b2 + hstep, voffB); PG8_STAGE(PG8_SA(0, 0), a2, voffA);
.LBB0_716:
	ds_read_b128 v[142:145], v151
	ds_read_b128 v[154:157], v151 offset:1024
	ds_read_b128 v[158:161], v151 offset:2048
	ds_read_b128 v[162:165], v151 offset:3072
	ds_read_b128 v[166:169], v152
	ds_read_b128 v[170:173], v152 offset:1024
	ds_read_b128 v[174:177], v152 offset:2048
	ds_read_b128 v[178:181], v152 offset:3072
	s_add_u32 s30, s28, 0xfffc0080
	s_addc_u32 s31, s29, -1
	s_cmp_eq_u32 s58, 12
	s_cselect_b32 s35, s21, s31
	s_cselect_b32 s34, s54, s30
	s_cselect_b32 s31, s19, s57
	s_cselect_b32 s30, s55, s56
	v_lshl_add_u64 v[146:147], s[28:29], 0, v[134:135]
	s_add_i32 m0, s40, 0xc000
	ds_read_b128 v[182:185], v153
	ds_read_b128 v[186:189], v153 offset:1024
	ds_read_b128 v[190:193], v153 offset:2048
	ds_read_b128 v[194:197], v153 offset:3072
	ds_read_b128 v[198:201], v153 offset:4096
	ds_read_b128 v[202:205], v153 offset:5120
	ds_read_b128 v[206:209], v153 offset:6144
	ds_read_b128 v[210:213], v153 offset:7168
	global_load_lds_dwordx4 v[146:147], off
	v_lshl_add_u64 v[146:147], s[28:29], 0, v[136:137]
	s_add_i32 m0, s40, 0xe000
	s_nop 0
	global_load_lds_dwordx4 v[146:147], off
	s_waitcnt vmcnt(8)
	s_waitcnt lgkmcnt(0)
	s_barrier
	s_waitcnt lgkmcnt(0)
	v_mfma_f32_16x16x32_bf16 v[126:129], v[142:145], v[182:185], v[126:129]
	v_mfma_f32_16x16x32_bf16 v[122:125], v[158:161], v[182:185], v[122:125]
	v_mfma_f32_16x16x32_bf16 v[114:117], v[142:145], v[190:193], v[114:117]
	v_mfma_f32_16x16x32_bf16 v[106:109], v[158:161], v[190:193], v[106:109]
	v_mfma_f32_16x16x32_bf16 v[94:97], v[142:145], v[198:201], v[94:97]
	v_mfma_f32_16x16x32_bf16 v[90:93], v[158:161], v[198:201], v[90:93]
	v_mfma_f32_16x16x32_bf16 v[78:81], v[142:145], v[206:209], v[78:81]
	v_mfma_f32_16x16x32_bf16 v[74:77], v[158:161], v[206:209], v[74:77]
	v_mfma_f32_16x16x32_bf16 v[126:129], v[154:157], v[186:189], v[126:129]
	v_mfma_f32_16x16x32_bf16 v[122:125], v[162:165], v[186:189], v[122:125]
	v_mfma_f32_16x16x32_bf16 v[114:117], v[154:157], v[194:197], v[114:117]
	v_mfma_f32_16x16x32_bf16 v[106:109], v[162:165], v[194:197], v[106:109]
	v_mfma_f32_16x16x32_bf16 v[94:97], v[154:157], v[202:205], v[94:97]
	v_mfma_f32_16x16x32_bf16 v[90:93], v[162:165], v[202:205], v[90:93]
	v_mfma_f32_16x16x32_bf16 v[78:81], v[154:157], v[210:213], v[78:81]
	v_mfma_f32_16x16x32_bf16 v[74:77], v[162:165], v[210:213], v[74:77]
	v_mfma_f32_16x16x32_bf16 v[118:121], v[166:169], v[182:185], v[118:121]
	v_mfma_f32_16x16x32_bf16 v[110:113], v[174:177], v[182:185], v[110:113]
	v_mfma_f32_16x16x32_bf16 v[102:105], v[166:169], v[190:193], v[102:105]
	v_mfma_f32_16x16x32_bf16 v[98:101], v[174:177], v[190:193], v[98:101]
	v_mfma_f32_16x16x32_bf16 v[86:89], v[166:169], v[198:201], v[86:89]
	v_mfma_f32_16x16x32_bf16 v[82:85], v[174:177], v[198:201], v[82:85]
	v_mfma_f32_16x16x32_bf16 v[70:73], v[166:169], v[206:209], v[70:73]
	v_mfma_f32_16x16x32_bf16 v[66:69], v[174:177], v[206:209], v[66:69]
	v_mfma_f32_16x16x32_bf16 v[118:121], v[170:173], v[186:189], v[118:121]
	v_mfma_f32_16x16x32_bf16 v[110:113], v[178:181], v[186:189], v[110:113]
	v_mfma_f32_16x16x32_bf16 v[102:105], v[170:173], v[194:197], v[102:105]
	v_mfma_f32_16x16x32_bf16 v[98:101], v[178:181], v[194:197], v[98:101]
	v_mfma_f32_16x16x32_bf16 v[86:89], v[170:173], v[202:205], v[86:89]
	v_mfma_f32_16x16x32_bf16 v[82:85], v[178:181], v[202:205], v[82:85]
	v_mfma_f32_16x16x32_bf16 v[70:73], v[170:173], v[210:213], v[70:73]
	v_mfma_f32_16x16x32_bf16 v[66:69], v[178:181], v[210:213], v[66:69]
	s_barrier
	s_add_i32 s59, s48, s39
	v_lshl_add_u64 v[146:147], s[30:31], 0, v[130:131]
	s_mov_b32 m0, s59
	ds_read_b128 v[182:185], v153 offset:16384
	ds_read_b128 v[186:189], v153 offset:17408
	ds_read_b128 v[190:193], v153 offset:18432
	ds_read_b128 v[194:197], v153 offset:19456
	ds_read_b128 v[198:201], v153 offset:20480
	ds_read_b128 v[202:205], v153 offset:21504
	ds_read_b128 v[206:209], v153 offset:22528
	ds_read_b128 v[210:213], v153 offset:23552
	global_load_lds_dwordx4 v[146:147], off
	s_add_i32 m0, s59, 0x2000
	s_add_u32 s60, s30, 0x40000
	v_lshl_add_u64 v[214:215], s[30:31], 0, v[132:133]
	s_addc_u32 s61, s31, 0
	s_add_i32 s59, s49, s39
	global_load_lds_dwordx4 v[214:215], off
	v_lshl_add_u64 v[216:217], s[60:61], 0, v[130:131]
	s_mov_b32 m0, s59
	v_lshl_add_u64 v[218:219], s[34:35], 0, v[132:133]
	global_load_lds_dwordx4 v[216:217], off
	v_lshl_add_u64 v[216:217], s[60:61], 0, v[132:133]
	s_add_i32 m0, s59, 0x2000
	s_nop 0
	global_load_lds_dwordx4 v[216:217], off
	v_lshl_add_u64 v[216:217], s[34:35], 0, v[130:131]
	s_mov_b32 m0, s40
	s_nop 0
	global_load_lds_dwordx4 v[216:217], off
	s_mov_b32 m0, s41
	s_nop 0
	global_load_lds_dwordx4 v[218:219], off
	s_waitcnt vmcnt(8)
	s_waitcnt lgkmcnt(0)
	s_barrier
; #define PG8_STAGE(bufoff, gbase, voff) do { _Pragma("unroll") for (int _i = 0; _i < 2; ++_i) \
;         __builtin_amdgcn_global_load_lds((const unsigned*)((const char*)(gbase) + (voff)[_i]), (LAS unsigned*)(lds + (bufoff) + ldsw + _i * 8192), 16, 0, 0); } while (0)
; #define PG8_LDA(dst, b, h) do { _Pragma("unroll") for (int m = 0; m < 4; ++m) _Pragma("unroll") for (int k = 0; k < 2; ++k) dst[m][k] = *(const LAS bf16x8*)(lds + PG8_SA(b, h) + aoff + m * 2048 + k * 1024); } while (0)
; #define PG8_LDB(dst, b, h) do { _Pragma("unroll") for (int n = 0; n < 2; ++n) _Pragma("unroll") for (int k = 0; k < 2; ++k) dst[n][k] = *(const LAS bf16x8*)(lds + PG8_SB(b, h) + boff + n * 2048 + k * 1024); } while (0)
; #define PG8_MMA(ai, bj, At, Bt) do { __builtin_amdgcn_s_setprio(1); _Pragma("unroll") for (int m = 0; m < 4; ++m) _Pragma("unroll") for (int n = 0; n < 2; ++n) _Pragma("unroll") for (int k = 0; k < 2; ++k) \
;         acc[ai][bj][m][n] = __builtin_amdgcn_mfma_f32_16x16x32_bf16(Bt[n][k], At[m][k], acc[ai][bj][m][n], 0, 0, 0); __builtin_amdgcn_s_setprio(0); } while (0)
; #define PG8_WAIT_V(n) asm volatile("s_waitcnt vmcnt(" #n ")" ::: "memory")
; #define PG8_WAIT_L(n) asm volatile("s_waitcnt lgkmcnt(" #n ")" ::: "memory")
; #define PG8_BAR __builtin_amdgcn_s_barrier()
; #define PG8_SCHED __builtin_amdgcn_sched_barrier(0)
; template <class Epi>
; __device__ __forceinline__ void gemm_phase(LAS unsigned char* lds, const Gemm g, const StaticOrder& S, const Epi& E) {
;     ...
;             PG8_WAIT_V(8); PG8_WAIT_L(0); PG8_BAR; PG8_MMA(1, 0, At, B0); PG8_MMA(1, 1, At, B1); PG8_BAR; PG8_SCHED;
;             PG8_LDB(B0, 1, 0); PG8_LDB(B1, 1, 1); PG8_SCHED; PG8_LDA(At, 1, 0); PG8_STAGE(PG8_SA(0, 1), a2 + hstep, voffA);
;             PG8_WAIT_V(8); PG8_WAIT_L(0); PG8_BAR; PG8_MMA(0, 0, At, B0); PG8_MMA(0, 1, At, B1); PG8_BAR; PG8_SCHED;
;             PG8_LDA(At, 1, 1); PG8_STAGE(PG8_SB(1, 0), b3, voffB); PG8_STAGE(PG8_SB(1, 1), b3 + hstep, voffB); PG8_STAGE(PG8_SA(1, 0), a3, voffA);
	s_waitcnt lgkmcnt(0)
	v_mfma_f32_16x16x32_bf16 v[62:65], v[142:145], v[182:185], v[62:65]
	v_mfma_f32_16x16x32_bf16 v[58:61], v[158:161], v[182:185], v[58:61]
	v_mfma_f32_16x16x32_bf16 v[46:49], v[142:145], v[190:193], v[46:49]
	v_mfma_f32_16x16x32_bf16 v[42:45], v[158:161], v[190:193], v[42:45]
	v_mfma_f32_16x16x32_bf16 v[30:33], v[142:145], v[198:201], v[30:33]
	v_mfma_f32_16x16x32_bf16 v[26:29], v[158:161], v[198:201], v[26:29]
	v_mfma_f32_16x16x32_bf16 v[14:17], v[142:145], v[206:209], v[14:17]
	v_mfma_f32_16x16x32_bf16 v[10:13], v[158:161], v[206:209], v[10:13]
	v_mfma_f32_16x16x32_bf16 v[62:65], v[154:157], v[186:189], v[62:65]
	v_mfma_f32_16x16x32_bf16 v[58:61], v[162:165], v[186:189], v[58:61]
	v_mfma_f32_16x16x32_bf16 v[46:49], v[154:157], v[194:197], v[46:49]
	v_mfma_f32_16x16x32_bf16 v[42:45], v[162:165], v[194:197], v[42:45]
	v_mfma_f32_16x16x32_bf16 v[30:33], v[154:157], v[202:205], v[30:33]
	v_mfma_f32_16x16x32_bf16 v[26:29], v[162:165], v[202:205], v[26:29]
	v_mfma_f32_16x16x32_bf16 v[14:17], v[154:157], v[210:213], v[14:17]
	v_mfma_f32_16x16x32_bf16 v[10:13], v[162:165], v[210:213], v[10:13]
	v_mfma_f32_16x16x32_bf16 v[54:57], v[166:169], v[182:185], v[54:57]
	v_mfma_f32_16x16x32_bf16 v[50:53], v[174:177], v[182:185], v[50:53]
	v_mfma_f32_16x16x32_bf16 v[38:41], v[166:169], v[190:193], v[38:41]
	v_mfma_f32_16x16x32_bf16 v[34:37], v[174:177], v[190:193], v[34:37]
	v_mfma_f32_16x16x32_bf16 v[22:25], v[166:169], v[198:201], v[22:25]
	v_mfma_f32_16x16x32_bf16 v[18:21], v[174:177], v[198:201], v[18:21]
	v_mfma_f32_16x16x32_bf16 v[6:9], v[166:169], v[206:209], v[6:9]
	v_mfma_f32_16x16x32_bf16 v[2:5], v[174:177], v[206:209], v[2:5]
	v_mfma_f32_16x16x32_bf16 v[54:57], v[170:173], v[186:189], v[54:57]
	v_mfma_f32_16x16x32_bf16 v[50:53], v[178:181], v[186:189], v[50:53]
	v_mfma_f32_16x16x32_bf16 v[38:41], v[170:173], v[194:197], v[38:41]
	v_mfma_f32_16x16x32_bf16 v[34:37], v[178:181], v[194:197], v[34:37]
	v_mfma_f32_16x16x32_bf16 v[22:25], v[170:173], v[202:205], v[22:25]
	v_mfma_f32_16x16x32_bf16 v[18:21], v[178:181], v[202:205], v[18:21]
	v_mfma_f32_16x16x32_bf16 v[6:9], v[170:173], v[210:213], v[6:9]
	v_mfma_f32_16x16x32_bf16 v[2:5], v[178:181], v[210:213], v[2:5]
	s_barrier
	s_add_i32 s59, 0, 0x18000
	s_add_i32 s60, 0, 0x1c000
	v_add_u32_e32 v162, s59, v149
	v_add_u32_e32 v178, s60, v149
	ds_read_b128 v[142:145], v162
	ds_read_b128 v[154:157], v162 offset:1024
	ds_read_b128 v[158:161], v162 offset:2048
	ds_read_b128 v[162:165], v162 offset:3072
	ds_read_b128 v[166:169], v178
	ds_read_b128 v[170:173], v178 offset:1024
	ds_read_b128 v[174:177], v178 offset:2048
	ds_read_b128 v[178:181], v178 offset:3072
	s_add_u32 s34, s34, 0x40000
	s_addc_u32 s35, s35, 0
	s_mov_b32 m0, s42
	v_lshl_add_u64 v[220:221], s[34:35], 0, v[130:131]
	ds_read_b128 v[182:185], v153 offset:32768
	ds_read_b128 v[186:189], v153 offset:33792
	ds_read_b128 v[190:193], v153 offset:34816
	ds_read_b128 v[194:197], v153 offset:35840
	ds_read_b128 v[198:201], v153 offset:36864
	ds_read_b128 v[202:205], v153 offset:37888
	ds_read_b128 v[206:209], v153 offset:38912
	ds_read_b128 v[210:213], v153 offset:39936
	global_load_lds_dwordx4 v[220:221], off
	v_lshl_add_u64 v[220:221], s[34:35], 0, v[132:133]
	s_mov_b32 m0, s43
	s_nop 0
	global_load_lds_dwordx4 v[220:221], off
	s_waitcnt vmcnt(8)
	s_waitcnt lgkmcnt(0)
	s_barrier
	s_waitcnt lgkmcnt(0)
	v_mfma_f32_16x16x32_bf16 v[126:129], v[142:145], v[182:185], v[126:129]
	v_mfma_f32_16x16x32_bf16 v[122:125], v[158:161], v[182:185], v[122:125]
	v_mfma_f32_16x16x32_bf16 v[114:117], v[142:145], v[190:193], v[114:117]
	v_mfma_f32_16x16x32_bf16 v[106:109], v[158:161], v[190:193], v[106:109]
	v_mfma_f32_16x16x32_bf16 v[94:97], v[142:145], v[198:201], v[94:97]
	v_mfma_f32_16x16x32_bf16 v[90:93], v[158:161], v[198:201], v[90:93]
	v_mfma_f32_16x16x32_bf16 v[78:81], v[142:145], v[206:209], v[78:81]
	v_mfma_f32_16x16x32_bf16 v[74:77], v[158:161], v[206:209], v[74:77]
	v_mfma_f32_16x16x32_bf16 v[126:129], v[154:157], v[186:189], v[126:129]
	v_mfma_f32_16x16x32_bf16 v[122:125], v[162:165], v[186:189], v[122:125]
	v_mfma_f32_16x16x32_bf16 v[114:117], v[154:157], v[194:197], v[114:117]
	v_mfma_f32_16x16x32_bf16 v[106:109], v[162:165], v[194:197], v[106:109]
	v_mfma_f32_16x16x32_bf16 v[94:97], v[154:157], v[202:205], v[94:97]
	v_mfma_f32_16x16x32_bf16 v[90:93], v[162:165], v[202:205], v[90:93]
	v_mfma_f32_16x16x32_bf16 v[78:81], v[154:157], v[210:213], v[78:81]
	v_mfma_f32_16x16x32_bf16 v[74:77], v[162:165], v[210:213], v[74:77]
	v_mfma_f32_16x16x32_bf16 v[118:121], v[166:169], v[182:185], v[118:121]
	v_mfma_f32_16x16x32_bf16 v[110:113], v[174:177], v[182:185], v[110:113]
	v_mfma_f32_16x16x32_bf16 v[102:105], v[166:169], v[190:193], v[102:105]
	v_mfma_f32_16x16x32_bf16 v[98:101], v[174:177], v[190:193], v[98:101]
	v_mfma_f32_16x16x32_bf16 v[86:89], v[166:169], v[198:201], v[86:89]
	v_mfma_f32_16x16x32_bf16 v[82:85], v[174:177], v[198:201], v[82:85]
	v_mfma_f32_16x16x32_bf16 v[70:73], v[166:169], v[206:209], v[70:73]
	v_mfma_f32_16x16x32_bf16 v[66:69], v[174:177], v[206:209], v[66:69]
	v_mfma_f32_16x16x32_bf16 v[118:121], v[170:173], v[186:189], v[118:121]
	v_mfma_f32_16x16x32_bf16 v[110:113], v[178:181], v[186:189], v[110:113]
	v_mfma_f32_16x16x32_bf16 v[102:105], v[170:173], v[194:197], v[102:105]
	v_mfma_f32_16x16x32_bf16 v[98:101], v[178:181], v[194:197], v[98:101]
	v_mfma_f32_16x16x32_bf16 v[86:89], v[170:173], v[202:205], v[86:89]
	v_mfma_f32_16x16x32_bf16 v[82:85], v[178:181], v[202:205], v[82:85]
	v_mfma_f32_16x16x32_bf16 v[70:73], v[170:173], v[210:213], v[70:73]
	v_mfma_f32_16x16x32_bf16 v[66:69], v[178:181], v[210:213], v[66:69]
	s_barrier
; #define PG8_STAGE(bufoff, gbase, voff) do { _Pragma("unroll") for (int _i = 0; _i < 2; ++_i) \
;         __builtin_amdgcn_global_load_lds((const unsigned*)((const char*)(gbase) + (voff)[_i]), (LAS unsigned*)(lds + (bufoff) + ldsw + _i * 8192), 16, 0, 0); } while (0)
; #define PG8_LDA(dst, b, h) do { _Pragma("unroll") for (int m = 0; m < 4; ++m) _Pragma("unroll") for (int k = 0; k < 2; ++k) dst[m][k] = *(const LAS bf16x8*)(lds + PG8_SA(b, h) + aoff + m * 2048 + k * 1024); } while (0)
; #define PG8_MMA(ai, bj, At, Bt) do { __builtin_amdgcn_s_setprio(1); _Pragma("unroll") for (int m = 0; m < 4; ++m) _Pragma("unroll") for (int n = 0; n < 2; ++n) _Pragma("unroll") for (int k = 0; k < 2; ++k) \
;         acc[ai][bj][m][n] = __builtin_amdgcn_mfma_f32_16x16x32_bf16(Bt[n][k], At[m][k], acc[ai][bj][m][n], 0, 0, 0); __builtin_amdgcn_s_setprio(0); } while (0)
; #define PG8_WAIT_V(n) asm volatile("s_waitcnt vmcnt(" #n ")" ::: "memory")
; #define PG8_WAIT_L(n) asm volatile("s_waitcnt lgkmcnt(" #n ")" ::: "memory")
; #define PG8_BAR __builtin_amdgcn_s_barrier()
; #define PG8_SCHED __builtin_amdgcn_sched_barrier(0)
; template <class Epi>
; __device__ __forceinline__ void gemm_phase(LAS unsigned char* lds, const Gemm g, const StaticOrder& S, const Epi& E) {
;     ...
;             PG8_LDA(At, 1, 1); PG8_STAGE(PG8_SB(1, 0), b3, voffB); PG8_STAGE(PG8_SB(1, 1), b3 + hstep, voffB); PG8_STAGE(PG8_SA(1, 0), a3, voffA);
;             PG8_WAIT_V(8); PG8_WAIT_L(0); PG8_BAR; PG8_MMA(1, 0, At, B0); PG8_MMA(1, 1, At, B1); PG8_BAR; PG8_SCHED;
;         }
;         if (wr == 0) PG8_BAR;
	s_add_i32 s34, s59, s39
	v_lshl_add_u64 v[146:147], v[146:147], 0, s[4:5]
	s_mov_b32 m0, s34
	ds_read_b128 v[182:185], v153 offset:49152
	ds_read_b128 v[186:189], v153 offset:50176
	ds_read_b128 v[190:193], v153 offset:51200
	ds_read_b128 v[194:197], v153 offset:52224
	ds_read_b128 v[198:201], v153 offset:53248
	ds_read_b128 v[202:205], v153 offset:54272
	ds_read_b128 v[206:209], v153 offset:55296
	ds_read_b128 v[210:213], v153 offset:56320
	global_load_lds_dwordx4 v[146:147], off
	s_add_i32 m0, s34, 0x2000
	s_add_u32 s30, s30, 0x40080
	v_lshl_add_u64 v[146:147], v[214:215], 0, s[4:5]
	s_addc_u32 s31, s31, 0
	s_add_i32 s34, s60, s39
	global_load_lds_dwordx4 v[146:147], off
	v_lshl_add_u64 v[146:147], s[30:31], 0, v[130:131]
	s_mov_b32 m0, s34
	s_nop 0
	global_load_lds_dwordx4 v[146:147], off
	v_lshl_add_u64 v[146:147], s[30:31], 0, v[132:133]
	s_add_i32 m0, s34, 0x2000
	s_nop 0
	global_load_lds_dwordx4 v[146:147], off
	v_lshl_add_u64 v[146:147], v[216:217], 0, s[4:5]
	s_mov_b32 m0, s45
	s_nop 0
	global_load_lds_dwordx4 v[146:147], off
	v_lshl_add_u64 v[146:147], v[218:219], 0, s[4:5]
	s_mov_b32 m0, s46
	s_nop 0
	global_load_lds_dwordx4 v[146:147], off
	s_waitcnt vmcnt(8)
	s_waitcnt lgkmcnt(0)
	s_barrier
	s_waitcnt lgkmcnt(0)
	v_mfma_f32_16x16x32_bf16 v[62:65], v[142:145], v[182:185], v[62:65]
	v_mfma_f32_16x16x32_bf16 v[58:61], v[158:161], v[182:185], v[58:61]
	v_mfma_f32_16x16x32_bf16 v[46:49], v[142:145], v[190:193], v[46:49]
	v_mfma_f32_16x16x32_bf16 v[42:45], v[158:161], v[190:193], v[42:45]
	v_mfma_f32_16x16x32_bf16 v[30:33], v[142:145], v[198:201], v[30:33]
	v_mfma_f32_16x16x32_bf16 v[26:29], v[158:161], v[198:201], v[26:29]
	v_mfma_f32_16x16x32_bf16 v[14:17], v[142:145], v[206:209], v[14:17]
	v_mfma_f32_16x16x32_bf16 v[10:13], v[158:161], v[206:209], v[10:13]
	v_mfma_f32_16x16x32_bf16 v[62:65], v[154:157], v[186:189], v[62:65]
	v_mfma_f32_16x16x32_bf16 v[58:61], v[162:165], v[186:189], v[58:61]
	v_mfma_f32_16x16x32_bf16 v[46:49], v[154:157], v[194:197], v[46:49]
	v_mfma_f32_16x16x32_bf16 v[42:45], v[162:165], v[194:197], v[42:45]
	v_mfma_f32_16x16x32_bf16 v[30:33], v[154:157], v[202:205], v[30:33]
	v_mfma_f32_16x16x32_bf16 v[26:29], v[162:165], v[202:205], v[26:29]
	v_mfma_f32_16x16x32_bf16 v[14:17], v[154:157], v[210:213], v[14:17]
	v_mfma_f32_16x16x32_bf16 v[10:13], v[162:165], v[210:213], v[10:13]
	v_mfma_f32_16x16x32_bf16 v[54:57], v[166:169], v[182:185], v[54:57]
	v_mfma_f32_16x16x32_bf16 v[50:53], v[174:177], v[182:185], v[50:53]
	v_mfma_f32_16x16x32_bf16 v[38:41], v[166:169], v[190:193], v[38:41]
	v_mfma_f32_16x16x32_bf16 v[34:37], v[174:177], v[190:193], v[34:37]
	v_mfma_f32_16x16x32_bf16 v[22:25], v[166:169], v[198:201], v[22:25]
	v_mfma_f32_16x16x32_bf16 v[18:21], v[174:177], v[198:201], v[18:21]
	v_mfma_f32_16x16x32_bf16 v[6:9], v[166:169], v[206:209], v[6:9]
	v_mfma_f32_16x16x32_bf16 v[2:5], v[174:177], v[206:209], v[2:5]
	v_mfma_f32_16x16x32_bf16 v[54:57], v[170:173], v[186:189], v[54:57]
	v_mfma_f32_16x16x32_bf16 v[50:53], v[178:181], v[186:189], v[50:53]
	v_mfma_f32_16x16x32_bf16 v[38:41], v[170:173], v[194:197], v[38:41]
	v_mfma_f32_16x16x32_bf16 v[34:37], v[178:181], v[194:197], v[34:37]
	v_mfma_f32_16x16x32_bf16 v[22:25], v[170:173], v[202:205], v[22:25]
	v_mfma_f32_16x16x32_bf16 v[18:21], v[178:181], v[202:205], v[18:21]
	v_mfma_f32_16x16x32_bf16 v[6:9], v[170:173], v[210:213], v[6:9]
	v_mfma_f32_16x16x32_bf16 v[2:5], v[178:181], v[210:213], v[2:5]
	s_barrier
	s_add_i32 s58, s58, 2
	s_add_u32 s28, s28, 0x100
	s_addc_u32 s29, s29, 0
	s_add_u32 s56, s56, 0x100
	s_addc_u32 s57, s57, 0
	s_cmp_gt_u32 s58, 13
	s_cbranch_scc0 .LBB0_716
	s_and_b64 vcc, exec, s[6:7]
	s_cbranch_vccz .LBB0_719
	s_barrier

; #define SEAM(k) do { if ((k) + 1 < hi) { if ((k) == 0) { __syncthreads(); cg::this_grid().sync(); } \
;         else { if (!xposted) { if (threadIdx.x == 0) { xst[0] = 0u; xst[1] = 0u; } __syncthreads(); xbar = xcd_barrier_post((unsigned*)(ws + 65536), xst); xposted = true; } xcd_barrier(xbar); } } } while (0)
; __global__ void __launch_bounds__(512) fwd_kernel(Args a) {
;     ...
;     if (IN(8)) { pg8::Gemm g{(const bf16_t*)(ws + WS_XB), (const bf16_t*)(ws + WS_WOUT), M, D, D}; pg8::StaticOrder S; S.init(M, D, G, bx);
;                  pg8::EpiResid E{hbuf, hbuf, ALPHA, 1.0f}; pg8::gemm_phase(lds, g, S, E); SEAM(8); }
.LBB0_723:
	s_setprio 0
	v_readlane_b32 s0, v238, 21
	v_readlane_b32 s1, v238, 22
	s_cmp_lt_i32 s1, 10
	s_cbranch_scc1 .LBB0_780
	v_readlane_b32 s0, v238, 23
	v_readlane_b32 s1, v238, 24
	s_xor_b64 s[0:1], s[0:1], -1
	s_andn2_b64 vcc, exec, s[0:1]
	v_cmp_eq_u32_e64 s[0:1], 0, v1
	s_cbranch_vccnz .LBB0_731
	s_and_saveexec_b64 s[2:3], s[0:1]
	s_cbranch_execz .LBB0_727
	s_add_i32 s4, 0, 0x23ff0
	v_mov_b32_e32 v2, 0
	v_mov_b32_e32 v3, s4
	s_add_i32 s4, 0, 0x23ff4
	ds_write_b32 v3, v2
	v_mov_b32_e32 v3, s4
	ds_write_b32 v3, v2

; #define PG8_STAGE(bufoff, gbase, voff) do { _Pragma("unroll") for (int _i = 0; _i < 2; ++_i) \
;         __builtin_amdgcn_global_load_lds((const unsigned*)((const char*)(gbase) + (voff)[_i]), (LAS unsigned*)(lds + (bufoff) + ldsw + _i * 8192), 16, 0, 0); } while (0)
; #define PG8_WAIT_V(n) asm volatile("s_waitcnt vmcnt(" #n ")" ::: "memory")
; #define PG8_BAR __builtin_amdgcn_s_barrier()
; template <class Epi>
; __device__ __forceinline__ void gemm_phase(LAS unsigned char* lds, const Gemm g, const StaticOrder& S, const Epi& E) {
;     const int tid = threadIdx.x, wid = __builtin_amdgcn_readfirstlane(tid >> 6), lane = tid & 63, wr = wid >> 2, wc = wid & 3, fr = lane & 15, fq = lane >> 4;
;     const int K = g.K, nt = K / BK;
;     unsigned voffA[2], voffB[2];
; #pragma unroll
;     for (int i = 0; i < 2; ++i) { int R, C; stage_rc(tid * 16 + i * 8192, R, C); const int Rb = Epi::PERM ? ((R & ~31) + perm32(R & 31)) : R;
;         voffA[i] = (unsigned)(R * K + C) * 2u; voffB[i] = (unsigned)(Rb * K + C) * 2u; }
;     const size_t kstep = (size_t)(BK * 2);
;     const size_t hstep = (size_t)HALF * K * 2;
;     const size_t tstep = 2 * hstep;
;     const unsigned ldsw = (unsigned)wid * 1024u;
;     const int aoff = lds_byte(wr * 64 + fr, fq * 8), boff = lds_byte(wc * 32 + fr, fq * 8);
;     ...
;     Unit cur, nxt; int ui = 0;
;     if (!S.next(0, cur)) return;
;     f32x4 acc[2][2][4][2];
; #pragma unroll
;     for (int a = 0; a < 2; ++a)
; #pragma unroll
;         for (int b = 0; b < 2; ++b)
; #pragma unroll
;             for (int m = 0; m < 4; ++m)
; #pragma unroll
;                 for (int n = 0; n < 2; ++n) acc[a][b][m][n] = (f32x4){0.f, 0.f, 0.f, 0.f};
;     bf16x8 At[4][2], B0[2][2], B1[2][2];
;     const char* cA = (const char*)g.A + (size_t)cur.pm * tstep; const char* cB = (const char*)g.Bt + (size_t)cur.pn * tstep;
;     PG8_STAGE(PG8_SB(0, 0), cB, voffB); PG8_STAGE(PG8_SB(0, 1), cB + hstep, voffB); PG8_STAGE(PG8_SA(0, 0), cA, voffA); PG8_STAGE(PG8_SA(0, 1), cA + hstep, voffA);
;     if (wr == 1) PG8_BAR;
;     PG8_WAIT_V(2); PG8_BAR;
;     PG8_STAGE(PG8_SB(1, 0), cB + kstep, voffB); PG8_STAGE(PG8_SA(1, 0), cA + kstep, voffA); PG8_STAGE(PG8_SB(1, 1), cB + hstep + kstep, voffB);
;     PG8_WAIT_V(6); PG8_BAR;
.LBB0_841:
	s_nop 0
	v_readlane_b32 s2, v238, 21
	v_readlane_b32 s3, v238, 22
	s_cmp_lt_i32 s2, 11
	s_cselect_b64 s[0:1], -1, 0
	s_cmp_gt_i32 s3, 10
	s_cselect_b64 s[2:3], -1, 0
	s_and_b64 s[0:1], s[0:1], s[2:3]
	s_andn2_b64 vcc, exec, s[0:1]
	s_cbranch_vccnz .LBB0_915
	v_and_b32_e32 v150, 0x3ff, v0
	s_cmpk_gt_i32 s92, 0xaff
	v_readfirstlane_b32 s1, v150
	s_cbranch_scc1 .LBB0_858
	v_lshrrev_b32_e32 v2, 5, v150
	v_lshrrev_b32_e32 v4, 1, v150
	v_and_b32_e32 v2, 4, v2
	v_bfe_u32 v3, v150, 2, 2
	v_and_b32_e32 v13, 24, v4
	v_or3_b32 v2, v2, v3, v13
	v_lshlrev_b32_e32 v3, 4, v150
	v_add_u32_e32 v10, 0x2000, v3
	v_lshrrev_b32_e32 v4, 7, v10
	s_movk_i32 s0, 0xe0
	v_and_b32_e32 v6, 32, v150
	s_add_u32 s26, s86, 0x3000000
	v_and_or_b32 v5, v4, s0, v2
	v_bitop3_b32 v11, v3, v6, 48 bitop3:0x6c
	v_and_b32_e32 v12, 64, v150
	v_bfe_u32 v14, v150, 2, 4
	s_movk_i32 s0, 0xf0
	s_addc_u32 s27, s87, 0
	v_or_b32_e32 v3, v11, v12
	v_and_or_b32 v4, v4, s0, v14
	s_add_u32 s28, s86, 0x1b00000
	v_lshl_or_b32 v132, v4, 11, v3
	v_lshrrev_b32_e32 v4, 3, v150
	s_movk_i32 s0, 0x60
	s_addc_u32 s29, s87, 0
	v_and_or_b32 v2, v4, s0, v2
	s_movk_i32 s0, 0x70
	s_ashr_i32 s31, s92, 31
	v_lshl_or_b32 v134, v2, 11, v3
	v_and_or_b32 v2, v4, s0, v14
	s_lshr_b32 s0, s31, 29
	s_add_i32 s0, s92, s0
	s_lshr_b32 s6, s1, 6
	s_ashr_i32 s2, s0, 3
	s_and_b32 s0, s0, -8
	s_lshr_b32 s8, s1, 8
	s_lshl_b32 s30, s6, 10
	s_sub_i32 s0, s92, s0
	s_cmp_lt_i32 s0, 0
	s_movk_i32 s33, 0x161
	s_cselect_b32 s3, s33, 0x160
	s_mul_i32 s0, s0, s3
	s_add_i32 s0, s0, s2
	s_mul_hi_i32 s2, s0, 0x2e8ba2e9
	s_lshr_b32 s3, s2, 31
	s_ashr_i32 s2, s2, 5
	s_add_i32 s2, s2, s3
	s_lshl_b32 s3, s2, 3
	s_mulk_i32 s2, 0xb0
	s_sub_i32 s2, s0, s2
	s_sext_i32_i16 s0, s2
	s_bfe_u32 s0, s0, 0x3001c
	s_add_i32 s4, s2, s0
	s_sext_i32_i16 s0, s4
	s_and_b32 s4, s4, 0xfff8
	s_sub_i32 s2, s2, s4
	s_sext_i32_i16 s2, s2
	s_lshr_b32 s0, s0, 3
	s_add_i32 s18, s3, s2
	s_ashr_i32 s19, s18, 31
	s_bfe_i64 s[4:5], s[0:1], 0x100000
	s_lshl_b64 s[2:3], s[18:19], 19
	s_lshl_b64 s[4:5], s[4:5], 19
	s_add_u32 s22, s28, s4
	s_addc_u32 s23, s29, s5
	s_add_i32 s19, s30, 0
	s_add_i32 m0, s19, 0x10000
	v_lshl_or_b32 v130, v5, 11, v3
	global_load_lds_dwordx4 v134, s[22:23]
	s_add_i32 m0, s19, 0x12000
	s_add_u32 s4, s22, 0x40000
	global_load_lds_dwordx4 v130, s[22:23]
	s_addc_u32 s5, s23, 0
	s_add_i32 m0, s19, 0x14000
	v_lshl_or_b32 v136, v2, 11, v3
	global_load_lds_dwordx4 v134, s[4:5]
	s_add_i32 m0, s19, 0x16000
	s_add_u32 s20, s26, s2
	s_addc_u32 s21, s27, s3
	s_add_i32 s34, s19, 0x2000
	global_load_lds_dwordx4 v130, s[4:5]
	s_mov_b32 m0, s19
	s_add_u32 s2, s20, 0x40000
	global_load_lds_dwordx4 v136, s[20:21]
	s_mov_b32 m0, s34
	s_addc_u32 s3, s21, 0
	s_add_i32 s35, s19, 0x4000
	global_load_lds_dwordx4 v132, s[20:21]
	s_mov_b32 m0, s35
	s_waitcnt lgkmcnt(0)
	s_add_i32 s36, s19, 0x6000
	global_load_lds_dwordx4 v136, s[2:3]
	s_mov_b32 m0, s36
	v_mov_b32_e32 v135, 0
	global_load_lds_dwordx4 v132, s[2:3]
	v_mov_b32_e32 v131, v135
	v_mov_b32_e32 v137, v135
	v_mov_b32_e32 v133, v135
	s_cmp_eq_u32 s8, 1
	s_mov_b32 s37, 0
	v_lshl_add_u64 v[8:9], s[22:23], 0, v[134:135]
	v_lshl_add_u64 v[6:7], s[22:23], 0, v[130:131]
	v_lshl_add_u64 v[2:3], s[20:21], 0, v[136:137]
	s_cselect_b64 s[2:3], -1, 0
	s_cmp_lg_u32 s8, 1
	v_lshl_add_u64 v[4:5], s[20:21], 0, v[132:133]
	s_cbranch_scc1 .LBB0_845
	s_barrier
	s_setprio 1

; #define PG8_STAGE(bufoff, gbase, voff) do { _Pragma("unroll") for (int _i = 0; _i < 2; ++_i) \
;         __builtin_amdgcn_global_load_lds((const unsigned*)((const char*)(gbase) + (voff)[_i]), (LAS unsigned*)(lds + (bufoff) + ldsw + _i * 8192), 16, 0, 0); } while (0)
; #define PG8_LDA(dst, b, h) do { _Pragma("unroll") for (int m = 0; m < 4; ++m) _Pragma("unroll") for (int k = 0; k < 2; ++k) dst[m][k] = *(const LAS bf16x8*)(lds + PG8_SA(b, h) + aoff + m * 2048 + k * 1024); } while (0)
; #define PG8_LDB(dst, b, h) do { _Pragma("unroll") for (int n = 0; n < 2; ++n) _Pragma("unroll") for (int k = 0; k < 2; ++k) dst[n][k] = *(const LAS bf16x8*)(lds + PG8_SB(b, h) + boff + n * 2048 + k * 1024); } while (0)
; #define PG8_MMA(ai, bj, At, Bt) do { __builtin_amdgcn_s_setprio(1); _Pragma("unroll") for (int m = 0; m < 4; ++m) _Pragma("unroll") for (int n = 0; n < 2; ++n) _Pragma("unroll") for (int k = 0; k < 2; ++k) \
;         acc[ai][bj][m][n] = __builtin_amdgcn_mfma_f32_16x16x32_bf16(Bt[n][k], At[m][k], acc[ai][bj][m][n], 0, 0, 0); __builtin_amdgcn_s_setprio(0); } while (0)
; #define PG8_WAIT_V(n) asm volatile("s_waitcnt vmcnt(" #n ")" ::: "memory")
; #define PG8_WAIT_L(n) asm volatile("s_waitcnt lgkmcnt(" #n ")" ::: "memory")
; #define PG8_BAR __builtin_amdgcn_s_barrier()
; #define PG8_SCHED __builtin_amdgcn_sched_barrier(0)
; template <class Epi>
; __device__ __forceinline__ void gemm_phase(LAS unsigned char* lds, const Gemm g, const StaticOrder& S, const Epi& E) {
;     ...
;         for (int t = 0; t < nt; t += 2) {
;             const bool last = (t == nt - 2);
;             const char* a1 = cA + (size_t)(t + 1) * kstep;
;             const char* a2 = last ? nA : cA + (size_t)(t + 2) * kstep; const char* b2 = last ? nB : cB + (size_t)(t + 2) * kstep;
;             const char* a3 = a2 + kstep; const char* b3 = b2 + kstep;
;             PG8_LDB(B0, 0, 0); PG8_LDB(B1, 0, 1); PG8_SCHED; PG8_LDA(At, 0, 0); PG8_STAGE(PG8_SA(1, 1), a1 + hstep, voffA);
;             PG8_WAIT_V(8); PG8_WAIT_L(0); PG8_BAR; PG8_MMA(0, 0, At, B0); PG8_MMA(0, 1, At, B1); PG8_BAR; PG8_SCHED;
;             PG8_LDA(At, 0, 1); PG8_STAGE(PG8_SB(0, 0), b2, voffB); PG8_STAGE(PG8_SB(0, 1), b2 + hstep, voffB); PG8_STAGE(PG8_SA(0, 0), a2, voffA);
.LBB0_851:
	ds_read_b128 v[146:149], v154
	ds_read_b128 v[158:161], v154 offset:1024
	ds_read_b128 v[162:165], v154 offset:2048
	ds_read_b128 v[166:169], v154 offset:3072
	ds_read_b128 v[170:173], v155
	ds_read_b128 v[174:177], v155 offset:1024
	ds_read_b128 v[178:181], v155 offset:2048
	ds_read_b128 v[182:185], v155 offset:3072
	s_add_u32 s22, s20, 0xfffc0080
	s_addc_u32 s23, s21, -1
	s_cmp_eq_u32 s49, 12
	s_cselect_b32 s25, s13, s23
	s_cselect_b32 s24, s45, s22
	s_cselect_b32 s23, s11, s48
	s_cselect_b32 s22, s46, s47
	v_lshl_add_u64 v[218:219], s[20:21], 0, v[138:139]
	s_add_i32 m0, s19, 0xc000
	ds_read_b128 v[186:189], v156
	ds_read_b128 v[190:193], v156 offset:1024
	ds_read_b128 v[194:197], v156 offset:2048
	ds_read_b128 v[198:201], v156 offset:3072
	ds_read_b128 v[202:205], v156 offset:4096
	ds_read_b128 v[206:209], v156 offset:5120
	ds_read_b128 v[210:213], v156 offset:6144
	ds_read_b128 v[214:217], v156 offset:7168
	global_load_lds_dwordx4 v[218:219], off
	v_lshl_add_u64 v[218:219], s[20:21], 0, v[140:141]
	s_add_i32 m0, s19, 0xe000
	s_nop 0
	global_load_lds_dwordx4 v[218:219], off
	s_waitcnt vmcnt(8)
	s_waitcnt lgkmcnt(0)
	s_barrier
	s_waitcnt lgkmcnt(0)
	v_mfma_f32_16x16x32_bf16 v[126:129], v[146:149], v[186:189], v[126:129]
	v_mfma_f32_16x16x32_bf16 v[118:121], v[162:165], v[186:189], v[118:121]
	v_mfma_f32_16x16x32_bf16 v[110:113], v[146:149], v[194:197], v[110:113]
	v_mfma_f32_16x16x32_bf16 v[102:105], v[162:165], v[194:197], v[102:105]
	v_mfma_f32_16x16x32_bf16 v[94:97], v[146:149], v[202:205], v[94:97]
	v_mfma_f32_16x16x32_bf16 v[86:89], v[162:165], v[202:205], v[86:89]
	v_mfma_f32_16x16x32_bf16 v[78:81], v[146:149], v[210:213], v[78:81]
	v_mfma_f32_16x16x32_bf16 v[70:73], v[162:165], v[210:213], v[70:73]
	v_mfma_f32_16x16x32_bf16 v[126:129], v[158:161], v[190:193], v[126:129]
	v_mfma_f32_16x16x32_bf16 v[118:121], v[166:169], v[190:193], v[118:121]
	v_mfma_f32_16x16x32_bf16 v[110:113], v[158:161], v[198:201], v[110:113]
	v_mfma_f32_16x16x32_bf16 v[102:105], v[166:169], v[198:201], v[102:105]
	v_mfma_f32_16x16x32_bf16 v[94:97], v[158:161], v[206:209], v[94:97]
	v_mfma_f32_16x16x32_bf16 v[86:89], v[166:169], v[206:209], v[86:89]
	v_mfma_f32_16x16x32_bf16 v[78:81], v[158:161], v[214:217], v[78:81]
	v_mfma_f32_16x16x32_bf16 v[70:73], v[166:169], v[214:217], v[70:73]
	v_mfma_f32_16x16x32_bf16 v[122:125], v[170:173], v[186:189], v[122:125]
	v_mfma_f32_16x16x32_bf16 v[114:117], v[178:181], v[186:189], v[114:117]
	v_mfma_f32_16x16x32_bf16 v[106:109], v[170:173], v[194:197], v[106:109]
	v_mfma_f32_16x16x32_bf16 v[98:101], v[178:181], v[194:197], v[98:101]
	v_mfma_f32_16x16x32_bf16 v[90:93], v[170:173], v[202:205], v[90:93]
	v_mfma_f32_16x16x32_bf16 v[82:85], v[178:181], v[202:205], v[82:85]
	v_mfma_f32_16x16x32_bf16 v[74:77], v[170:173], v[210:213], v[74:77]
	v_mfma_f32_16x16x32_bf16 v[66:69], v[178:181], v[210:213], v[66:69]
	v_mfma_f32_16x16x32_bf16 v[122:125], v[174:177], v[190:193], v[122:125]
	v_mfma_f32_16x16x32_bf16 v[114:117], v[182:185], v[190:193], v[114:117]
	v_mfma_f32_16x16x32_bf16 v[106:109], v[174:177], v[198:201], v[106:109]
	v_mfma_f32_16x16x32_bf16 v[98:101], v[182:185], v[198:201], v[98:101]
	v_mfma_f32_16x16x32_bf16 v[90:93], v[174:177], v[206:209], v[90:93]
	v_mfma_f32_16x16x32_bf16 v[82:85], v[182:185], v[206:209], v[82:85]
	v_mfma_f32_16x16x32_bf16 v[74:77], v[174:177], v[214:217], v[74:77]
	v_mfma_f32_16x16x32_bf16 v[66:69], v[182:185], v[214:217], v[66:69]
	s_barrier
	s_add_i32 s50, s41, s30
	v_lshl_add_u64 v[218:219], s[22:23], 0, v[134:135]
	s_mov_b32 m0, s50
	ds_read_b128 v[186:189], v156 offset:16384
	ds_read_b128 v[190:193], v156 offset:17408
	ds_read_b128 v[194:197], v156 offset:18432
	ds_read_b128 v[198:201], v156 offset:19456
	ds_read_b128 v[202:205], v156 offset:20480
	ds_read_b128 v[206:209], v156 offset:21504
	ds_read_b128 v[210:213], v156 offset:22528
	ds_read_b128 v[214:217], v156 offset:23552
	global_load_lds_dwordx4 v[218:219], off
	s_add_i32 m0, s50, 0x2000
	s_add_u32 s50, s22, 0x40000
	v_lshl_add_u64 v[220:221], s[22:23], 0, v[130:131]
	s_addc_u32 s51, s23, 0
	s_add_i32 s52, s42, s30
	global_load_lds_dwordx4 v[220:221], off
	v_lshl_add_u64 v[222:223], s[50:51], 0, v[134:135]
	s_mov_b32 m0, s52
	v_lshl_add_u64 v[224:225], s[24:25], 0, v[132:133]
	global_load_lds_dwordx4 v[222:223], off
	v_lshl_add_u64 v[222:223], s[50:51], 0, v[130:131]
	s_add_i32 m0, s52, 0x2000
	s_nop 0
	global_load_lds_dwordx4 v[222:223], off
	v_lshl_add_u64 v[222:223], s[24:25], 0, v[136:137]
	s_mov_b32 m0, s19
	s_nop 0
	global_load_lds_dwordx4 v[222:223], off
	s_mov_b32 m0, s34
	s_nop 0
	global_load_lds_dwordx4 v[224:225], off
	s_waitcnt vmcnt(8)
	s_waitcnt lgkmcnt(0)
	s_barrier
; #define PG8_STAGE(bufoff, gbase, voff) do { _Pragma("unroll") for (int _i = 0; _i < 2; ++_i) \
;         __builtin_amdgcn_global_load_lds((const unsigned*)((const char*)(gbase) + (voff)[_i]), (LAS unsigned*)(lds + (bufoff) + ldsw + _i * 8192), 16, 0, 0); } while (0)
; #define PG8_LDA(dst, b, h) do { _Pragma("unroll") for (int m = 0; m < 4; ++m) _Pragma("unroll") for (int k = 0; k < 2; ++k) dst[m][k] = *(const LAS bf16x8*)(lds + PG8_SA(b, h) + aoff + m * 2048 + k * 1024); } while (0)
; #define PG8_LDB(dst, b, h) do { _Pragma("unroll") for (int n = 0; n < 2; ++n) _Pragma("unroll") for (int k = 0; k < 2; ++k) dst[n][k] = *(const LAS bf16x8*)(lds + PG8_SB(b, h) + boff + n * 2048 + k * 1024); } while (0)
; #define PG8_MMA(ai, bj, At, Bt) do { __builtin_amdgcn_s_setprio(1); _Pragma("unroll") for (int m = 0; m < 4; ++m) _Pragma("unroll") for (int n = 0; n < 2; ++n) _Pragma("unroll") for (int k = 0; k < 2; ++k) \
;         acc[ai][bj][m][n] = __builtin_amdgcn_mfma_f32_16x16x32_bf16(Bt[n][k], At[m][k], acc[ai][bj][m][n], 0, 0, 0); __builtin_amdgcn_s_setprio(0); } while (0)
; #define PG8_WAIT_V(n) asm volatile("s_waitcnt vmcnt(" #n ")" ::: "memory")
; #define PG8_WAIT_L(n) asm volatile("s_waitcnt lgkmcnt(" #n ")" ::: "memory")
; #define PG8_BAR __builtin_amdgcn_s_barrier()
; #define PG8_SCHED __builtin_amdgcn_sched_barrier(0)
; template <class Epi>
; __device__ __forceinline__ void gemm_phase(LAS unsigned char* lds, const Gemm g, const StaticOrder& S, const Epi& E) {
;     ...
;             PG8_WAIT_V(8); PG8_WAIT_L(0); PG8_BAR; PG8_MMA(1, 0, At, B0); PG8_MMA(1, 1, At, B1); PG8_BAR; PG8_SCHED;
;             PG8_LDB(B0, 1, 0); PG8_LDB(B1, 1, 1); PG8_SCHED; PG8_LDA(At, 1, 0); PG8_STAGE(PG8_SA(0, 1), a2 + hstep, voffA);
;             PG8_WAIT_V(8); PG8_WAIT_L(0); PG8_BAR; PG8_MMA(0, 0, At, B0); PG8_MMA(0, 1, At, B1); PG8_BAR; PG8_SCHED;
;             PG8_LDA(At, 1, 1); PG8_STAGE(PG8_SB(1, 0), b3, voffB); PG8_STAGE(PG8_SB(1, 1), b3 + hstep, voffB); PG8_STAGE(PG8_SA(1, 0), a3, voffA);
	s_waitcnt lgkmcnt(0)
	v_mfma_f32_16x16x32_bf16 v[62:65], v[146:149], v[186:189], v[62:65]
	v_mfma_f32_16x16x32_bf16 v[54:57], v[162:165], v[186:189], v[54:57]
	v_mfma_f32_16x16x32_bf16 v[46:49], v[146:149], v[194:197], v[46:49]
	v_mfma_f32_16x16x32_bf16 v[38:41], v[162:165], v[194:197], v[38:41]
	v_mfma_f32_16x16x32_bf16 v[30:33], v[146:149], v[202:205], v[30:33]
	v_mfma_f32_16x16x32_bf16 v[22:25], v[162:165], v[202:205], v[22:25]
	v_mfma_f32_16x16x32_bf16 v[14:17], v[146:149], v[210:213], v[14:17]
	v_mfma_f32_16x16x32_bf16 v[6:9], v[162:165], v[210:213], v[6:9]
	v_mfma_f32_16x16x32_bf16 v[62:65], v[158:161], v[190:193], v[62:65]
	v_mfma_f32_16x16x32_bf16 v[54:57], v[166:169], v[190:193], v[54:57]
	v_mfma_f32_16x16x32_bf16 v[46:49], v[158:161], v[198:201], v[46:49]
	v_mfma_f32_16x16x32_bf16 v[38:41], v[166:169], v[198:201], v[38:41]
	v_mfma_f32_16x16x32_bf16 v[30:33], v[158:161], v[206:209], v[30:33]
	v_mfma_f32_16x16x32_bf16 v[22:25], v[166:169], v[206:209], v[22:25]
	v_mfma_f32_16x16x32_bf16 v[14:17], v[158:161], v[214:217], v[14:17]
	v_mfma_f32_16x16x32_bf16 v[6:9], v[166:169], v[214:217], v[6:9]
	v_mfma_f32_16x16x32_bf16 v[58:61], v[170:173], v[186:189], v[58:61]
	v_mfma_f32_16x16x32_bf16 v[50:53], v[178:181], v[186:189], v[50:53]
	v_mfma_f32_16x16x32_bf16 v[42:45], v[170:173], v[194:197], v[42:45]
	v_mfma_f32_16x16x32_bf16 v[34:37], v[178:181], v[194:197], v[34:37]
	v_mfma_f32_16x16x32_bf16 v[26:29], v[170:173], v[202:205], v[26:29]
	v_mfma_f32_16x16x32_bf16 v[18:21], v[178:181], v[202:205], v[18:21]
	v_mfma_f32_16x16x32_bf16 v[10:13], v[170:173], v[210:213], v[10:13]
	v_mfma_f32_16x16x32_bf16 v[2:5], v[178:181], v[210:213], v[2:5]
	v_mfma_f32_16x16x32_bf16 v[58:61], v[174:177], v[190:193], v[58:61]
	v_mfma_f32_16x16x32_bf16 v[50:53], v[182:185], v[190:193], v[50:53]
	v_mfma_f32_16x16x32_bf16 v[42:45], v[174:177], v[198:201], v[42:45]
	v_mfma_f32_16x16x32_bf16 v[34:37], v[182:185], v[198:201], v[34:37]
	v_mfma_f32_16x16x32_bf16 v[26:29], v[174:177], v[206:209], v[26:29]
	v_mfma_f32_16x16x32_bf16 v[18:21], v[182:185], v[206:209], v[18:21]
	v_mfma_f32_16x16x32_bf16 v[10:13], v[174:177], v[214:217], v[10:13]
	v_mfma_f32_16x16x32_bf16 v[2:5], v[182:185], v[214:217], v[2:5]
	s_barrier
	s_add_i32 s50, 0, 0x18000
	v_add_u32_e32 v157, s50, v152
	s_add_i32 s51, 0, 0x1c000
	ds_read_b128 v[146:149], v157
	ds_read_b128 v[158:161], v157 offset:1024
	ds_read_b128 v[162:165], v157 offset:2048
	ds_read_b128 v[166:169], v157 offset:3072
	v_add_u32_e32 v157, s51, v152
	ds_read_b128 v[170:173], v157
	ds_read_b128 v[174:177], v157 offset:1024
	ds_read_b128 v[178:181], v157 offset:2048
	ds_read_b128 v[182:185], v157 offset:3072
	s_add_u32 s24, s24, 0x40000
	s_addc_u32 s25, s25, 0
	s_mov_b32 m0, s35
	v_lshl_add_u64 v[226:227], s[24:25], 0, v[136:137]
	ds_read_b128 v[186:189], v156 offset:32768
	ds_read_b128 v[190:193], v156 offset:33792
	ds_read_b128 v[194:197], v156 offset:34816
	ds_read_b128 v[198:201], v156 offset:35840
	ds_read_b128 v[202:205], v156 offset:36864
	ds_read_b128 v[206:209], v156 offset:37888
	ds_read_b128 v[210:213], v156 offset:38912
	ds_read_b128 v[214:217], v156 offset:39936
	global_load_lds_dwordx4 v[226:227], off
	v_lshl_add_u64 v[226:227], s[24:25], 0, v[132:133]
	s_mov_b32 m0, s36
	s_nop 0
	global_load_lds_dwordx4 v[226:227], off
	s_waitcnt vmcnt(8)
	s_waitcnt lgkmcnt(0)
	s_barrier
	s_waitcnt lgkmcnt(0)
	v_mfma_f32_16x16x32_bf16 v[126:129], v[146:149], v[186:189], v[126:129]
	v_mfma_f32_16x16x32_bf16 v[118:121], v[162:165], v[186:189], v[118:121]
	v_mfma_f32_16x16x32_bf16 v[110:113], v[146:149], v[194:197], v[110:113]
	v_mfma_f32_16x16x32_bf16 v[102:105], v[162:165], v[194:197], v[102:105]
	v_mfma_f32_16x16x32_bf16 v[94:97], v[146:149], v[202:205], v[94:97]
	v_mfma_f32_16x16x32_bf16 v[86:89], v[162:165], v[202:205], v[86:89]
	v_mfma_f32_16x16x32_bf16 v[78:81], v[146:149], v[210:213], v[78:81]
	v_mfma_f32_16x16x32_bf16 v[70:73], v[162:165], v[210:213], v[70:73]
	v_mfma_f32_16x16x32_bf16 v[126:129], v[158:161], v[190:193], v[126:129]
	v_mfma_f32_16x16x32_bf16 v[118:121], v[166:169], v[190:193], v[118:121]
	v_mfma_f32_16x16x32_bf16 v[110:113], v[158:161], v[198:201], v[110:113]
	v_mfma_f32_16x16x32_bf16 v[102:105], v[166:169], v[198:201], v[102:105]
	v_mfma_f32_16x16x32_bf16 v[94:97], v[158:161], v[206:209], v[94:97]
	v_mfma_f32_16x16x32_bf16 v[86:89], v[166:169], v[206:209], v[86:89]
	v_mfma_f32_16x16x32_bf16 v[78:81], v[158:161], v[214:217], v[78:81]
	v_mfma_f32_16x16x32_bf16 v[70:73], v[166:169], v[214:217], v[70:73]
	v_mfma_f32_16x16x32_bf16 v[122:125], v[170:173], v[186:189], v[122:125]
	v_mfma_f32_16x16x32_bf16 v[114:117], v[178:181], v[186:189], v[114:117]
	v_mfma_f32_16x16x32_bf16 v[106:109], v[170:173], v[194:197], v[106:109]
	v_mfma_f32_16x16x32_bf16 v[98:101], v[178:181], v[194:197], v[98:101]
	v_mfma_f32_16x16x32_bf16 v[90:93], v[170:173], v[202:205], v[90:93]
	v_mfma_f32_16x16x32_bf16 v[82:85], v[178:181], v[202:205], v[82:85]
	v_mfma_f32_16x16x32_bf16 v[74:77], v[170:173], v[210:213], v[74:77]
	v_mfma_f32_16x16x32_bf16 v[66:69], v[178:181], v[210:213], v[66:69]
	v_mfma_f32_16x16x32_bf16 v[122:125], v[174:177], v[190:193], v[122:125]
	v_mfma_f32_16x16x32_bf16 v[114:117], v[182:185], v[190:193], v[114:117]
	v_mfma_f32_16x16x32_bf16 v[106:109], v[174:177], v[198:201], v[106:109]
	v_mfma_f32_16x16x32_bf16 v[98:101], v[182:185], v[198:201], v[98:101]
	v_mfma_f32_16x16x32_bf16 v[90:93], v[174:177], v[206:209], v[90:93]
	v_mfma_f32_16x16x32_bf16 v[82:85], v[182:185], v[206:209], v[82:85]
	v_mfma_f32_16x16x32_bf16 v[74:77], v[174:177], v[214:217], v[74:77]
	v_mfma_f32_16x16x32_bf16 v[66:69], v[182:185], v[214:217], v[66:69]
	s_barrier
; #define PG8_STAGE(bufoff, gbase, voff) do { _Pragma("unroll") for (int _i = 0; _i < 2; ++_i) \
;         __builtin_amdgcn_global_load_lds((const unsigned*)((const char*)(gbase) + (voff)[_i]), (LAS unsigned*)(lds + (bufoff) + ldsw + _i * 8192), 16, 0, 0); } while (0)
; #define PG8_LDA(dst, b, h) do { _Pragma("unroll") for (int m = 0; m < 4; ++m) _Pragma("unroll") for (int k = 0; k < 2; ++k) dst[m][k] = *(const LAS bf16x8*)(lds + PG8_SA(b, h) + aoff + m * 2048 + k * 1024); } while (0)
; #define PG8_MMA(ai, bj, At, Bt) do { __builtin_amdgcn_s_setprio(1); _Pragma("unroll") for (int m = 0; m < 4; ++m) _Pragma("unroll") for (int n = 0; n < 2; ++n) _Pragma("unroll") for (int k = 0; k < 2; ++k) \
;         acc[ai][bj][m][n] = __builtin_amdgcn_mfma_f32_16x16x32_bf16(Bt[n][k], At[m][k], acc[ai][bj][m][n], 0, 0, 0); __builtin_amdgcn_s_setprio(0); } while (0)
; #define PG8_WAIT_V(n) asm volatile("s_waitcnt vmcnt(" #n ")" ::: "memory")
; #define PG8_WAIT_L(n) asm volatile("s_waitcnt lgkmcnt(" #n ")" ::: "memory")
; #define PG8_BAR __builtin_amdgcn_s_barrier()
; #define PG8_SCHED __builtin_amdgcn_sched_barrier(0)
; template <class Epi>
; __device__ __forceinline__ void gemm_phase(LAS unsigned char* lds, const Gemm g, const StaticOrder& S, const Epi& E) {
;     ...
;             PG8_LDA(At, 1, 1); PG8_STAGE(PG8_SB(1, 0), b3, voffB); PG8_STAGE(PG8_SB(1, 1), b3 + hstep, voffB); PG8_STAGE(PG8_SA(1, 0), a3, voffA);
;             PG8_WAIT_V(8); PG8_WAIT_L(0); PG8_BAR; PG8_MMA(1, 0, At, B0); PG8_MMA(1, 1, At, B1); PG8_BAR; PG8_SCHED;
;         }
;         if (wr == 0) PG8_BAR;
	s_add_i32 s24, s50, s30
	v_lshl_add_u64 v[218:219], v[218:219], 0, s[6:7]
	s_mov_b32 m0, s24
	ds_read_b128 v[186:189], v156 offset:49152
	ds_read_b128 v[190:193], v156 offset:50176
	ds_read_b128 v[194:197], v156 offset:51200
	ds_read_b128 v[198:201], v156 offset:52224
	ds_read_b128 v[202:205], v156 offset:53248
	ds_read_b128 v[206:209], v156 offset:54272
	ds_read_b128 v[210:213], v156 offset:55296
	ds_read_b128 v[214:217], v156 offset:56320
	global_load_lds_dwordx4 v[218:219], off
	s_add_i32 m0, s24, 0x2000
	s_add_u32 s22, s22, 0x40080
	v_lshl_add_u64 v[218:219], v[220:221], 0, s[6:7]
	s_addc_u32 s23, s23, 0
	s_add_i32 s24, s51, s30
	global_load_lds_dwordx4 v[218:219], off
	v_lshl_add_u64 v[218:219], s[22:23], 0, v[134:135]
	s_mov_b32 m0, s24
	s_nop 0
	global_load_lds_dwordx4 v[218:219], off
	v_lshl_add_u64 v[218:219], s[22:23], 0, v[130:131]
	s_add_i32 m0, s24, 0x2000
	s_nop 0
	global_load_lds_dwordx4 v[218:219], off
	v_lshl_add_u64 v[218:219], v[222:223], 0, s[6:7]
	s_mov_b32 m0, s38
	s_nop 0
	global_load_lds_dwordx4 v[218:219], off
	v_lshl_add_u64 v[218:219], v[224:225], 0, s[6:7]
	s_mov_b32 m0, s39
	s_nop 0
	global_load_lds_dwordx4 v[218:219], off
	s_waitcnt vmcnt(8)
	s_waitcnt lgkmcnt(0)
	s_barrier
	s_waitcnt lgkmcnt(0)
	v_mfma_f32_16x16x32_bf16 v[62:65], v[146:149], v[186:189], v[62:65]
	v_mfma_f32_16x16x32_bf16 v[54:57], v[162:165], v[186:189], v[54:57]
	v_mfma_f32_16x16x32_bf16 v[46:49], v[146:149], v[194:197], v[46:49]
	v_mfma_f32_16x16x32_bf16 v[38:41], v[162:165], v[194:197], v[38:41]
	v_mfma_f32_16x16x32_bf16 v[30:33], v[146:149], v[202:205], v[30:33]
	v_mfma_f32_16x16x32_bf16 v[22:25], v[162:165], v[202:205], v[22:25]
	v_mfma_f32_16x16x32_bf16 v[14:17], v[146:149], v[210:213], v[14:17]
	v_mfma_f32_16x16x32_bf16 v[6:9], v[162:165], v[210:213], v[6:9]
	v_mfma_f32_16x16x32_bf16 v[62:65], v[158:161], v[190:193], v[62:65]
	v_mfma_f32_16x16x32_bf16 v[54:57], v[166:169], v[190:193], v[54:57]
	v_mfma_f32_16x16x32_bf16 v[46:49], v[158:161], v[198:201], v[46:49]
	v_mfma_f32_16x16x32_bf16 v[38:41], v[166:169], v[198:201], v[38:41]
	v_mfma_f32_16x16x32_bf16 v[30:33], v[158:161], v[206:209], v[30:33]
	v_mfma_f32_16x16x32_bf16 v[22:25], v[166:169], v[206:209], v[22:25]
	v_mfma_f32_16x16x32_bf16 v[14:17], v[158:161], v[214:217], v[14:17]
	v_mfma_f32_16x16x32_bf16 v[6:9], v[166:169], v[214:217], v[6:9]
	v_mfma_f32_16x16x32_bf16 v[58:61], v[170:173], v[186:189], v[58:61]
	v_mfma_f32_16x16x32_bf16 v[50:53], v[178:181], v[186:189], v[50:53]
	v_mfma_f32_16x16x32_bf16 v[42:45], v[170:173], v[194:197], v[42:45]
	v_mfma_f32_16x16x32_bf16 v[34:37], v[178:181], v[194:197], v[34:37]
	v_mfma_f32_16x16x32_bf16 v[26:29], v[170:173], v[202:205], v[26:29]
	v_mfma_f32_16x16x32_bf16 v[18:21], v[178:181], v[202:205], v[18:21]
	v_mfma_f32_16x16x32_bf16 v[10:13], v[170:173], v[210:213], v[10:13]
	v_mfma_f32_16x16x32_bf16 v[2:5], v[178:181], v[210:213], v[2:5]
	v_mfma_f32_16x16x32_bf16 v[58:61], v[174:177], v[190:193], v[58:61]
	v_mfma_f32_16x16x32_bf16 v[50:53], v[182:185], v[190:193], v[50:53]
	v_mfma_f32_16x16x32_bf16 v[42:45], v[174:177], v[198:201], v[42:45]
	v_mfma_f32_16x16x32_bf16 v[34:37], v[182:185], v[198:201], v[34:37]
	v_mfma_f32_16x16x32_bf16 v[26:29], v[174:177], v[206:209], v[26:29]
	v_mfma_f32_16x16x32_bf16 v[18:21], v[182:185], v[206:209], v[18:21]
	v_mfma_f32_16x16x32_bf16 v[10:13], v[174:177], v[214:217], v[10:13]
	v_mfma_f32_16x16x32_bf16 v[2:5], v[182:185], v[214:217], v[2:5]
	s_barrier
	s_add_i32 s49, s49, 2
	s_add_u32 s20, s20, 0x100
	s_addc_u32 s21, s21, 0
	s_add_u32 s47, s47, 0x100
	s_addc_u32 s48, s48, 0
	s_cmp_gt_u32 s49, 13
	s_cbranch_scc0 .LBB0_851
	s_and_b64 vcc, exec, s[8:9]
	s_cbranch_vccz .LBB0_854
	s_barrier

; #define SEAM(k) do { if ((k) + 1 < hi) { if ((k) == 0) { __syncthreads(); cg::this_grid().sync(); } \
;         else { if (!xposted) { if (threadIdx.x == 0) { xst[0] = 0u; xst[1] = 0u; } __syncthreads(); xbar = xcd_barrier_post((unsigned*)(ws + 65536), xst); xposted = true; } xcd_barrier(xbar); } } } while (0)
; __global__ void __launch_bounds__(512) fwd_kernel(Args a) {
;     ...
;     if (IN(10)) { pg8::Gemm g{(const bf16_t*)(ws + WS_XB), (const bf16_t*)(ws + WS_WUP2), M, NUP, D}; pg8::StaticOrder S; S.init(M, NUP, G, bx);
;                   pg8::EpiSwiGLU E{(bf16_t*)(ws + WS_BIG), FF}; pg8::gemm_phase(lds, g, S, E); SEAM(10); }
.LBB0_858:
	s_setprio 0
	v_readlane_b32 s0, v238, 21
	v_readlane_b32 s1, v238, 22
	s_cmp_lt_i32 s1, 12
	s_cbranch_scc1 .LBB0_915
	v_readlane_b32 s0, v238, 23
	v_readlane_b32 s1, v238, 24
	s_xor_b64 s[0:1], s[0:1], -1
	s_andn2_b64 vcc, exec, s[0:1]
	v_cmp_eq_u32_e64 s[0:1], 0, v150
	s_cbranch_vccnz .LBB0_866
	s_and_saveexec_b64 s[2:3], s[0:1]
	s_cbranch_execz .LBB0_862
	s_add_i32 s4, 0, 0x23ff0
	v_mov_b32_e32 v2, 0
	v_mov_b32_e32 v3, s4
	s_add_i32 s4, 0, 0x23ff4
	ds_write_b32 v3, v2
	v_mov_b32_e32 v3, s4
	ds_write_b32 v3, v2

; #define PG8_STAGE(bufoff, gbase, voff) do { _Pragma("unroll") for (int _i = 0; _i < 2; ++_i) \
;         __builtin_amdgcn_global_load_lds((const unsigned*)((const char*)(gbase) + (voff)[_i]), (LAS unsigned*)(lds + (bufoff) + ldsw + _i * 8192), 16, 0, 0); } while (0)
; #define PG8_WAIT_V(n) asm volatile("s_waitcnt vmcnt(" #n ")" ::: "memory")
; #define PG8_BAR __builtin_amdgcn_s_barrier()
; template <class Epi>
; __device__ __forceinline__ void gemm_phase(LAS unsigned char* lds, const Gemm g, const StaticOrder& S, const Epi& E) {
;     const int tid = threadIdx.x, wid = __builtin_amdgcn_readfirstlane(tid >> 6), lane = tid & 63, wr = wid >> 2, wc = wid & 3, fr = lane & 15, fq = lane >> 4;
;     const int K = g.K, nt = K / BK;
;     unsigned voffA[2], voffB[2];
; #pragma unroll
;     for (int i = 0; i < 2; ++i) { int R, C; stage_rc(tid * 16 + i * 8192, R, C); const int Rb = Epi::PERM ? ((R & ~31) + perm32(R & 31)) : R;
;         voffA[i] = (unsigned)(R * K + C) * 2u; voffB[i] = (unsigned)(Rb * K + C) * 2u; }
;     const size_t kstep = (size_t)(BK * 2);
;     const size_t hstep = (size_t)HALF * K * 2;
;     const size_t tstep = 2 * hstep;
;     const unsigned ldsw = (unsigned)wid * 1024u;
;     const int aoff = lds_byte(wr * 64 + fr, fq * 8), boff = lds_byte(wc * 32 + fr, fq * 8);
;     ...
;     Unit cur, nxt; int ui = 0;
;     if (!S.next(0, cur)) return;
;     f32x4 acc[2][2][4][2];
; #pragma unroll
;     for (int a = 0; a < 2; ++a)
; #pragma unroll
;         for (int b = 0; b < 2; ++b)
; #pragma unroll
;             for (int m = 0; m < 4; ++m)
; #pragma unroll
;                 for (int n = 0; n < 2; ++n) acc[a][b][m][n] = (f32x4){0.f, 0.f, 0.f, 0.f};
;     bf16x8 At[4][2], B0[2][2], B1[2][2];
;     const char* cA = (const char*)g.A + (size_t)cur.pm * tstep; const char* cB = (const char*)g.Bt + (size_t)cur.pn * tstep;
;     PG8_STAGE(PG8_SB(0, 0), cB, voffB); PG8_STAGE(PG8_SB(0, 1), cB + hstep, voffB); PG8_STAGE(PG8_SA(0, 0), cA, voffA); PG8_STAGE(PG8_SA(0, 1), cA + hstep, voffA);
;     if (wr == 1) PG8_BAR;
;     PG8_WAIT_V(2); PG8_BAR;
;     PG8_STAGE(PG8_SB(1, 0), cB + kstep, voffB); PG8_STAGE(PG8_SA(1, 0), cA + kstep, voffA); PG8_STAGE(PG8_SB(1, 1), cB + hstep + kstep, voffB);
;     PG8_WAIT_V(6); PG8_BAR;
.LBB0_921:
	s_add_u32 s28, s86, 0x7000000
	s_addc_u32 s29, s87, 0
	s_add_u32 s30, s86, 0x2600000
	s_addc_u32 s31, s87, 0
	s_add_i32 s1, s2, s1
	v_lshlrev_b32_e32 v2, 4, v192
	v_and_b32_e32 v3, 32, v192
	s_ashr_i32 s2, s1, 31
	v_bfe_u32 v4, v192, 2, 4
	v_bitop3_b32 v10, v2, v3, 48 bitop3:0x6c
	v_lshrrev_b32_e32 v5, 3, v192
	s_movk_i32 s3, 0x70
	v_add_u32_e32 v2, 0x2000, v2
	s_lshr_b32 s2, s2, 27
	v_and_or_b32 v5, v5, s3, v4
	v_lshrrev_b32_e32 v2, 7, v2
	s_movk_i32 s3, 0xf0
	s_add_i32 s2, s1, s2
	v_and_or_b32 v2, v2, s3, v4
	s_ashr_i32 s3, s2, 5
	s_and_b32 s2, s2, 0xffe0
	s_sub_i32 s2, s1, s2
	s_bfe_i32 s1, s2, 0x80000
	s_bfe_u32 s1, s1, 0x3000c
	s_add_i32 s6, s2, s1
	s_bfe_i32 s1, s6, 0x80000
	s_and_b32 s6, s6, 0xf8
	s_sub_i32 s2, s2, s6
	s_lshl_b32 s3, s3, 3
	s_sext_i32_i16 s7, s1
	s_sext_i32_i8 s2, s2
	s_lshr_b32 s5, s4, 6
	s_waitcnt lgkmcnt(0)
	s_add_i32 s50, s3, s2
	s_ashr_i32 s2, s7, 3
	s_lshr_b32 s0, s4, 8
	s_lshl_b32 s33, s5, 10
	s_lshr_b32 s1, s7, 3
	s_mul_hi_i32 s3, s2, 0x160000
	s_mul_i32 s2, s2, 0x160000
	v_and_b32_e32 v11, 64, v192
	s_add_u32 s24, s30, s2
	v_or_b32_e32 v3, v10, v11
	v_mul_u32_u24_e32 v12, 0x1600, v5
	s_addc_u32 s25, s31, s3
	s_add_i32 s34, s33, 0
	v_or_b32_e32 v170, v12, v3
	s_add_i32 m0, s34, 0x10000
	v_mul_u32_u24_e32 v13, 0x1600, v2
	global_load_lds_dwordx4 v170, s[24:25]
	s_add_i32 m0, s34, 0x12000
	v_or_b32_e32 v172, v13, v3
	s_add_u32 s2, s24, 0xb0000
	global_load_lds_dwordx4 v172, s[24:25]
	s_addc_u32 s3, s25, 0
	s_add_i32 m0, s34, 0x14000
	s_mul_i32 s8, s50, 0x160000
	global_load_lds_dwordx4 v170, s[2:3]
	s_add_i32 m0, s34, 0x16000
	s_mul_hi_i32 s6, s50, 0x160000
	s_add_u32 s22, s28, s8
	s_addc_u32 s23, s29, s6
	s_add_i32 s35, s34, 0x2000
	global_load_lds_dwordx4 v172, s[2:3]
	s_mov_b32 m0, s34
	s_add_u32 s2, s22, 0xb0000
	global_load_lds_dwordx4 v170, s[22:23]
	s_mov_b32 m0, s35
	s_addc_u32 s3, s23, 0
	s_add_i32 s36, s34, 0x4000
	global_load_lds_dwordx4 v172, s[22:23]
	s_mov_b32 m0, s36
	s_add_i32 s37, s34, 0x6000
	global_load_lds_dwordx4 v170, s[2:3]
	s_mov_b32 m0, s37
	v_mov_b32_e32 v171, 0
	global_load_lds_dwordx4 v172, s[2:3]
	v_mov_b32_e32 v173, v171
	s_cmp_eq_u32 s0, 1
	s_mov_b32 s38, 0
	v_lshl_add_u64 v[8:9], s[24:25], 0, v[170:171]
	v_lshl_add_u64 v[6:7], s[24:25], 0, v[172:173]
	s_mov_b64 s[2:3], 0xb0000
	v_lshl_add_u64 v[2:3], s[22:23], 0, v[170:171]
	s_cselect_b64 s[6:7], -1, 0
	s_cmp_lg_u32 s0, 1
	v_lshl_add_u64 v[4:5], s[22:23], 0, v[172:173]
	s_cbranch_scc1 .LBB0_923
	s_barrier
	s_setprio 1

; #define PG8_STAGE(bufoff, gbase, voff) do { _Pragma("unroll") for (int _i = 0; _i < 2; ++_i) \
;         __builtin_amdgcn_global_load_lds((const unsigned*)((const char*)(gbase) + (voff)[_i]), (LAS unsigned*)(lds + (bufoff) + ldsw + _i * 8192), 16, 0, 0); } while (0)
; #define PG8_LDA(dst, b, h) do { _Pragma("unroll") for (int m = 0; m < 4; ++m) _Pragma("unroll") for (int k = 0; k < 2; ++k) dst[m][k] = *(const LAS bf16x8*)(lds + PG8_SA(b, h) + aoff + m * 2048 + k * 1024); } while (0)
; #define PG8_LDB(dst, b, h) do { _Pragma("unroll") for (int n = 0; n < 2; ++n) _Pragma("unroll") for (int k = 0; k < 2; ++k) dst[n][k] = *(const LAS bf16x8*)(lds + PG8_SB(b, h) + boff + n * 2048 + k * 1024); } while (0)
; #define PG8_MMA(ai, bj, At, Bt) do { __builtin_amdgcn_s_setprio(1); _Pragma("unroll") for (int m = 0; m < 4; ++m) _Pragma("unroll") for (int n = 0; n < 2; ++n) _Pragma("unroll") for (int k = 0; k < 2; ++k) \
;         acc[ai][bj][m][n] = __builtin_amdgcn_mfma_f32_16x16x32_bf16(Bt[n][k], At[m][k], acc[ai][bj][m][n], 0, 0, 0); __builtin_amdgcn_s_setprio(0); } while (0)
; #define PG8_WAIT_V(n) asm volatile("s_waitcnt vmcnt(" #n ")" ::: "memory")
; #define PG8_WAIT_L(n) asm volatile("s_waitcnt lgkmcnt(" #n ")" ::: "memory")
; #define PG8_BAR __builtin_amdgcn_s_barrier()
; #define PG8_SCHED __builtin_amdgcn_sched_barrier(0)
; template <class Epi>
; __device__ __forceinline__ void gemm_phase(LAS unsigned char* lds, const Gemm g, const StaticOrder& S, const Epi& E) {
;     ...
;         for (int t = 0; t < nt; t += 2) {
;             const bool last = (t == nt - 2);
;             const char* a1 = cA + (size_t)(t + 1) * kstep;
;             const char* a2 = last ? nA : cA + (size_t)(t + 2) * kstep; const char* b2 = last ? nB : cB + (size_t)(t + 2) * kstep;
;             const char* a3 = a2 + kstep; const char* b3 = b2 + kstep;
;             PG8_LDB(B0, 0, 0); PG8_LDB(B1, 0, 1); PG8_SCHED; PG8_LDA(At, 0, 0); PG8_STAGE(PG8_SA(1, 1), a1 + hstep, voffA);
;             PG8_WAIT_V(8); PG8_WAIT_L(0); PG8_BAR; PG8_MMA(0, 0, At, B0); PG8_MMA(0, 1, At, B1); PG8_BAR; PG8_SCHED;
;             PG8_LDA(At, 0, 1); PG8_STAGE(PG8_SB(0, 0), b2, voffB); PG8_STAGE(PG8_SB(0, 1), b2 + hstep, voffB); PG8_STAGE(PG8_SA(0, 0), a2, voffA);
.LBB0_937:
	ds_read_b128 v[130:133], v196
	ds_read_b128 v[134:137], v196 offset:1024
	ds_read_b128 v[138:141], v196 offset:2048
	ds_read_b128 v[142:145], v196 offset:3072
	ds_read_b128 v[146:149], v197
	ds_read_b128 v[150:153], v197 offset:1024
	ds_read_b128 v[154:157], v197 offset:2048
	ds_read_b128 v[158:161], v197 offset:3072
	s_add_u32 s24, s22, 0xfff50080
	s_addc_u32 s25, s23, -1
	s_cmp_eq_u32 s54, 40
	s_cselect_b32 s27, s5, s25
	s_cselect_b32 s26, s4, s24
	s_cselect_b32 s25, s21, s53
	s_cselect_b32 s24, s20, s52
	v_lshl_add_u64 v[190:191], s[22:23], 0, v[174:175]
	s_add_i32 m0, s34, 0xc000
	ds_read_b128 v[162:165], v198
	ds_read_b128 v[166:169], v198 offset:1024
	ds_read_b128 v[182:185], v198 offset:2048
	ds_read_b128 v[186:189], v198 offset:3072
	ds_read_b128 v[200:203], v198 offset:4096
	ds_read_b128 v[204:207], v198 offset:5120
	ds_read_b128 v[208:211], v198 offset:6144
	ds_read_b128 v[212:215], v198 offset:7168
	global_load_lds_dwordx4 v[190:191], off
	v_lshl_add_u64 v[190:191], s[22:23], 0, v[176:177]
	s_add_i32 m0, s34, 0xe000
	s_nop 0
	global_load_lds_dwordx4 v[190:191], off
	s_waitcnt vmcnt(8)
	s_waitcnt lgkmcnt(0)
	s_barrier
	s_waitcnt lgkmcnt(0)
	v_mfma_f32_16x16x32_bf16 v[126:129], v[130:133], v[162:165], v[126:129]
	v_mfma_f32_16x16x32_bf16 v[122:125], v[138:141], v[162:165], v[122:125]
	v_mfma_f32_16x16x32_bf16 v[118:121], v[130:133], v[182:185], v[118:121]
	v_mfma_f32_16x16x32_bf16 v[114:117], v[138:141], v[182:185], v[114:117]
	v_mfma_f32_16x16x32_bf16 v[94:97], v[130:133], v[200:203], v[94:97]
	v_mfma_f32_16x16x32_bf16 v[90:93], v[138:141], v[200:203], v[90:93]
	v_mfma_f32_16x16x32_bf16 v[82:85], v[130:133], v[208:211], v[82:85]
	v_mfma_f32_16x16x32_bf16 v[74:77], v[138:141], v[208:211], v[74:77]
	v_mfma_f32_16x16x32_bf16 v[126:129], v[134:137], v[166:169], v[126:129]
	v_mfma_f32_16x16x32_bf16 v[122:125], v[142:145], v[166:169], v[122:125]
	v_mfma_f32_16x16x32_bf16 v[118:121], v[134:137], v[186:189], v[118:121]
	v_mfma_f32_16x16x32_bf16 v[114:117], v[142:145], v[186:189], v[114:117]
	v_mfma_f32_16x16x32_bf16 v[94:97], v[134:137], v[204:207], v[94:97]
	v_mfma_f32_16x16x32_bf16 v[90:93], v[142:145], v[204:207], v[90:93]
	v_mfma_f32_16x16x32_bf16 v[82:85], v[134:137], v[212:215], v[82:85]
	v_mfma_f32_16x16x32_bf16 v[74:77], v[142:145], v[212:215], v[74:77]
	v_mfma_f32_16x16x32_bf16 v[110:113], v[146:149], v[162:165], v[110:113]
	v_mfma_f32_16x16x32_bf16 v[106:109], v[154:157], v[162:165], v[106:109]
	v_mfma_f32_16x16x32_bf16 v[102:105], v[146:149], v[182:185], v[102:105]
	v_mfma_f32_16x16x32_bf16 v[98:101], v[154:157], v[182:185], v[98:101]
	v_mfma_f32_16x16x32_bf16 v[86:89], v[146:149], v[200:203], v[86:89]
	v_mfma_f32_16x16x32_bf16 v[78:81], v[154:157], v[200:203], v[78:81]
	v_mfma_f32_16x16x32_bf16 v[70:73], v[146:149], v[208:211], v[70:73]
	v_mfma_f32_16x16x32_bf16 v[66:69], v[154:157], v[208:211], v[66:69]
	v_mfma_f32_16x16x32_bf16 v[110:113], v[150:153], v[166:169], v[110:113]
	v_mfma_f32_16x16x32_bf16 v[106:109], v[158:161], v[166:169], v[106:109]
	v_mfma_f32_16x16x32_bf16 v[102:105], v[150:153], v[186:189], v[102:105]
	v_mfma_f32_16x16x32_bf16 v[98:101], v[158:161], v[186:189], v[98:101]
	v_mfma_f32_16x16x32_bf16 v[86:89], v[150:153], v[204:207], v[86:89]
	v_mfma_f32_16x16x32_bf16 v[78:81], v[158:161], v[204:207], v[78:81]
	v_mfma_f32_16x16x32_bf16 v[70:73], v[150:153], v[212:215], v[70:73]
	v_mfma_f32_16x16x32_bf16 v[66:69], v[158:161], v[212:215], v[66:69]
	s_barrier
	s_add_i32 s55, s42, s33
	v_lshl_add_u64 v[190:191], s[24:25], 0, v[170:171]
	s_mov_b32 m0, s55
	ds_read_b128 v[162:165], v198 offset:16384
	ds_read_b128 v[166:169], v198 offset:17408
	ds_read_b128 v[182:185], v198 offset:18432
	ds_read_b128 v[186:189], v198 offset:19456
	ds_read_b128 v[200:203], v198 offset:20480
	ds_read_b128 v[204:207], v198 offset:21504
	ds_read_b128 v[208:211], v198 offset:22528
	ds_read_b128 v[212:215], v198 offset:23552
	global_load_lds_dwordx4 v[190:191], off
	s_add_i32 m0, s55, 0x2000
	s_add_u32 s56, s24, 0xb0000
	v_lshl_add_u64 v[216:217], s[24:25], 0, v[172:173]
	s_addc_u32 s57, s25, 0
	s_add_i32 s55, s43, s33
	global_load_lds_dwordx4 v[216:217], off
	v_lshl_add_u64 v[218:219], s[56:57], 0, v[170:171]
	s_mov_b32 m0, s55
	v_lshl_add_u64 v[220:221], s[26:27], 0, v[172:173]
	global_load_lds_dwordx4 v[218:219], off
	v_lshl_add_u64 v[218:219], s[56:57], 0, v[172:173]
	s_add_i32 m0, s55, 0x2000
	s_nop 0
	global_load_lds_dwordx4 v[218:219], off
	v_lshl_add_u64 v[218:219], s[26:27], 0, v[170:171]
	s_mov_b32 m0, s34
	s_nop 0
	global_load_lds_dwordx4 v[218:219], off
	s_mov_b32 m0, s35
	s_nop 0
	global_load_lds_dwordx4 v[220:221], off
	s_waitcnt vmcnt(8)
	s_waitcnt lgkmcnt(0)
	s_barrier
; #define PG8_STAGE(bufoff, gbase, voff) do { _Pragma("unroll") for (int _i = 0; _i < 2; ++_i) \
;         __builtin_amdgcn_global_load_lds((const unsigned*)((const char*)(gbase) + (voff)[_i]), (LAS unsigned*)(lds + (bufoff) + ldsw + _i * 8192), 16, 0, 0); } while (0)
; #define PG8_LDA(dst, b, h) do { _Pragma("unroll") for (int m = 0; m < 4; ++m) _Pragma("unroll") for (int k = 0; k < 2; ++k) dst[m][k] = *(const LAS bf16x8*)(lds + PG8_SA(b, h) + aoff + m * 2048 + k * 1024); } while (0)
; #define PG8_LDB(dst, b, h) do { _Pragma("unroll") for (int n = 0; n < 2; ++n) _Pragma("unroll") for (int k = 0; k < 2; ++k) dst[n][k] = *(const LAS bf16x8*)(lds + PG8_SB(b, h) + boff + n * 2048 + k * 1024); } while (0)
; #define PG8_MMA(ai, bj, At, Bt) do { __builtin_amdgcn_s_setprio(1); _Pragma("unroll") for (int m = 0; m < 4; ++m) _Pragma("unroll") for (int n = 0; n < 2; ++n) _Pragma("unroll") for (int k = 0; k < 2; ++k) \
;         acc[ai][bj][m][n] = __builtin_amdgcn_mfma_f32_16x16x32_bf16(Bt[n][k], At[m][k], acc[ai][bj][m][n], 0, 0, 0); __builtin_amdgcn_s_setprio(0); } while (0)
; #define PG8_WAIT_V(n) asm volatile("s_waitcnt vmcnt(" #n ")" ::: "memory")
; #define PG8_WAIT_L(n) asm volatile("s_waitcnt lgkmcnt(" #n ")" ::: "memory")
; #define PG8_BAR __builtin_amdgcn_s_barrier()
; #define PG8_SCHED __builtin_amdgcn_sched_barrier(0)
; template <class Epi>
; __device__ __forceinline__ void gemm_phase(LAS unsigned char* lds, const Gemm g, const StaticOrder& S, const Epi& E) {
;     ...
;             PG8_WAIT_V(8); PG8_WAIT_L(0); PG8_BAR; PG8_MMA(1, 0, At, B0); PG8_MMA(1, 1, At, B1); PG8_BAR; PG8_SCHED;
;             PG8_LDB(B0, 1, 0); PG8_LDB(B1, 1, 1); PG8_SCHED; PG8_LDA(At, 1, 0); PG8_STAGE(PG8_SA(0, 1), a2 + hstep, voffA);
;             PG8_WAIT_V(8); PG8_WAIT_L(0); PG8_BAR; PG8_MMA(0, 0, At, B0); PG8_MMA(0, 1, At, B1); PG8_BAR; PG8_SCHED;
;             PG8_LDA(At, 1, 1); PG8_STAGE(PG8_SB(1, 0), b3, voffB); PG8_STAGE(PG8_SB(1, 1), b3 + hstep, voffB); PG8_STAGE(PG8_SA(1, 0), a3, voffA);
	s_waitcnt lgkmcnt(0)
	v_mfma_f32_16x16x32_bf16 v[62:65], v[130:133], v[162:165], v[62:65]
	v_mfma_f32_16x16x32_bf16 v[58:61], v[138:141], v[162:165], v[58:61]
	v_mfma_f32_16x16x32_bf16 v[54:57], v[130:133], v[182:185], v[54:57]
	v_mfma_f32_16x16x32_bf16 v[50:53], v[138:141], v[182:185], v[50:53]
	v_mfma_f32_16x16x32_bf16 v[38:41], v[130:133], v[200:203], v[38:41]
	v_mfma_f32_16x16x32_bf16 v[34:37], v[138:141], v[200:203], v[34:37]
	v_mfma_f32_16x16x32_bf16 v[22:25], v[130:133], v[208:211], v[22:25]
	v_mfma_f32_16x16x32_bf16 v[18:21], v[138:141], v[208:211], v[18:21]
	v_mfma_f32_16x16x32_bf16 v[62:65], v[134:137], v[166:169], v[62:65]
	v_mfma_f32_16x16x32_bf16 v[58:61], v[142:145], v[166:169], v[58:61]
	v_mfma_f32_16x16x32_bf16 v[54:57], v[134:137], v[186:189], v[54:57]
	v_mfma_f32_16x16x32_bf16 v[50:53], v[142:145], v[186:189], v[50:53]
	v_mfma_f32_16x16x32_bf16 v[38:41], v[134:137], v[204:207], v[38:41]
	v_mfma_f32_16x16x32_bf16 v[34:37], v[142:145], v[204:207], v[34:37]
	v_mfma_f32_16x16x32_bf16 v[22:25], v[134:137], v[212:215], v[22:25]
	v_mfma_f32_16x16x32_bf16 v[18:21], v[142:145], v[212:215], v[18:21]
	v_mfma_f32_16x16x32_bf16 v[46:49], v[146:149], v[162:165], v[46:49]
	v_mfma_f32_16x16x32_bf16 v[42:45], v[154:157], v[162:165], v[42:45]
	v_mfma_f32_16x16x32_bf16 v[30:33], v[146:149], v[182:185], v[30:33]
	v_mfma_f32_16x16x32_bf16 v[26:29], v[154:157], v[182:185], v[26:29]
	v_mfma_f32_16x16x32_bf16 v[14:17], v[146:149], v[200:203], v[14:17]
	v_mfma_f32_16x16x32_bf16 v[10:13], v[154:157], v[200:203], v[10:13]
	v_mfma_f32_16x16x32_bf16 v[6:9], v[146:149], v[208:211], v[6:9]
	v_mfma_f32_16x16x32_bf16 v[2:5], v[154:157], v[208:211], v[2:5]
	v_mfma_f32_16x16x32_bf16 v[46:49], v[150:153], v[166:169], v[46:49]
	v_mfma_f32_16x16x32_bf16 v[42:45], v[158:161], v[166:169], v[42:45]
	v_mfma_f32_16x16x32_bf16 v[30:33], v[150:153], v[186:189], v[30:33]
	v_mfma_f32_16x16x32_bf16 v[26:29], v[158:161], v[186:189], v[26:29]
	v_mfma_f32_16x16x32_bf16 v[14:17], v[150:153], v[204:207], v[14:17]
	v_mfma_f32_16x16x32_bf16 v[10:13], v[158:161], v[204:207], v[10:13]
	v_mfma_f32_16x16x32_bf16 v[6:9], v[150:153], v[212:215], v[6:9]
	v_mfma_f32_16x16x32_bf16 v[2:5], v[158:161], v[212:215], v[2:5]
	s_barrier
	s_add_i32 s55, 0, 0x18000
	s_add_i32 s56, 0, 0x1c000
	v_add_u32_e32 v142, s55, v194
	v_add_u32_e32 v158, s56, v194
	ds_read_b128 v[130:133], v142
	ds_read_b128 v[134:137], v142 offset:1024
	ds_read_b128 v[138:141], v142 offset:2048
	ds_read_b128 v[142:145], v142 offset:3072
	ds_read_b128 v[146:149], v158
	ds_read_b128 v[150:153], v158 offset:1024
	ds_read_b128 v[154:157], v158 offset:2048
	ds_read_b128 v[158:161], v158 offset:3072
	s_add_u32 s26, s26, 0xb0000
	s_addc_u32 s27, s27, 0
	s_mov_b32 m0, s36
	v_lshl_add_u64 v[222:223], s[26:27], 0, v[170:171]
	ds_read_b128 v[162:165], v198 offset:32768
	ds_read_b128 v[166:169], v198 offset:33792
	ds_read_b128 v[182:185], v198 offset:34816
	ds_read_b128 v[186:189], v198 offset:35840
	ds_read_b128 v[200:203], v198 offset:36864
	ds_read_b128 v[204:207], v198 offset:37888
	ds_read_b128 v[208:211], v198 offset:38912
	ds_read_b128 v[212:215], v198 offset:39936
	global_load_lds_dwordx4 v[222:223], off
	v_lshl_add_u64 v[222:223], s[26:27], 0, v[172:173]
	s_mov_b32 m0, s37
	s_nop 0
	global_load_lds_dwordx4 v[222:223], off
	s_waitcnt vmcnt(8)
	s_waitcnt lgkmcnt(0)
	s_barrier
	s_waitcnt lgkmcnt(0)
	v_mfma_f32_16x16x32_bf16 v[126:129], v[130:133], v[162:165], v[126:129]
	v_mfma_f32_16x16x32_bf16 v[122:125], v[138:141], v[162:165], v[122:125]
	v_mfma_f32_16x16x32_bf16 v[118:121], v[130:133], v[182:185], v[118:121]
	v_mfma_f32_16x16x32_bf16 v[114:117], v[138:141], v[182:185], v[114:117]
	v_mfma_f32_16x16x32_bf16 v[94:97], v[130:133], v[200:203], v[94:97]
	v_mfma_f32_16x16x32_bf16 v[90:93], v[138:141], v[200:203], v[90:93]
	v_mfma_f32_16x16x32_bf16 v[82:85], v[130:133], v[208:211], v[82:85]
	v_mfma_f32_16x16x32_bf16 v[74:77], v[138:141], v[208:211], v[74:77]
	v_mfma_f32_16x16x32_bf16 v[126:129], v[134:137], v[166:169], v[126:129]
	v_mfma_f32_16x16x32_bf16 v[122:125], v[142:145], v[166:169], v[122:125]
	v_mfma_f32_16x16x32_bf16 v[118:121], v[134:137], v[186:189], v[118:121]
	v_mfma_f32_16x16x32_bf16 v[114:117], v[142:145], v[186:189], v[114:117]
	v_mfma_f32_16x16x32_bf16 v[94:97], v[134:137], v[204:207], v[94:97]
	v_mfma_f32_16x16x32_bf16 v[90:93], v[142:145], v[204:207], v[90:93]
	v_mfma_f32_16x16x32_bf16 v[82:85], v[134:137], v[212:215], v[82:85]
	v_mfma_f32_16x16x32_bf16 v[74:77], v[142:145], v[212:215], v[74:77]
	v_mfma_f32_16x16x32_bf16 v[110:113], v[146:149], v[162:165], v[110:113]
	v_mfma_f32_16x16x32_bf16 v[106:109], v[154:157], v[162:165], v[106:109]
	v_mfma_f32_16x16x32_bf16 v[102:105], v[146:149], v[182:185], v[102:105]
	v_mfma_f32_16x16x32_bf16 v[98:101], v[154:157], v[182:185], v[98:101]
	v_mfma_f32_16x16x32_bf16 v[86:89], v[146:149], v[200:203], v[86:89]
	v_mfma_f32_16x16x32_bf16 v[78:81], v[154:157], v[200:203], v[78:81]
	v_mfma_f32_16x16x32_bf16 v[70:73], v[146:149], v[208:211], v[70:73]
	v_mfma_f32_16x16x32_bf16 v[66:69], v[154:157], v[208:211], v[66:69]
	v_mfma_f32_16x16x32_bf16 v[110:113], v[150:153], v[166:169], v[110:113]
	v_mfma_f32_16x16x32_bf16 v[106:109], v[158:161], v[166:169], v[106:109]
	v_mfma_f32_16x16x32_bf16 v[102:105], v[150:153], v[186:189], v[102:105]
	v_mfma_f32_16x16x32_bf16 v[98:101], v[158:161], v[186:189], v[98:101]
	v_mfma_f32_16x16x32_bf16 v[86:89], v[150:153], v[204:207], v[86:89]
	v_mfma_f32_16x16x32_bf16 v[78:81], v[158:161], v[204:207], v[78:81]
	v_mfma_f32_16x16x32_bf16 v[70:73], v[150:153], v[212:215], v[70:73]
	v_mfma_f32_16x16x32_bf16 v[66:69], v[158:161], v[212:215], v[66:69]
	s_barrier
; #define PG8_STAGE(bufoff, gbase, voff) do { _Pragma("unroll") for (int _i = 0; _i < 2; ++_i) \
;         __builtin_amdgcn_global_load_lds((const unsigned*)((const char*)(gbase) + (voff)[_i]), (LAS unsigned*)(lds + (bufoff) + ldsw + _i * 8192), 16, 0, 0); } while (0)
; #define PG8_LDA(dst, b, h) do { _Pragma("unroll") for (int m = 0; m < 4; ++m) _Pragma("unroll") for (int k = 0; k < 2; ++k) dst[m][k] = *(const LAS bf16x8*)(lds + PG8_SA(b, h) + aoff + m * 2048 + k * 1024); } while (0)
; #define PG8_MMA(ai, bj, At, Bt) do { __builtin_amdgcn_s_setprio(1); _Pragma("unroll") for (int m = 0; m < 4; ++m) _Pragma("unroll") for (int n = 0; n < 2; ++n) _Pragma("unroll") for (int k = 0; k < 2; ++k) \
;         acc[ai][bj][m][n] = __builtin_amdgcn_mfma_f32_16x16x32_bf16(Bt[n][k], At[m][k], acc[ai][bj][m][n], 0, 0, 0); __builtin_amdgcn_s_setprio(0); } while (0)
; #define PG8_WAIT_V(n) asm volatile("s_waitcnt vmcnt(" #n ")" ::: "memory")
; #define PG8_WAIT_L(n) asm volatile("s_waitcnt lgkmcnt(" #n ")" ::: "memory")
; #define PG8_BAR __builtin_amdgcn_s_barrier()
; #define PG8_SCHED __builtin_amdgcn_sched_barrier(0)
; template <class Epi>
; __device__ __forceinline__ void gemm_phase(LAS unsigned char* lds, const Gemm g, const StaticOrder& S, const Epi& E) {
;     ...
;             PG8_LDA(At, 1, 1); PG8_STAGE(PG8_SB(1, 0), b3, voffB); PG8_STAGE(PG8_SB(1, 1), b3 + hstep, voffB); PG8_STAGE(PG8_SA(1, 0), a3, voffA);
;             PG8_WAIT_V(8); PG8_WAIT_L(0); PG8_BAR; PG8_MMA(1, 0, At, B0); PG8_MMA(1, 1, At, B1); PG8_BAR; PG8_SCHED;
;         }
;         if (wr == 0) PG8_BAR;
	s_add_i32 s26, s55, s33
	v_lshl_add_u64 v[190:191], v[190:191], 0, s[8:9]
	s_mov_b32 m0, s26
	ds_read_b128 v[162:165], v198 offset:49152
	ds_read_b128 v[166:169], v198 offset:50176
	ds_read_b128 v[182:185], v198 offset:51200
	ds_read_b128 v[186:189], v198 offset:52224
	ds_read_b128 v[200:203], v198 offset:53248
	ds_read_b128 v[204:207], v198 offset:54272
	ds_read_b128 v[208:211], v198 offset:55296
	ds_read_b128 v[212:215], v198 offset:56320
	global_load_lds_dwordx4 v[190:191], off
	s_add_i32 m0, s26, 0x2000
	s_add_u32 s24, s24, 0xb0080
	v_lshl_add_u64 v[190:191], v[216:217], 0, s[8:9]
	s_addc_u32 s25, s25, 0
	s_add_i32 s26, s56, s33
	global_load_lds_dwordx4 v[190:191], off
	v_lshl_add_u64 v[190:191], s[24:25], 0, v[170:171]
	s_mov_b32 m0, s26
	s_nop 0
	global_load_lds_dwordx4 v[190:191], off
	v_lshl_add_u64 v[190:191], s[24:25], 0, v[172:173]
	s_add_i32 m0, s26, 0x2000
	s_nop 0
	global_load_lds_dwordx4 v[190:191], off
	v_lshl_add_u64 v[190:191], v[218:219], 0, s[8:9]
	s_mov_b32 m0, s39
	s_nop 0
	global_load_lds_dwordx4 v[190:191], off
	v_lshl_add_u64 v[190:191], v[220:221], 0, s[8:9]
	s_mov_b32 m0, s40
	s_nop 0
	global_load_lds_dwordx4 v[190:191], off
	s_waitcnt vmcnt(8)
	s_waitcnt lgkmcnt(0)
	s_barrier
	s_waitcnt lgkmcnt(0)
	v_mfma_f32_16x16x32_bf16 v[62:65], v[130:133], v[162:165], v[62:65]
	v_mfma_f32_16x16x32_bf16 v[58:61], v[138:141], v[162:165], v[58:61]
	v_mfma_f32_16x16x32_bf16 v[54:57], v[130:133], v[182:185], v[54:57]
	v_mfma_f32_16x16x32_bf16 v[50:53], v[138:141], v[182:185], v[50:53]
	v_mfma_f32_16x16x32_bf16 v[38:41], v[130:133], v[200:203], v[38:41]
	v_mfma_f32_16x16x32_bf16 v[34:37], v[138:141], v[200:203], v[34:37]
	v_mfma_f32_16x16x32_bf16 v[22:25], v[130:133], v[208:211], v[22:25]
	v_mfma_f32_16x16x32_bf16 v[18:21], v[138:141], v[208:211], v[18:21]
	v_mfma_f32_16x16x32_bf16 v[62:65], v[134:137], v[166:169], v[62:65]
	v_mfma_f32_16x16x32_bf16 v[58:61], v[142:145], v[166:169], v[58:61]
	v_mfma_f32_16x16x32_bf16 v[54:57], v[134:137], v[186:189], v[54:57]
	v_mfma_f32_16x16x32_bf16 v[50:53], v[142:145], v[186:189], v[50:53]
	v_mfma_f32_16x16x32_bf16 v[38:41], v[134:137], v[204:207], v[38:41]
	v_mfma_f32_16x16x32_bf16 v[34:37], v[142:145], v[204:207], v[34:37]
	v_mfma_f32_16x16x32_bf16 v[22:25], v[134:137], v[212:215], v[22:25]
	v_mfma_f32_16x16x32_bf16 v[18:21], v[142:145], v[212:215], v[18:21]
	v_mfma_f32_16x16x32_bf16 v[46:49], v[146:149], v[162:165], v[46:49]
	v_mfma_f32_16x16x32_bf16 v[42:45], v[154:157], v[162:165], v[42:45]
	v_mfma_f32_16x16x32_bf16 v[30:33], v[146:149], v[182:185], v[30:33]
	v_mfma_f32_16x16x32_bf16 v[26:29], v[154:157], v[182:185], v[26:29]
	v_mfma_f32_16x16x32_bf16 v[14:17], v[146:149], v[200:203], v[14:17]
	v_mfma_f32_16x16x32_bf16 v[10:13], v[154:157], v[200:203], v[10:13]
	v_mfma_f32_16x16x32_bf16 v[6:9], v[146:149], v[208:211], v[6:9]
	v_mfma_f32_16x16x32_bf16 v[2:5], v[154:157], v[208:211], v[2:5]
	v_mfma_f32_16x16x32_bf16 v[46:49], v[150:153], v[166:169], v[46:49]
	v_mfma_f32_16x16x32_bf16 v[42:45], v[158:161], v[166:169], v[42:45]
	v_mfma_f32_16x16x32_bf16 v[30:33], v[150:153], v[186:189], v[30:33]
	v_mfma_f32_16x16x32_bf16 v[26:29], v[158:161], v[186:189], v[26:29]
	v_mfma_f32_16x16x32_bf16 v[14:17], v[150:153], v[204:207], v[14:17]
	v_mfma_f32_16x16x32_bf16 v[10:13], v[158:161], v[204:207], v[10:13]
	v_mfma_f32_16x16x32_bf16 v[6:9], v[150:153], v[212:215], v[6:9]
	v_mfma_f32_16x16x32_bf16 v[2:5], v[158:161], v[212:215], v[2:5]
	s_barrier
	s_add_i32 s54, s54, 2
	s_add_u32 s22, s22, 0x100
	s_addc_u32 s23, s23, 0
	s_add_u32 s52, s52, 0x100
	s_addc_u32 s53, s53, 0
	s_cmp_gt_u32 s54, 41
	s_cbranch_scc0 .LBB0_937
	s_and_b64 vcc, exec, s[10:11]
	s_cbranch_vccz .LBB0_940
	s_barrier

; #define SEAM(k) do { if ((k) + 1 < hi) { if ((k) == 0) { __syncthreads(); cg::this_grid().sync(); } \
;         else { if (!xposted) { if (threadIdx.x == 0) { xst[0] = 0u; xst[1] = 0u; } __syncthreads(); xbar = xcd_barrier_post((unsigned*)(ws + 65536), xst); xposted = true; } xcd_barrier(xbar); } } } while (0)
; __global__ void __launch_bounds__(512) fwd_kernel(Args a) {
;     ...
;     if (IN(11)) { pg8::Gemm g{(const bf16_t*)(ws + WS_BIG), (const bf16_t*)(ws + WS_WD2), M, D, FF}; pg8::StaticOrder S; S.init(M, D, G, bx);
;                   pg8::EpiResid E{hbuf, hbuf, ALPHA, 0.5f}; pg8::gemm_phase(lds, g, S, E); SEAM(11); }
.LBB0_944:
	s_setprio 0
	v_readlane_b32 s4, v238, 21
	v_readlane_b32 s5, v238, 22
	s_cmp_lt_i32 s5, 13
	s_cbranch_scc1 .LBB0_1001
	v_readlane_b32 s0, v238, 23
	v_readlane_b32 s1, v238, 24
	s_xor_b64 s[0:1], s[0:1], -1
	s_andn2_b64 vcc, exec, s[0:1]
	v_cmp_eq_u32_e64 s[0:1], 0, v192
	s_cbranch_vccnz .LBB0_952
	s_and_saveexec_b64 s[2:3], s[0:1]
	s_cbranch_execz .LBB0_948
	s_add_i32 s4, 0, 0x23ff0
	v_mov_b32_e32 v2, 0
	v_mov_b32_e32 v3, s4
	s_add_i32 s4, 0, 0x23ff4
	ds_write_b32 v3, v2
	v_mov_b32_e32 v3, s4
	ds_write_b32 v3, v2
